# GEMM load segments: m0 write moved ahead of the address add so the s_nop 0 before each LDS-DMA load goes (136 sites)
# speedup vs baseline: 1.0145x; 1.0145x over previous
.LBB0_372:
	s_ashr_i32 s21, s20, 31
	s_lshl_b64 s[22:23], s[20:21], 19
	s_add_u32 s22, s96, s22
	s_addc_u32 s23, s97, s23
	s_and_b64 s[24:25], s[4:5], exec
	s_cselect_b32 s21, s23, s29
	s_cselect_b32 s27, s22, s28
	s_ashr_i32 s13, s12, 31
	s_lshl_b64 s[24:25], s[12:13], 19
	s_add_u32 s24, s14, s24
	s_addc_u32 s25, s15, s25
	s_and_b64 s[36:37], s[4:5], exec
	s_cselect_b32 s13, s25, s31
	s_cselect_b32 s48, s24, s30
	s_add_u32 s49, s30, 0x100
	s_addc_u32 s50, s31, 0
	s_mov_b32 s51, -2
	ds_read_b128 v[150:153], v180
	ds_read_b128 v[154:157], v180 offset:1024
	ds_read_b128 v[158:161], v180 offset:2048
	ds_read_b128 v[162:165], v180 offset:3072
	ds_read_b128 v[184:187], v181
	ds_read_b128 v[188:191], v181 offset:1024
	ds_read_b128 v[192:195], v181 offset:2048
	ds_read_b128 v[196:199], v181 offset:3072
	s_add_u32 s30, s28, 0x100
	s_addc_u32 s31, s29, 0
	s_cmp_eq_u32 s51, 12
	s_cselect_b32 s39, s21, s31
	s_cselect_b32 s38, s27, s30
	s_cselect_b32 s37, s13, s50
	s_cselect_b32 s36, s48, s49
	v_lshl_add_u64 v[166:167], s[28:29], 0, v[142:143]
	s_add_i32 m0, s17, 0xc000
	ds_read_b128 v[200:203], v182
	ds_read_b128 v[204:207], v182 offset:1024
	ds_read_b128 v[208:211], v182 offset:2048
	ds_read_b128 v[212:215], v182 offset:3072
	ds_read_b128 v[216:219], v182 offset:4096
	ds_read_b128 v[220:223], v182 offset:5120
	ds_read_b128 v[224:227], v182 offset:6144
	ds_read_b128 v[228:231], v182 offset:7168
	global_load_lds_dwordx4 v[166:167], off
	s_add_i32 m0, s17, 0xe000
	v_lshl_add_u64 v[166:167], s[28:29], 0, v[144:145]
	global_load_lds_dwordx4 v[166:167], off
	s_waitcnt vmcnt(8)
	s_waitcnt lgkmcnt(0)
	s_barrier
	s_setprio 1
	s_waitcnt lgkmcnt(0)
	v_mfma_f32_16x16x32_bf16 v[82:85], v[150:153], v[200:203], 0
	v_mfma_f32_16x16x32_bf16 v[78:81], v[158:161], v[200:203], 0
	v_mfma_f32_16x16x32_bf16 v[70:73], v[150:153], v[208:211], 0
	v_mfma_f32_16x16x32_bf16 v[66:69], v[158:161], v[208:211], 0
	v_mfma_f32_16x16x32_bf16 v[62:65], v[150:153], v[216:219], 0
	v_mfma_f32_16x16x32_bf16 v[58:61], v[158:161], v[216:219], 0
	v_mfma_f32_16x16x32_bf16 v[54:57], v[150:153], v[224:227], 0
	v_mfma_f32_16x16x32_bf16 v[50:53], v[158:161], v[224:227], 0
	v_mfma_f32_16x16x32_bf16 v[82:85], v[154:157], v[204:207], v[82:85]
	v_mfma_f32_16x16x32_bf16 v[78:81], v[162:165], v[204:207], v[78:81]
	v_mfma_f32_16x16x32_bf16 v[70:73], v[154:157], v[212:215], v[70:73]
	v_mfma_f32_16x16x32_bf16 v[66:69], v[162:165], v[212:215], v[66:69]
	v_mfma_f32_16x16x32_bf16 v[62:65], v[154:157], v[220:223], v[62:65]
	v_mfma_f32_16x16x32_bf16 v[58:61], v[162:165], v[220:223], v[58:61]
	v_mfma_f32_16x16x32_bf16 v[54:57], v[154:157], v[228:231], v[54:57]
	v_mfma_f32_16x16x32_bf16 v[50:53], v[162:165], v[228:231], v[50:53]
	s_setprio 0
	s_setprio 1
	v_mfma_f32_16x16x32_bf16 v[126:129], v[184:187], v[200:203], 0
	v_mfma_f32_16x16x32_bf16 v[122:125], v[192:195], v[200:203], 0
	v_mfma_f32_16x16x32_bf16 v[118:121], v[184:187], v[208:211], 0
	v_mfma_f32_16x16x32_bf16 v[114:117], v[192:195], v[208:211], 0
	v_mfma_f32_16x16x32_bf16 v[110:113], v[184:187], v[216:219], 0
	v_mfma_f32_16x16x32_bf16 v[106:109], v[192:195], v[216:219], 0
	v_mfma_f32_16x16x32_bf16 v[102:105], v[184:187], v[224:227], 0
	v_mfma_f32_16x16x32_bf16 v[98:101], v[192:195], v[224:227], 0
	v_mfma_f32_16x16x32_bf16 v[126:129], v[188:191], v[204:207], v[126:129]
	v_mfma_f32_16x16x32_bf16 v[122:125], v[196:199], v[204:207], v[122:125]
	v_mfma_f32_16x16x32_bf16 v[118:121], v[188:191], v[212:215], v[118:121]
	v_mfma_f32_16x16x32_bf16 v[114:117], v[196:199], v[212:215], v[114:117]
	v_mfma_f32_16x16x32_bf16 v[110:113], v[188:191], v[220:223], v[110:113]
	v_mfma_f32_16x16x32_bf16 v[106:109], v[196:199], v[220:223], v[106:109]
	v_mfma_f32_16x16x32_bf16 v[102:105], v[188:191], v[228:231], v[102:105]
	v_mfma_f32_16x16x32_bf16 v[98:101], v[196:199], v[228:231], v[98:101]
	s_setprio 0
	s_barrier
	s_add_i32 s28, s45, s16
	v_lshl_add_u64 v[166:167], s[36:37], 0, v[134:135]
	s_mov_b32 m0, s28
	ds_read_b128 v[200:203], v182 offset:16384
	ds_read_b128 v[204:207], v182 offset:17408
	ds_read_b128 v[208:211], v182 offset:18432
	ds_read_b128 v[212:215], v182 offset:19456
	ds_read_b128 v[216:219], v182 offset:20480
	ds_read_b128 v[220:223], v182 offset:21504
	ds_read_b128 v[224:227], v182 offset:22528
	ds_read_b128 v[228:231], v182 offset:23552
	global_load_lds_dwordx4 v[166:167], off
	s_add_i32 m0, s28, 0x2000
	s_add_u32 s28, s36, 0x40000
	v_lshl_add_u64 v[232:233], s[36:37], 0, v[136:137]
	s_addc_u32 s29, s37, 0
	s_add_i32 s52, s46, s16
	global_load_lds_dwordx4 v[232:233], off
	v_lshl_add_u64 v[234:235], s[28:29], 0, v[134:135]
	s_mov_b32 m0, s52
	v_lshl_add_u64 v[236:237], s[38:39], 0, v[130:131]
	global_load_lds_dwordx4 v[234:235], off
	s_add_i32 m0, s52, 0x2000
	v_lshl_add_u64 v[234:235], s[28:29], 0, v[136:137]
	global_load_lds_dwordx4 v[234:235], off
	s_mov_b32 m0, s17
	v_lshl_add_u64 v[234:235], s[38:39], 0, v[132:133]
	global_load_lds_dwordx4 v[234:235], off
	s_mov_b32 m0, s34
	s_nop 0
	global_load_lds_dwordx4 v[236:237], off
	s_waitcnt vmcnt(8)
	s_waitcnt lgkmcnt(0)
	s_barrier
	s_setprio 1
	s_waitcnt lgkmcnt(0)
	v_mfma_f32_16x16x32_bf16 v[38:41], v[150:153], v[200:203], 0
	v_mfma_f32_16x16x32_bf16 v[34:37], v[158:161], v[200:203], 0
	v_mfma_f32_16x16x32_bf16 v[26:29], v[150:153], v[208:211], 0
	v_mfma_f32_16x16x32_bf16 v[22:25], v[158:161], v[208:211], 0
	v_mfma_f32_16x16x32_bf16 v[14:17], v[150:153], v[216:219], 0
	v_mfma_f32_16x16x32_bf16 v[10:13], v[158:161], v[216:219], 0
	v_mfma_f32_16x16x32_bf16 v[6:9], v[150:153], v[224:227], 0
	v_mfma_f32_16x16x32_bf16 v[2:5], v[158:161], v[224:227], 0
	v_mfma_f32_16x16x32_bf16 v[38:41], v[154:157], v[204:207], v[38:41]
	v_mfma_f32_16x16x32_bf16 v[34:37], v[162:165], v[204:207], v[34:37]
	v_mfma_f32_16x16x32_bf16 v[26:29], v[154:157], v[212:215], v[26:29]
	v_mfma_f32_16x16x32_bf16 v[22:25], v[162:165], v[212:215], v[22:25]
	v_mfma_f32_16x16x32_bf16 v[14:17], v[154:157], v[220:223], v[14:17]
	v_mfma_f32_16x16x32_bf16 v[10:13], v[162:165], v[220:223], v[10:13]
	v_mfma_f32_16x16x32_bf16 v[6:9], v[154:157], v[228:231], v[6:9]
	v_mfma_f32_16x16x32_bf16 v[2:5], v[162:165], v[228:231], v[2:5]
	s_setprio 0
	s_setprio 1
	v_mfma_f32_16x16x32_bf16 v[94:97], v[184:187], v[200:203], 0
	v_mfma_f32_16x16x32_bf16 v[90:93], v[192:195], v[200:203], 0
	v_mfma_f32_16x16x32_bf16 v[86:89], v[184:187], v[208:211], 0
	v_mfma_f32_16x16x32_bf16 v[74:77], v[192:195], v[208:211], 0
	v_mfma_f32_16x16x32_bf16 v[46:49], v[184:187], v[216:219], 0
	v_mfma_f32_16x16x32_bf16 v[42:45], v[192:195], v[216:219], 0
	v_mfma_f32_16x16x32_bf16 v[30:33], v[184:187], v[224:227], 0
	v_mfma_f32_16x16x32_bf16 v[18:21], v[192:195], v[224:227], 0
	v_mfma_f32_16x16x32_bf16 v[94:97], v[188:191], v[204:207], v[94:97]
	v_mfma_f32_16x16x32_bf16 v[90:93], v[196:199], v[204:207], v[90:93]
	v_mfma_f32_16x16x32_bf16 v[86:89], v[188:191], v[212:215], v[86:89]
	v_mfma_f32_16x16x32_bf16 v[74:77], v[196:199], v[212:215], v[74:77]
	v_mfma_f32_16x16x32_bf16 v[46:49], v[188:191], v[220:223], v[46:49]
	v_mfma_f32_16x16x32_bf16 v[42:45], v[196:199], v[220:223], v[42:45]
	v_mfma_f32_16x16x32_bf16 v[30:33], v[188:191], v[228:231], v[30:33]
	v_mfma_f32_16x16x32_bf16 v[18:21], v[196:199], v[228:231], v[18:21]
	s_setprio 0
	s_barrier
	s_add_i32 s52, 0, 0x18000
	v_add_u32_e32 v138, s52, v178
	s_add_i32 s53, 0, 0x1c000
	ds_read_b128 v[150:153], v138
	ds_read_b128 v[154:157], v138 offset:1024
	ds_read_b128 v[158:161], v138 offset:2048
	ds_read_b128 v[162:165], v138 offset:3072
	v_add_u32_e32 v138, s53, v178
	ds_read_b128 v[184:187], v138
	ds_read_b128 v[188:191], v138 offset:1024
	ds_read_b128 v[192:195], v138 offset:2048
	ds_read_b128 v[196:199], v138 offset:3072
	s_add_u32 s28, s38, 0x40000
	s_addc_u32 s29, s39, 0
	s_mov_b32 m0, s35
	v_lshl_add_u64 v[238:239], s[28:29], 0, v[132:133]
	ds_read_b128 v[200:203], v182 offset:32768
	ds_read_b128 v[204:207], v182 offset:33792
	ds_read_b128 v[208:211], v182 offset:34816
	ds_read_b128 v[212:215], v182 offset:35840
	ds_read_b128 v[216:219], v182 offset:36864
	ds_read_b128 v[220:223], v182 offset:37888
	ds_read_b128 v[224:227], v182 offset:38912
	ds_read_b128 v[228:231], v182 offset:39936
	global_load_lds_dwordx4 v[238:239], off
	s_mov_b32 m0, s40
	v_lshl_add_u64 v[238:239], s[28:29], 0, v[130:131]
	global_load_lds_dwordx4 v[238:239], off
	s_waitcnt vmcnt(8)
	s_waitcnt lgkmcnt(0)
	s_barrier
	s_setprio 1
	s_waitcnt lgkmcnt(0)
	v_mfma_f32_16x16x32_bf16 v[82:85], v[150:153], v[200:203], v[82:85]
	v_mfma_f32_16x16x32_bf16 v[78:81], v[158:161], v[200:203], v[78:81]
	v_mfma_f32_16x16x32_bf16 v[70:73], v[150:153], v[208:211], v[70:73]
	v_mfma_f32_16x16x32_bf16 v[66:69], v[158:161], v[208:211], v[66:69]
	v_mfma_f32_16x16x32_bf16 v[62:65], v[150:153], v[216:219], v[62:65]
	v_mfma_f32_16x16x32_bf16 v[58:61], v[158:161], v[216:219], v[58:61]
	v_mfma_f32_16x16x32_bf16 v[54:57], v[150:153], v[224:227], v[54:57]
	v_mfma_f32_16x16x32_bf16 v[50:53], v[158:161], v[224:227], v[50:53]
	v_mfma_f32_16x16x32_bf16 v[82:85], v[154:157], v[204:207], v[82:85]
	v_mfma_f32_16x16x32_bf16 v[78:81], v[162:165], v[204:207], v[78:81]
	v_mfma_f32_16x16x32_bf16 v[70:73], v[154:157], v[212:215], v[70:73]
	v_mfma_f32_16x16x32_bf16 v[66:69], v[162:165], v[212:215], v[66:69]
	v_mfma_f32_16x16x32_bf16 v[62:65], v[154:157], v[220:223], v[62:65]
	v_mfma_f32_16x16x32_bf16 v[58:61], v[162:165], v[220:223], v[58:61]
	v_mfma_f32_16x16x32_bf16 v[54:57], v[154:157], v[228:231], v[54:57]
	v_mfma_f32_16x16x32_bf16 v[50:53], v[162:165], v[228:231], v[50:53]
	s_setprio 0
	s_setprio 1
	v_mfma_f32_16x16x32_bf16 v[126:129], v[184:187], v[200:203], v[126:129]
	v_mfma_f32_16x16x32_bf16 v[122:125], v[192:195], v[200:203], v[122:125]
	v_mfma_f32_16x16x32_bf16 v[118:121], v[184:187], v[208:211], v[118:121]
	v_mfma_f32_16x16x32_bf16 v[114:117], v[192:195], v[208:211], v[114:117]
	v_mfma_f32_16x16x32_bf16 v[110:113], v[184:187], v[216:219], v[110:113]
	v_mfma_f32_16x16x32_bf16 v[106:109], v[192:195], v[216:219], v[106:109]
	v_mfma_f32_16x16x32_bf16 v[102:105], v[184:187], v[224:227], v[102:105]
	v_mfma_f32_16x16x32_bf16 v[98:101], v[192:195], v[224:227], v[98:101]
	v_mfma_f32_16x16x32_bf16 v[126:129], v[188:191], v[204:207], v[126:129]
	v_mfma_f32_16x16x32_bf16 v[122:125], v[196:199], v[204:207], v[122:125]
	v_mfma_f32_16x16x32_bf16 v[118:121], v[188:191], v[212:215], v[118:121]
	v_mfma_f32_16x16x32_bf16 v[114:117], v[196:199], v[212:215], v[114:117]
	v_mfma_f32_16x16x32_bf16 v[110:113], v[188:191], v[220:223], v[110:113]
	v_mfma_f32_16x16x32_bf16 v[106:109], v[196:199], v[220:223], v[106:109]
	v_mfma_f32_16x16x32_bf16 v[102:105], v[188:191], v[228:231], v[102:105]
	v_mfma_f32_16x16x32_bf16 v[98:101], v[196:199], v[228:231], v[98:101]
	s_setprio 0
	s_barrier
	s_add_i32 s28, s52, s16
	v_lshl_add_u64 v[166:167], v[166:167], 0, s[6:7]
	s_mov_b32 m0, s28
	ds_read_b128 v[200:203], v182 offset:49152
	ds_read_b128 v[204:207], v182 offset:50176
	ds_read_b128 v[208:211], v182 offset:51200
	ds_read_b128 v[212:215], v182 offset:52224
	ds_read_b128 v[216:219], v182 offset:53248
	ds_read_b128 v[220:223], v182 offset:54272
	ds_read_b128 v[224:227], v182 offset:55296
	ds_read_b128 v[228:231], v182 offset:56320
	global_load_lds_dwordx4 v[166:167], off
	s_add_i32 m0, s28, 0x2000
	s_add_u32 s28, s36, 0x40080
	v_lshl_add_u64 v[166:167], v[232:233], 0, s[6:7]
	s_addc_u32 s29, s37, 0
	s_add_i32 s36, s53, s16
	global_load_lds_dwordx4 v[166:167], off
	s_mov_b32 m0, s36
	v_lshl_add_u64 v[166:167], s[28:29], 0, v[134:135]
	global_load_lds_dwordx4 v[166:167], off
	s_add_i32 m0, s36, 0x2000
	v_lshl_add_u64 v[166:167], s[28:29], 0, v[136:137]
	global_load_lds_dwordx4 v[166:167], off
	s_mov_b32 m0, s42
	v_lshl_add_u64 v[166:167], v[234:235], 0, s[6:7]
	global_load_lds_dwordx4 v[166:167], off
	s_mov_b32 m0, s43
	v_lshl_add_u64 v[166:167], v[236:237], 0, s[6:7]
	global_load_lds_dwordx4 v[166:167], off
	s_waitcnt vmcnt(8)
	s_waitcnt lgkmcnt(0)
	s_barrier
	s_setprio 1
	s_waitcnt lgkmcnt(0)
	v_mfma_f32_16x16x32_bf16 v[38:41], v[150:153], v[200:203], v[38:41]
	v_mfma_f32_16x16x32_bf16 v[34:37], v[158:161], v[200:203], v[34:37]
	v_mfma_f32_16x16x32_bf16 v[26:29], v[150:153], v[208:211], v[26:29]
	v_mfma_f32_16x16x32_bf16 v[22:25], v[158:161], v[208:211], v[22:25]
	v_mfma_f32_16x16x32_bf16 v[14:17], v[150:153], v[216:219], v[14:17]
	v_mfma_f32_16x16x32_bf16 v[10:13], v[158:161], v[216:219], v[10:13]
	v_mfma_f32_16x16x32_bf16 v[6:9], v[150:153], v[224:227], v[6:9]
	v_mfma_f32_16x16x32_bf16 v[2:5], v[158:161], v[224:227], v[2:5]
	v_mfma_f32_16x16x32_bf16 v[38:41], v[154:157], v[204:207], v[38:41]
	v_mfma_f32_16x16x32_bf16 v[34:37], v[162:165], v[204:207], v[34:37]
	v_mfma_f32_16x16x32_bf16 v[26:29], v[154:157], v[212:215], v[26:29]
	v_mfma_f32_16x16x32_bf16 v[22:25], v[162:165], v[212:215], v[22:25]
	v_mfma_f32_16x16x32_bf16 v[14:17], v[154:157], v[220:223], v[14:17]
	v_mfma_f32_16x16x32_bf16 v[10:13], v[162:165], v[220:223], v[10:13]
	v_mfma_f32_16x16x32_bf16 v[6:9], v[154:157], v[228:231], v[6:9]
	v_mfma_f32_16x16x32_bf16 v[2:5], v[162:165], v[228:231], v[2:5]
	s_setprio 0
	s_setprio 1
	v_mfma_f32_16x16x32_bf16 v[94:97], v[184:187], v[200:203], v[94:97]
	v_mfma_f32_16x16x32_bf16 v[90:93], v[192:195], v[200:203], v[90:93]
	v_mfma_f32_16x16x32_bf16 v[86:89], v[184:187], v[208:211], v[86:89]
	v_mfma_f32_16x16x32_bf16 v[74:77], v[192:195], v[208:211], v[74:77]
	v_mfma_f32_16x16x32_bf16 v[46:49], v[184:187], v[216:219], v[46:49]
	v_mfma_f32_16x16x32_bf16 v[42:45], v[192:195], v[216:219], v[42:45]
	v_mfma_f32_16x16x32_bf16 v[30:33], v[184:187], v[224:227], v[30:33]
	v_mfma_f32_16x16x32_bf16 v[18:21], v[192:195], v[224:227], v[18:21]
	v_mfma_f32_16x16x32_bf16 v[94:97], v[188:191], v[204:207], v[94:97]
	v_mfma_f32_16x16x32_bf16 v[90:93], v[196:199], v[204:207], v[90:93]
	v_mfma_f32_16x16x32_bf16 v[86:89], v[188:191], v[212:215], v[86:89]
	v_mfma_f32_16x16x32_bf16 v[74:77], v[196:199], v[212:215], v[74:77]
	v_mfma_f32_16x16x32_bf16 v[46:49], v[188:191], v[220:223], v[46:49]
	v_mfma_f32_16x16x32_bf16 v[42:45], v[196:199], v[220:223], v[42:45]
	v_mfma_f32_16x16x32_bf16 v[30:33], v[188:191], v[228:231], v[30:33]
	v_mfma_f32_16x16x32_bf16 v[18:21], v[196:199], v[228:231], v[18:21]
	s_setprio 0
	s_barrier
	s_add_i32 s51, s51, 2
	s_add_u32 s49, s49, 0x100
	s_addc_u32 s50, s50, 0
	s_cmp_gt_u32 s51, 13
	s_mov_b64 s[28:29], s[30:31]
	s_cbranch_scc0 .LBB0_373
	s_branch .Lpeel_exit_373
.LBB0_373:
	ds_read_b128 v[150:153], v180
	ds_read_b128 v[154:157], v180 offset:1024
	ds_read_b128 v[158:161], v180 offset:2048
	ds_read_b128 v[162:165], v180 offset:3072
	ds_read_b128 v[184:187], v181
	ds_read_b128 v[188:191], v181 offset:1024
	ds_read_b128 v[192:195], v181 offset:2048
	ds_read_b128 v[196:199], v181 offset:3072
	s_add_u32 s30, s28, 0x100
	s_addc_u32 s31, s29, 0
	s_cmp_eq_u32 s51, 12
	s_cselect_b32 s39, s21, s31
	s_cselect_b32 s38, s27, s30
	s_cselect_b32 s37, s13, s50
	s_cselect_b32 s36, s48, s49
	v_lshl_add_u64 v[166:167], s[28:29], 0, v[142:143]
	s_add_i32 m0, s17, 0xc000
	ds_read_b128 v[200:203], v182
	ds_read_b128 v[204:207], v182 offset:1024
	ds_read_b128 v[208:211], v182 offset:2048
	ds_read_b128 v[212:215], v182 offset:3072
	ds_read_b128 v[216:219], v182 offset:4096
	ds_read_b128 v[220:223], v182 offset:5120
	ds_read_b128 v[224:227], v182 offset:6144
	ds_read_b128 v[228:231], v182 offset:7168
	global_load_lds_dwordx4 v[166:167], off
	s_add_i32 m0, s17, 0xe000
	v_lshl_add_u64 v[166:167], s[28:29], 0, v[144:145]
	global_load_lds_dwordx4 v[166:167], off
	s_waitcnt vmcnt(8)
	s_waitcnt lgkmcnt(0)
	s_barrier
	s_setprio 1
	s_waitcnt lgkmcnt(0)
	v_mfma_f32_16x16x32_bf16 v[82:85], v[150:153], v[200:203], v[82:85]
	v_mfma_f32_16x16x32_bf16 v[78:81], v[158:161], v[200:203], v[78:81]
	v_mfma_f32_16x16x32_bf16 v[70:73], v[150:153], v[208:211], v[70:73]
	v_mfma_f32_16x16x32_bf16 v[66:69], v[158:161], v[208:211], v[66:69]
	v_mfma_f32_16x16x32_bf16 v[62:65], v[150:153], v[216:219], v[62:65]
	v_mfma_f32_16x16x32_bf16 v[58:61], v[158:161], v[216:219], v[58:61]
	v_mfma_f32_16x16x32_bf16 v[54:57], v[150:153], v[224:227], v[54:57]
	v_mfma_f32_16x16x32_bf16 v[50:53], v[158:161], v[224:227], v[50:53]
	v_mfma_f32_16x16x32_bf16 v[82:85], v[154:157], v[204:207], v[82:85]
	v_mfma_f32_16x16x32_bf16 v[78:81], v[162:165], v[204:207], v[78:81]
	v_mfma_f32_16x16x32_bf16 v[70:73], v[154:157], v[212:215], v[70:73]
	v_mfma_f32_16x16x32_bf16 v[66:69], v[162:165], v[212:215], v[66:69]
	v_mfma_f32_16x16x32_bf16 v[62:65], v[154:157], v[220:223], v[62:65]
	v_mfma_f32_16x16x32_bf16 v[58:61], v[162:165], v[220:223], v[58:61]
	v_mfma_f32_16x16x32_bf16 v[54:57], v[154:157], v[228:231], v[54:57]
	v_mfma_f32_16x16x32_bf16 v[50:53], v[162:165], v[228:231], v[50:53]
	s_setprio 0
	s_setprio 1
	v_mfma_f32_16x16x32_bf16 v[126:129], v[184:187], v[200:203], v[126:129]
	v_mfma_f32_16x16x32_bf16 v[122:125], v[192:195], v[200:203], v[122:125]
	v_mfma_f32_16x16x32_bf16 v[118:121], v[184:187], v[208:211], v[118:121]
	v_mfma_f32_16x16x32_bf16 v[114:117], v[192:195], v[208:211], v[114:117]
	v_mfma_f32_16x16x32_bf16 v[110:113], v[184:187], v[216:219], v[110:113]
	v_mfma_f32_16x16x32_bf16 v[106:109], v[192:195], v[216:219], v[106:109]
	v_mfma_f32_16x16x32_bf16 v[102:105], v[184:187], v[224:227], v[102:105]
	v_mfma_f32_16x16x32_bf16 v[98:101], v[192:195], v[224:227], v[98:101]
	v_mfma_f32_16x16x32_bf16 v[126:129], v[188:191], v[204:207], v[126:129]
	v_mfma_f32_16x16x32_bf16 v[122:125], v[196:199], v[204:207], v[122:125]
	v_mfma_f32_16x16x32_bf16 v[118:121], v[188:191], v[212:215], v[118:121]
	v_mfma_f32_16x16x32_bf16 v[114:117], v[196:199], v[212:215], v[114:117]
	v_mfma_f32_16x16x32_bf16 v[110:113], v[188:191], v[220:223], v[110:113]
	v_mfma_f32_16x16x32_bf16 v[106:109], v[196:199], v[220:223], v[106:109]
	v_mfma_f32_16x16x32_bf16 v[102:105], v[188:191], v[228:231], v[102:105]
	v_mfma_f32_16x16x32_bf16 v[98:101], v[196:199], v[228:231], v[98:101]
	s_setprio 0
	s_barrier
	s_add_i32 s28, s45, s16
	v_lshl_add_u64 v[166:167], s[36:37], 0, v[134:135]
	s_mov_b32 m0, s28
	ds_read_b128 v[200:203], v182 offset:16384
	ds_read_b128 v[204:207], v182 offset:17408
	ds_read_b128 v[208:211], v182 offset:18432
	ds_read_b128 v[212:215], v182 offset:19456
	ds_read_b128 v[216:219], v182 offset:20480
	ds_read_b128 v[220:223], v182 offset:21504
	ds_read_b128 v[224:227], v182 offset:22528
	ds_read_b128 v[228:231], v182 offset:23552
	global_load_lds_dwordx4 v[166:167], off
	s_add_i32 m0, s28, 0x2000
	s_add_u32 s28, s36, 0x40000
	v_lshl_add_u64 v[232:233], s[36:37], 0, v[136:137]
	s_addc_u32 s29, s37, 0
	s_add_i32 s52, s46, s16
	global_load_lds_dwordx4 v[232:233], off
	v_lshl_add_u64 v[234:235], s[28:29], 0, v[134:135]
	s_mov_b32 m0, s52
	v_lshl_add_u64 v[236:237], s[38:39], 0, v[130:131]
	global_load_lds_dwordx4 v[234:235], off
	s_add_i32 m0, s52, 0x2000
	v_lshl_add_u64 v[234:235], s[28:29], 0, v[136:137]
	global_load_lds_dwordx4 v[234:235], off
	s_mov_b32 m0, s17
	v_lshl_add_u64 v[234:235], s[38:39], 0, v[132:133]
	global_load_lds_dwordx4 v[234:235], off
	s_mov_b32 m0, s34
	s_nop 0
	global_load_lds_dwordx4 v[236:237], off
	s_waitcnt vmcnt(8)
	s_waitcnt lgkmcnt(0)
	s_barrier
	s_setprio 1
	s_waitcnt lgkmcnt(0)
	v_mfma_f32_16x16x32_bf16 v[38:41], v[150:153], v[200:203], v[38:41]
	v_mfma_f32_16x16x32_bf16 v[34:37], v[158:161], v[200:203], v[34:37]
	v_mfma_f32_16x16x32_bf16 v[26:29], v[150:153], v[208:211], v[26:29]
	v_mfma_f32_16x16x32_bf16 v[22:25], v[158:161], v[208:211], v[22:25]
	v_mfma_f32_16x16x32_bf16 v[14:17], v[150:153], v[216:219], v[14:17]
	v_mfma_f32_16x16x32_bf16 v[10:13], v[158:161], v[216:219], v[10:13]
	v_mfma_f32_16x16x32_bf16 v[6:9], v[150:153], v[224:227], v[6:9]
	v_mfma_f32_16x16x32_bf16 v[2:5], v[158:161], v[224:227], v[2:5]
	v_mfma_f32_16x16x32_bf16 v[38:41], v[154:157], v[204:207], v[38:41]
	v_mfma_f32_16x16x32_bf16 v[34:37], v[162:165], v[204:207], v[34:37]
	v_mfma_f32_16x16x32_bf16 v[26:29], v[154:157], v[212:215], v[26:29]
	v_mfma_f32_16x16x32_bf16 v[22:25], v[162:165], v[212:215], v[22:25]
	v_mfma_f32_16x16x32_bf16 v[14:17], v[154:157], v[220:223], v[14:17]
	v_mfma_f32_16x16x32_bf16 v[10:13], v[162:165], v[220:223], v[10:13]
	v_mfma_f32_16x16x32_bf16 v[6:9], v[154:157], v[228:231], v[6:9]
	v_mfma_f32_16x16x32_bf16 v[2:5], v[162:165], v[228:231], v[2:5]
	s_setprio 0
	s_setprio 1
	v_mfma_f32_16x16x32_bf16 v[94:97], v[184:187], v[200:203], v[94:97]
	v_mfma_f32_16x16x32_bf16 v[90:93], v[192:195], v[200:203], v[90:93]
	v_mfma_f32_16x16x32_bf16 v[86:89], v[184:187], v[208:211], v[86:89]
	v_mfma_f32_16x16x32_bf16 v[74:77], v[192:195], v[208:211], v[74:77]
	v_mfma_f32_16x16x32_bf16 v[46:49], v[184:187], v[216:219], v[46:49]
	v_mfma_f32_16x16x32_bf16 v[42:45], v[192:195], v[216:219], v[42:45]
	v_mfma_f32_16x16x32_bf16 v[30:33], v[184:187], v[224:227], v[30:33]
	v_mfma_f32_16x16x32_bf16 v[18:21], v[192:195], v[224:227], v[18:21]
	v_mfma_f32_16x16x32_bf16 v[94:97], v[188:191], v[204:207], v[94:97]
	v_mfma_f32_16x16x32_bf16 v[90:93], v[196:199], v[204:207], v[90:93]
	v_mfma_f32_16x16x32_bf16 v[86:89], v[188:191], v[212:215], v[86:89]
	v_mfma_f32_16x16x32_bf16 v[74:77], v[196:199], v[212:215], v[74:77]
	v_mfma_f32_16x16x32_bf16 v[46:49], v[188:191], v[220:223], v[46:49]
	v_mfma_f32_16x16x32_bf16 v[42:45], v[196:199], v[220:223], v[42:45]
	v_mfma_f32_16x16x32_bf16 v[30:33], v[188:191], v[228:231], v[30:33]
	v_mfma_f32_16x16x32_bf16 v[18:21], v[196:199], v[228:231], v[18:21]
	s_setprio 0
	s_barrier
	s_add_i32 s52, 0, 0x18000
	v_add_u32_e32 v138, s52, v178
	s_add_i32 s53, 0, 0x1c000
	ds_read_b128 v[150:153], v138
	ds_read_b128 v[154:157], v138 offset:1024
	ds_read_b128 v[158:161], v138 offset:2048
	ds_read_b128 v[162:165], v138 offset:3072
	v_add_u32_e32 v138, s53, v178
	ds_read_b128 v[184:187], v138
	ds_read_b128 v[188:191], v138 offset:1024
	ds_read_b128 v[192:195], v138 offset:2048
	ds_read_b128 v[196:199], v138 offset:3072
	s_add_u32 s28, s38, 0x40000
	s_addc_u32 s29, s39, 0
	s_mov_b32 m0, s35
	v_lshl_add_u64 v[238:239], s[28:29], 0, v[132:133]
	ds_read_b128 v[200:203], v182 offset:32768
	ds_read_b128 v[204:207], v182 offset:33792
	ds_read_b128 v[208:211], v182 offset:34816
	ds_read_b128 v[212:215], v182 offset:35840
	ds_read_b128 v[216:219], v182 offset:36864
	ds_read_b128 v[220:223], v182 offset:37888
	ds_read_b128 v[224:227], v182 offset:38912
	ds_read_b128 v[228:231], v182 offset:39936
	global_load_lds_dwordx4 v[238:239], off
	s_mov_b32 m0, s40
	v_lshl_add_u64 v[238:239], s[28:29], 0, v[130:131]
	global_load_lds_dwordx4 v[238:239], off
	s_waitcnt vmcnt(8)
	s_waitcnt lgkmcnt(0)
	s_barrier
	s_setprio 1
	s_waitcnt lgkmcnt(0)
	v_mfma_f32_16x16x32_bf16 v[82:85], v[150:153], v[200:203], v[82:85]
	v_mfma_f32_16x16x32_bf16 v[78:81], v[158:161], v[200:203], v[78:81]
	v_mfma_f32_16x16x32_bf16 v[70:73], v[150:153], v[208:211], v[70:73]
	v_mfma_f32_16x16x32_bf16 v[66:69], v[158:161], v[208:211], v[66:69]
	v_mfma_f32_16x16x32_bf16 v[62:65], v[150:153], v[216:219], v[62:65]
	v_mfma_f32_16x16x32_bf16 v[58:61], v[158:161], v[216:219], v[58:61]
	v_mfma_f32_16x16x32_bf16 v[54:57], v[150:153], v[224:227], v[54:57]
	v_mfma_f32_16x16x32_bf16 v[50:53], v[158:161], v[224:227], v[50:53]
	v_mfma_f32_16x16x32_bf16 v[82:85], v[154:157], v[204:207], v[82:85]
	v_mfma_f32_16x16x32_bf16 v[78:81], v[162:165], v[204:207], v[78:81]
	v_mfma_f32_16x16x32_bf16 v[70:73], v[154:157], v[212:215], v[70:73]
	v_mfma_f32_16x16x32_bf16 v[66:69], v[162:165], v[212:215], v[66:69]
	v_mfma_f32_16x16x32_bf16 v[62:65], v[154:157], v[220:223], v[62:65]
	v_mfma_f32_16x16x32_bf16 v[58:61], v[162:165], v[220:223], v[58:61]
	v_mfma_f32_16x16x32_bf16 v[54:57], v[154:157], v[228:231], v[54:57]
	v_mfma_f32_16x16x32_bf16 v[50:53], v[162:165], v[228:231], v[50:53]
	s_setprio 0
	s_setprio 1
	v_mfma_f32_16x16x32_bf16 v[126:129], v[184:187], v[200:203], v[126:129]
	v_mfma_f32_16x16x32_bf16 v[122:125], v[192:195], v[200:203], v[122:125]
	v_mfma_f32_16x16x32_bf16 v[118:121], v[184:187], v[208:211], v[118:121]
	v_mfma_f32_16x16x32_bf16 v[114:117], v[192:195], v[208:211], v[114:117]
	v_mfma_f32_16x16x32_bf16 v[110:113], v[184:187], v[216:219], v[110:113]
	v_mfma_f32_16x16x32_bf16 v[106:109], v[192:195], v[216:219], v[106:109]
	v_mfma_f32_16x16x32_bf16 v[102:105], v[184:187], v[224:227], v[102:105]
	v_mfma_f32_16x16x32_bf16 v[98:101], v[192:195], v[224:227], v[98:101]
	v_mfma_f32_16x16x32_bf16 v[126:129], v[188:191], v[204:207], v[126:129]
	v_mfma_f32_16x16x32_bf16 v[122:125], v[196:199], v[204:207], v[122:125]
	v_mfma_f32_16x16x32_bf16 v[118:121], v[188:191], v[212:215], v[118:121]
	v_mfma_f32_16x16x32_bf16 v[114:117], v[196:199], v[212:215], v[114:117]
	v_mfma_f32_16x16x32_bf16 v[110:113], v[188:191], v[220:223], v[110:113]
	v_mfma_f32_16x16x32_bf16 v[106:109], v[196:199], v[220:223], v[106:109]
	v_mfma_f32_16x16x32_bf16 v[102:105], v[188:191], v[228:231], v[102:105]
	v_mfma_f32_16x16x32_bf16 v[98:101], v[196:199], v[228:231], v[98:101]
	s_setprio 0
	s_barrier
	s_add_i32 s28, s52, s16
	v_lshl_add_u64 v[166:167], v[166:167], 0, s[6:7]
	s_mov_b32 m0, s28
	ds_read_b128 v[200:203], v182 offset:49152
	ds_read_b128 v[204:207], v182 offset:50176
	ds_read_b128 v[208:211], v182 offset:51200
	ds_read_b128 v[212:215], v182 offset:52224
	ds_read_b128 v[216:219], v182 offset:53248
	ds_read_b128 v[220:223], v182 offset:54272
	ds_read_b128 v[224:227], v182 offset:55296
	ds_read_b128 v[228:231], v182 offset:56320
	global_load_lds_dwordx4 v[166:167], off
	s_add_i32 m0, s28, 0x2000
	s_add_u32 s28, s36, 0x40080
	v_lshl_add_u64 v[166:167], v[232:233], 0, s[6:7]
	s_addc_u32 s29, s37, 0
	s_add_i32 s36, s53, s16
	global_load_lds_dwordx4 v[166:167], off
	s_mov_b32 m0, s36
	v_lshl_add_u64 v[166:167], s[28:29], 0, v[134:135]
	global_load_lds_dwordx4 v[166:167], off
	s_add_i32 m0, s36, 0x2000
	v_lshl_add_u64 v[166:167], s[28:29], 0, v[136:137]
	global_load_lds_dwordx4 v[166:167], off
	s_mov_b32 m0, s42
	v_lshl_add_u64 v[166:167], v[234:235], 0, s[6:7]
	global_load_lds_dwordx4 v[166:167], off
	s_mov_b32 m0, s43
	v_lshl_add_u64 v[166:167], v[236:237], 0, s[6:7]
	global_load_lds_dwordx4 v[166:167], off
	s_waitcnt vmcnt(8)
	s_waitcnt lgkmcnt(0)
	s_barrier
	s_setprio 1
	s_waitcnt lgkmcnt(0)
	v_mfma_f32_16x16x32_bf16 v[38:41], v[150:153], v[200:203], v[38:41]
	v_mfma_f32_16x16x32_bf16 v[34:37], v[158:161], v[200:203], v[34:37]
	v_mfma_f32_16x16x32_bf16 v[26:29], v[150:153], v[208:211], v[26:29]
	v_mfma_f32_16x16x32_bf16 v[22:25], v[158:161], v[208:211], v[22:25]
	v_mfma_f32_16x16x32_bf16 v[14:17], v[150:153], v[216:219], v[14:17]
	v_mfma_f32_16x16x32_bf16 v[10:13], v[158:161], v[216:219], v[10:13]
	v_mfma_f32_16x16x32_bf16 v[6:9], v[150:153], v[224:227], v[6:9]
	v_mfma_f32_16x16x32_bf16 v[2:5], v[158:161], v[224:227], v[2:5]
	v_mfma_f32_16x16x32_bf16 v[38:41], v[154:157], v[204:207], v[38:41]
	v_mfma_f32_16x16x32_bf16 v[34:37], v[162:165], v[204:207], v[34:37]
	v_mfma_f32_16x16x32_bf16 v[26:29], v[154:157], v[212:215], v[26:29]
	v_mfma_f32_16x16x32_bf16 v[22:25], v[162:165], v[212:215], v[22:25]
	v_mfma_f32_16x16x32_bf16 v[14:17], v[154:157], v[220:223], v[14:17]
	v_mfma_f32_16x16x32_bf16 v[10:13], v[162:165], v[220:223], v[10:13]
	v_mfma_f32_16x16x32_bf16 v[6:9], v[154:157], v[228:231], v[6:9]
	v_mfma_f32_16x16x32_bf16 v[2:5], v[162:165], v[228:231], v[2:5]
	s_setprio 0
	s_setprio 1
	v_mfma_f32_16x16x32_bf16 v[94:97], v[184:187], v[200:203], v[94:97]
	v_mfma_f32_16x16x32_bf16 v[90:93], v[192:195], v[200:203], v[90:93]
	v_mfma_f32_16x16x32_bf16 v[86:89], v[184:187], v[208:211], v[86:89]
	v_mfma_f32_16x16x32_bf16 v[74:77], v[192:195], v[208:211], v[74:77]
	v_mfma_f32_16x16x32_bf16 v[46:49], v[184:187], v[216:219], v[46:49]
	v_mfma_f32_16x16x32_bf16 v[42:45], v[192:195], v[216:219], v[42:45]
	v_mfma_f32_16x16x32_bf16 v[30:33], v[184:187], v[224:227], v[30:33]
	v_mfma_f32_16x16x32_bf16 v[18:21], v[192:195], v[224:227], v[18:21]
	v_mfma_f32_16x16x32_bf16 v[94:97], v[188:191], v[204:207], v[94:97]
	v_mfma_f32_16x16x32_bf16 v[90:93], v[196:199], v[204:207], v[90:93]
	v_mfma_f32_16x16x32_bf16 v[86:89], v[188:191], v[212:215], v[86:89]
	v_mfma_f32_16x16x32_bf16 v[74:77], v[196:199], v[212:215], v[74:77]
	v_mfma_f32_16x16x32_bf16 v[46:49], v[188:191], v[220:223], v[46:49]
	v_mfma_f32_16x16x32_bf16 v[42:45], v[196:199], v[220:223], v[42:45]
	v_mfma_f32_16x16x32_bf16 v[30:33], v[188:191], v[228:231], v[30:33]
	v_mfma_f32_16x16x32_bf16 v[18:21], v[196:199], v[228:231], v[18:21]
	s_setprio 0
	s_barrier
	s_add_i32 s51, s51, 2
	s_add_u32 s49, s49, 0x100
	s_addc_u32 s50, s50, 0
	s_cmp_gt_u32 s51, 13
	s_mov_b64 s[28:29], s[30:31]
	s_cbranch_scc0 .LBB0_373

.LBB0_404:
	s_ashr_i32 s29, s28, 31
	s_lshl_b64 s[30:31], s[28:29], 19
	s_add_u32 s30, s14, s30
	s_addc_u32 s31, s15, s31
	s_and_b64 s[34:35], s[24:25], exec
	s_cselect_b32 s5, s31, s41
	s_cselect_b32 s29, s30, s40
	s_ashr_i32 s27, s26, 31
	s_lshl_b64 s[34:35], s[26:27], 19
	s_add_u32 s36, s16, s34
	s_addc_u32 s37, s17, s35
	s_and_b64 s[34:35], s[24:25], exec
	s_cselect_b32 s27, s37, s43
	s_cselect_b32 s34, s36, s42
	s_add_u32 s35, s42, 0x100
	s_addc_u32 s39, s43, 0
	s_mov_b32 s61, -2
	ds_read_b128 v[140:143], v156
	ds_read_b128 v[144:147], v156 offset:1024
	ds_read_b128 v[148:151], v156 offset:2048
	ds_read_b128 v[164:167], v156 offset:3072
	ds_read_b128 v[168:171], v157
	ds_read_b128 v[178:181], v157 offset:1024
	ds_read_b128 v[182:185], v157 offset:2048
	ds_read_b128 v[186:189], v157 offset:3072
	s_add_u32 s42, s40, 0x100
	s_addc_u32 s43, s41, 0
	s_cmp_eq_u32 s61, 12
	s_cselect_b32 s47, s5, s43
	s_cselect_b32 s46, s29, s42
	s_cselect_b32 s45, s27, s39
	s_cselect_b32 s44, s34, s35
	v_lshl_add_u64 v[152:153], s[40:41], 0, v[136:137]
	s_add_i32 m0, s49, 0xc000
	ds_read_b128 v[190:193], v158
	ds_read_b128 v[194:197], v158 offset:1024
	ds_read_b128 v[198:201], v158 offset:2048
	ds_read_b128 v[202:205], v158 offset:3072
	ds_read_b128 v[206:209], v158 offset:4096
	ds_read_b128 v[210:213], v158 offset:5120
	ds_read_b128 v[214:217], v158 offset:6144
	ds_read_b128 v[218:221], v158 offset:7168
	global_load_lds_dwordx4 v[152:153], off
	s_add_i32 m0, s49, 0xe000
	v_lshl_add_u64 v[152:153], s[40:41], 0, v[138:139]
	global_load_lds_dwordx4 v[152:153], off
	s_waitcnt vmcnt(8)
	s_waitcnt lgkmcnt(0)
	s_barrier
	s_setprio 1
	s_waitcnt lgkmcnt(0)
	v_mfma_f32_16x16x32_bf16 v[126:129], v[140:143], v[190:193], 0
	v_mfma_f32_16x16x32_bf16 v[122:125], v[148:151], v[190:193], 0
	v_mfma_f32_16x16x32_bf16 v[110:113], v[140:143], v[198:201], 0
	v_mfma_f32_16x16x32_bf16 v[106:109], v[148:151], v[198:201], 0
	v_mfma_f32_16x16x32_bf16 v[94:97], v[140:143], v[206:209], 0
	v_mfma_f32_16x16x32_bf16 v[90:93], v[148:151], v[206:209], 0
	v_mfma_f32_16x16x32_bf16 v[78:81], v[140:143], v[214:217], 0
	v_mfma_f32_16x16x32_bf16 v[74:77], v[148:151], v[214:217], 0
	v_mfma_f32_16x16x32_bf16 v[126:129], v[144:147], v[194:197], v[126:129]
	v_mfma_f32_16x16x32_bf16 v[122:125], v[164:167], v[194:197], v[122:125]
	v_mfma_f32_16x16x32_bf16 v[110:113], v[144:147], v[202:205], v[110:113]
	v_mfma_f32_16x16x32_bf16 v[106:109], v[164:167], v[202:205], v[106:109]
	v_mfma_f32_16x16x32_bf16 v[94:97], v[144:147], v[210:213], v[94:97]
	v_mfma_f32_16x16x32_bf16 v[90:93], v[164:167], v[210:213], v[90:93]
	v_mfma_f32_16x16x32_bf16 v[78:81], v[144:147], v[218:221], v[78:81]
	v_mfma_f32_16x16x32_bf16 v[74:77], v[164:167], v[218:221], v[74:77]
	s_setprio 0
	s_setprio 1
	v_mfma_f32_16x16x32_bf16 v[118:121], v[168:171], v[190:193], 0
	v_mfma_f32_16x16x32_bf16 v[114:117], v[182:185], v[190:193], 0
	v_mfma_f32_16x16x32_bf16 v[102:105], v[168:171], v[198:201], 0
	v_mfma_f32_16x16x32_bf16 v[98:101], v[182:185], v[198:201], 0
	v_mfma_f32_16x16x32_bf16 v[86:89], v[168:171], v[206:209], 0
	v_mfma_f32_16x16x32_bf16 v[82:85], v[182:185], v[206:209], 0
	v_mfma_f32_16x16x32_bf16 v[70:73], v[168:171], v[214:217], 0
	v_mfma_f32_16x16x32_bf16 v[66:69], v[182:185], v[214:217], 0
	v_mfma_f32_16x16x32_bf16 v[118:121], v[178:181], v[194:197], v[118:121]
	v_mfma_f32_16x16x32_bf16 v[114:117], v[186:189], v[194:197], v[114:117]
	v_mfma_f32_16x16x32_bf16 v[102:105], v[178:181], v[202:205], v[102:105]
	v_mfma_f32_16x16x32_bf16 v[98:101], v[186:189], v[202:205], v[98:101]
	v_mfma_f32_16x16x32_bf16 v[86:89], v[178:181], v[210:213], v[86:89]
	v_mfma_f32_16x16x32_bf16 v[82:85], v[186:189], v[210:213], v[82:85]
	v_mfma_f32_16x16x32_bf16 v[70:73], v[178:181], v[218:221], v[70:73]
	v_mfma_f32_16x16x32_bf16 v[66:69], v[186:189], v[218:221], v[66:69]
	s_setprio 0
	s_barrier
	s_add_i32 s40, s59, s48
	v_lshl_add_u64 v[152:153], s[44:45], 0, v[132:133]
	s_mov_b32 m0, s40
	ds_read_b128 v[190:193], v158 offset:16384
	ds_read_b128 v[194:197], v158 offset:17408
	ds_read_b128 v[198:201], v158 offset:18432
	ds_read_b128 v[202:205], v158 offset:19456
	ds_read_b128 v[206:209], v158 offset:20480
	ds_read_b128 v[210:213], v158 offset:21504
	ds_read_b128 v[214:217], v158 offset:22528
	ds_read_b128 v[218:221], v158 offset:23552
	global_load_lds_dwordx4 v[152:153], off
	s_add_i32 m0, s40, 0x2000
	s_add_u32 s40, s44, 0x40000
	v_lshl_add_u64 v[172:173], s[44:45], 0, v[130:131]
	s_addc_u32 s41, s45, 0
	s_add_i32 s62, s60, s48
	global_load_lds_dwordx4 v[172:173], off
	v_lshl_add_u64 v[222:223], s[40:41], 0, v[132:133]
	s_mov_b32 m0, s62
	v_lshl_add_u64 v[224:225], s[46:47], 0, v[130:131]
	global_load_lds_dwordx4 v[222:223], off
	s_add_i32 m0, s62, 0x2000
	v_lshl_add_u64 v[222:223], s[40:41], 0, v[130:131]
	global_load_lds_dwordx4 v[222:223], off
	s_mov_b32 m0, s49
	v_lshl_add_u64 v[222:223], s[46:47], 0, v[132:133]
	global_load_lds_dwordx4 v[222:223], off
	s_mov_b32 m0, s50
	s_nop 0
	global_load_lds_dwordx4 v[224:225], off
	s_waitcnt vmcnt(8)
	s_waitcnt lgkmcnt(0)
	s_barrier
	s_setprio 1
	s_waitcnt lgkmcnt(0)
	v_mfma_f32_16x16x32_bf16 v[62:65], v[140:143], v[190:193], 0
	v_mfma_f32_16x16x32_bf16 v[58:61], v[148:151], v[190:193], 0
	v_mfma_f32_16x16x32_bf16 v[46:49], v[140:143], v[198:201], 0
	v_mfma_f32_16x16x32_bf16 v[42:45], v[148:151], v[198:201], 0
	v_mfma_f32_16x16x32_bf16 v[30:33], v[140:143], v[206:209], 0
	v_mfma_f32_16x16x32_bf16 v[26:29], v[148:151], v[206:209], 0
	v_mfma_f32_16x16x32_bf16 v[14:17], v[140:143], v[214:217], 0
	v_mfma_f32_16x16x32_bf16 v[10:13], v[148:151], v[214:217], 0
	v_mfma_f32_16x16x32_bf16 v[62:65], v[144:147], v[194:197], v[62:65]
	v_mfma_f32_16x16x32_bf16 v[58:61], v[164:167], v[194:197], v[58:61]
	v_mfma_f32_16x16x32_bf16 v[46:49], v[144:147], v[202:205], v[46:49]
	v_mfma_f32_16x16x32_bf16 v[42:45], v[164:167], v[202:205], v[42:45]
	v_mfma_f32_16x16x32_bf16 v[30:33], v[144:147], v[210:213], v[30:33]
	v_mfma_f32_16x16x32_bf16 v[26:29], v[164:167], v[210:213], v[26:29]
	v_mfma_f32_16x16x32_bf16 v[14:17], v[144:147], v[218:221], v[14:17]
	v_mfma_f32_16x16x32_bf16 v[10:13], v[164:167], v[218:221], v[10:13]
	s_setprio 0
	s_setprio 1
	v_mfma_f32_16x16x32_bf16 v[54:57], v[168:171], v[190:193], 0
	v_mfma_f32_16x16x32_bf16 v[50:53], v[182:185], v[190:193], 0
	v_mfma_f32_16x16x32_bf16 v[38:41], v[168:171], v[198:201], 0
	v_mfma_f32_16x16x32_bf16 v[34:37], v[182:185], v[198:201], 0
	v_mfma_f32_16x16x32_bf16 v[22:25], v[168:171], v[206:209], 0
	v_mfma_f32_16x16x32_bf16 v[18:21], v[182:185], v[206:209], 0
	v_mfma_f32_16x16x32_bf16 v[6:9], v[168:171], v[214:217], 0
	v_mfma_f32_16x16x32_bf16 v[2:5], v[182:185], v[214:217], 0
	v_mfma_f32_16x16x32_bf16 v[54:57], v[178:181], v[194:197], v[54:57]
	v_mfma_f32_16x16x32_bf16 v[50:53], v[186:189], v[194:197], v[50:53]
	v_mfma_f32_16x16x32_bf16 v[38:41], v[178:181], v[202:205], v[38:41]
	v_mfma_f32_16x16x32_bf16 v[34:37], v[186:189], v[202:205], v[34:37]
	v_mfma_f32_16x16x32_bf16 v[22:25], v[178:181], v[210:213], v[22:25]
	v_mfma_f32_16x16x32_bf16 v[18:21], v[186:189], v[210:213], v[18:21]
	v_mfma_f32_16x16x32_bf16 v[6:9], v[178:181], v[218:221], v[6:9]
	v_mfma_f32_16x16x32_bf16 v[2:5], v[186:189], v[218:221], v[2:5]
	s_setprio 0
	s_barrier
	s_add_i32 s62, 0, 0x18000
	v_add_u32_e32 v134, s62, v154
	s_add_i32 s63, 0, 0x1c000
	ds_read_b128 v[140:143], v134
	ds_read_b128 v[144:147], v134 offset:1024
	ds_read_b128 v[148:151], v134 offset:2048
	ds_read_b128 v[164:167], v134 offset:3072
	v_add_u32_e32 v134, s63, v154
	ds_read_b128 v[168:171], v134
	ds_read_b128 v[178:181], v134 offset:1024
	ds_read_b128 v[182:185], v134 offset:2048
	ds_read_b128 v[186:189], v134 offset:3072
	s_add_u32 s40, s46, 0x40000
	s_addc_u32 s41, s47, 0
	s_mov_b32 m0, s51
	v_lshl_add_u64 v[226:227], s[40:41], 0, v[132:133]
	ds_read_b128 v[190:193], v158 offset:32768
	ds_read_b128 v[194:197], v158 offset:33792
	ds_read_b128 v[198:201], v158 offset:34816
	ds_read_b128 v[202:205], v158 offset:35840
	ds_read_b128 v[206:209], v158 offset:36864
	ds_read_b128 v[210:213], v158 offset:37888
	ds_read_b128 v[214:217], v158 offset:38912
	ds_read_b128 v[218:221], v158 offset:39936
	global_load_lds_dwordx4 v[226:227], off
	s_mov_b32 m0, s52
	v_lshl_add_u64 v[226:227], s[40:41], 0, v[130:131]
	global_load_lds_dwordx4 v[226:227], off
	s_waitcnt vmcnt(8)
	s_waitcnt lgkmcnt(0)
	s_barrier
	s_setprio 1
	s_waitcnt lgkmcnt(0)
	v_mfma_f32_16x16x32_bf16 v[126:129], v[140:143], v[190:193], v[126:129]
	v_mfma_f32_16x16x32_bf16 v[122:125], v[148:151], v[190:193], v[122:125]
	v_mfma_f32_16x16x32_bf16 v[110:113], v[140:143], v[198:201], v[110:113]
	v_mfma_f32_16x16x32_bf16 v[106:109], v[148:151], v[198:201], v[106:109]
	v_mfma_f32_16x16x32_bf16 v[94:97], v[140:143], v[206:209], v[94:97]
	v_mfma_f32_16x16x32_bf16 v[90:93], v[148:151], v[206:209], v[90:93]
	v_mfma_f32_16x16x32_bf16 v[78:81], v[140:143], v[214:217], v[78:81]
	v_mfma_f32_16x16x32_bf16 v[74:77], v[148:151], v[214:217], v[74:77]
	v_mfma_f32_16x16x32_bf16 v[126:129], v[144:147], v[194:197], v[126:129]
	v_mfma_f32_16x16x32_bf16 v[122:125], v[164:167], v[194:197], v[122:125]
	v_mfma_f32_16x16x32_bf16 v[110:113], v[144:147], v[202:205], v[110:113]
	v_mfma_f32_16x16x32_bf16 v[106:109], v[164:167], v[202:205], v[106:109]
	v_mfma_f32_16x16x32_bf16 v[94:97], v[144:147], v[210:213], v[94:97]
	v_mfma_f32_16x16x32_bf16 v[90:93], v[164:167], v[210:213], v[90:93]
	v_mfma_f32_16x16x32_bf16 v[78:81], v[144:147], v[218:221], v[78:81]
	v_mfma_f32_16x16x32_bf16 v[74:77], v[164:167], v[218:221], v[74:77]
	s_setprio 0
	s_setprio 1
	v_mfma_f32_16x16x32_bf16 v[118:121], v[168:171], v[190:193], v[118:121]
	v_mfma_f32_16x16x32_bf16 v[114:117], v[182:185], v[190:193], v[114:117]
	v_mfma_f32_16x16x32_bf16 v[102:105], v[168:171], v[198:201], v[102:105]
	v_mfma_f32_16x16x32_bf16 v[98:101], v[182:185], v[198:201], v[98:101]
	v_mfma_f32_16x16x32_bf16 v[86:89], v[168:171], v[206:209], v[86:89]
	v_mfma_f32_16x16x32_bf16 v[82:85], v[182:185], v[206:209], v[82:85]
	v_mfma_f32_16x16x32_bf16 v[70:73], v[168:171], v[214:217], v[70:73]
	v_mfma_f32_16x16x32_bf16 v[66:69], v[182:185], v[214:217], v[66:69]
	v_mfma_f32_16x16x32_bf16 v[118:121], v[178:181], v[194:197], v[118:121]
	v_mfma_f32_16x16x32_bf16 v[114:117], v[186:189], v[194:197], v[114:117]
	v_mfma_f32_16x16x32_bf16 v[102:105], v[178:181], v[202:205], v[102:105]
	v_mfma_f32_16x16x32_bf16 v[98:101], v[186:189], v[202:205], v[98:101]
	v_mfma_f32_16x16x32_bf16 v[86:89], v[178:181], v[210:213], v[86:89]
	v_mfma_f32_16x16x32_bf16 v[82:85], v[186:189], v[210:213], v[82:85]
	v_mfma_f32_16x16x32_bf16 v[70:73], v[178:181], v[218:221], v[70:73]
	v_mfma_f32_16x16x32_bf16 v[66:69], v[186:189], v[218:221], v[66:69]
	s_setprio 0
	s_barrier
	s_add_i32 s40, s62, s48
	v_lshl_add_u64 v[152:153], v[152:153], 0, s[20:21]
	s_mov_b32 m0, s40
	ds_read_b128 v[190:193], v158 offset:49152
	ds_read_b128 v[194:197], v158 offset:50176
	ds_read_b128 v[198:201], v158 offset:51200
	ds_read_b128 v[202:205], v158 offset:52224
	ds_read_b128 v[206:209], v158 offset:53248
	ds_read_b128 v[210:213], v158 offset:54272
	ds_read_b128 v[214:217], v158 offset:55296
	ds_read_b128 v[218:221], v158 offset:56320
	global_load_lds_dwordx4 v[152:153], off
	s_add_i32 m0, s40, 0x2000
	s_add_u32 s40, s44, 0x40080
	v_lshl_add_u64 v[152:153], v[172:173], 0, s[20:21]
	s_addc_u32 s41, s45, 0
	s_add_i32 s44, s63, s48
	global_load_lds_dwordx4 v[152:153], off
	s_mov_b32 m0, s44
	v_lshl_add_u64 v[152:153], s[40:41], 0, v[132:133]
	global_load_lds_dwordx4 v[152:153], off
	s_add_i32 m0, s44, 0x2000
	v_lshl_add_u64 v[152:153], s[40:41], 0, v[130:131]
	global_load_lds_dwordx4 v[152:153], off
	s_mov_b32 m0, s55
	v_lshl_add_u64 v[152:153], v[222:223], 0, s[20:21]
	global_load_lds_dwordx4 v[152:153], off
	s_mov_b32 m0, s56
	v_lshl_add_u64 v[152:153], v[224:225], 0, s[20:21]
	global_load_lds_dwordx4 v[152:153], off
	s_waitcnt vmcnt(8)
	s_waitcnt lgkmcnt(0)
	s_barrier
	s_setprio 1
	s_waitcnt lgkmcnt(0)
	v_mfma_f32_16x16x32_bf16 v[62:65], v[140:143], v[190:193], v[62:65]
	v_mfma_f32_16x16x32_bf16 v[58:61], v[148:151], v[190:193], v[58:61]
	v_mfma_f32_16x16x32_bf16 v[46:49], v[140:143], v[198:201], v[46:49]
	v_mfma_f32_16x16x32_bf16 v[42:45], v[148:151], v[198:201], v[42:45]
	v_mfma_f32_16x16x32_bf16 v[30:33], v[140:143], v[206:209], v[30:33]
	v_mfma_f32_16x16x32_bf16 v[26:29], v[148:151], v[206:209], v[26:29]
	v_mfma_f32_16x16x32_bf16 v[14:17], v[140:143], v[214:217], v[14:17]
	v_mfma_f32_16x16x32_bf16 v[10:13], v[148:151], v[214:217], v[10:13]
	v_mfma_f32_16x16x32_bf16 v[62:65], v[144:147], v[194:197], v[62:65]
	v_mfma_f32_16x16x32_bf16 v[58:61], v[164:167], v[194:197], v[58:61]
	v_mfma_f32_16x16x32_bf16 v[46:49], v[144:147], v[202:205], v[46:49]
	v_mfma_f32_16x16x32_bf16 v[42:45], v[164:167], v[202:205], v[42:45]
	v_mfma_f32_16x16x32_bf16 v[30:33], v[144:147], v[210:213], v[30:33]
	v_mfma_f32_16x16x32_bf16 v[26:29], v[164:167], v[210:213], v[26:29]
	v_mfma_f32_16x16x32_bf16 v[14:17], v[144:147], v[218:221], v[14:17]
	v_mfma_f32_16x16x32_bf16 v[10:13], v[164:167], v[218:221], v[10:13]
	s_setprio 0
	s_setprio 1
	v_mfma_f32_16x16x32_bf16 v[54:57], v[168:171], v[190:193], v[54:57]
	v_mfma_f32_16x16x32_bf16 v[50:53], v[182:185], v[190:193], v[50:53]
	v_mfma_f32_16x16x32_bf16 v[38:41], v[168:171], v[198:201], v[38:41]
	v_mfma_f32_16x16x32_bf16 v[34:37], v[182:185], v[198:201], v[34:37]
	v_mfma_f32_16x16x32_bf16 v[22:25], v[168:171], v[206:209], v[22:25]
	v_mfma_f32_16x16x32_bf16 v[18:21], v[182:185], v[206:209], v[18:21]
	v_mfma_f32_16x16x32_bf16 v[6:9], v[168:171], v[214:217], v[6:9]
	v_mfma_f32_16x16x32_bf16 v[2:5], v[182:185], v[214:217], v[2:5]
	v_mfma_f32_16x16x32_bf16 v[54:57], v[178:181], v[194:197], v[54:57]
	v_mfma_f32_16x16x32_bf16 v[50:53], v[186:189], v[194:197], v[50:53]
	v_mfma_f32_16x16x32_bf16 v[38:41], v[178:181], v[202:205], v[38:41]
	v_mfma_f32_16x16x32_bf16 v[34:37], v[186:189], v[202:205], v[34:37]
	v_mfma_f32_16x16x32_bf16 v[22:25], v[178:181], v[210:213], v[22:25]
	v_mfma_f32_16x16x32_bf16 v[18:21], v[186:189], v[210:213], v[18:21]
	v_mfma_f32_16x16x32_bf16 v[6:9], v[178:181], v[218:221], v[6:9]
	v_mfma_f32_16x16x32_bf16 v[2:5], v[186:189], v[218:221], v[2:5]
	s_setprio 0
	s_barrier
	s_add_i32 s61, s61, 2
	s_add_u32 s35, s35, 0x100
	s_addc_u32 s39, s39, 0
	s_cmp_gt_u32 s61, 13
	s_mov_b64 s[40:41], s[42:43]
	s_cbranch_scc0 .LBB0_405
	s_branch .Lpeel_exit_405
.LBB0_405:
	ds_read_b128 v[140:143], v156
	ds_read_b128 v[144:147], v156 offset:1024
	ds_read_b128 v[148:151], v156 offset:2048
	ds_read_b128 v[164:167], v156 offset:3072
	ds_read_b128 v[168:171], v157
	ds_read_b128 v[178:181], v157 offset:1024
	ds_read_b128 v[182:185], v157 offset:2048
	ds_read_b128 v[186:189], v157 offset:3072
	s_add_u32 s42, s40, 0x100
	s_addc_u32 s43, s41, 0
	s_cmp_eq_u32 s61, 12
	s_cselect_b32 s47, s5, s43
	s_cselect_b32 s46, s29, s42
	s_cselect_b32 s45, s27, s39
	s_cselect_b32 s44, s34, s35
	v_lshl_add_u64 v[152:153], s[40:41], 0, v[136:137]
	s_add_i32 m0, s49, 0xc000
	ds_read_b128 v[190:193], v158
	ds_read_b128 v[194:197], v158 offset:1024
	ds_read_b128 v[198:201], v158 offset:2048
	ds_read_b128 v[202:205], v158 offset:3072
	ds_read_b128 v[206:209], v158 offset:4096
	ds_read_b128 v[210:213], v158 offset:5120
	ds_read_b128 v[214:217], v158 offset:6144
	ds_read_b128 v[218:221], v158 offset:7168
	global_load_lds_dwordx4 v[152:153], off
	s_add_i32 m0, s49, 0xe000
	v_lshl_add_u64 v[152:153], s[40:41], 0, v[138:139]
	global_load_lds_dwordx4 v[152:153], off
	s_waitcnt vmcnt(8)
	s_waitcnt lgkmcnt(0)
	s_barrier
	s_setprio 1
	s_waitcnt lgkmcnt(0)
	v_mfma_f32_16x16x32_bf16 v[126:129], v[140:143], v[190:193], v[126:129]
	v_mfma_f32_16x16x32_bf16 v[122:125], v[148:151], v[190:193], v[122:125]
	v_mfma_f32_16x16x32_bf16 v[110:113], v[140:143], v[198:201], v[110:113]
	v_mfma_f32_16x16x32_bf16 v[106:109], v[148:151], v[198:201], v[106:109]
	v_mfma_f32_16x16x32_bf16 v[94:97], v[140:143], v[206:209], v[94:97]
	v_mfma_f32_16x16x32_bf16 v[90:93], v[148:151], v[206:209], v[90:93]
	v_mfma_f32_16x16x32_bf16 v[78:81], v[140:143], v[214:217], v[78:81]
	v_mfma_f32_16x16x32_bf16 v[74:77], v[148:151], v[214:217], v[74:77]
	v_mfma_f32_16x16x32_bf16 v[126:129], v[144:147], v[194:197], v[126:129]
	v_mfma_f32_16x16x32_bf16 v[122:125], v[164:167], v[194:197], v[122:125]
	v_mfma_f32_16x16x32_bf16 v[110:113], v[144:147], v[202:205], v[110:113]
	v_mfma_f32_16x16x32_bf16 v[106:109], v[164:167], v[202:205], v[106:109]
	v_mfma_f32_16x16x32_bf16 v[94:97], v[144:147], v[210:213], v[94:97]
	v_mfma_f32_16x16x32_bf16 v[90:93], v[164:167], v[210:213], v[90:93]
	v_mfma_f32_16x16x32_bf16 v[78:81], v[144:147], v[218:221], v[78:81]
	v_mfma_f32_16x16x32_bf16 v[74:77], v[164:167], v[218:221], v[74:77]
	s_setprio 0
	s_setprio 1
	v_mfma_f32_16x16x32_bf16 v[118:121], v[168:171], v[190:193], v[118:121]
	v_mfma_f32_16x16x32_bf16 v[114:117], v[182:185], v[190:193], v[114:117]
	v_mfma_f32_16x16x32_bf16 v[102:105], v[168:171], v[198:201], v[102:105]
	v_mfma_f32_16x16x32_bf16 v[98:101], v[182:185], v[198:201], v[98:101]
	v_mfma_f32_16x16x32_bf16 v[86:89], v[168:171], v[206:209], v[86:89]
	v_mfma_f32_16x16x32_bf16 v[82:85], v[182:185], v[206:209], v[82:85]
	v_mfma_f32_16x16x32_bf16 v[70:73], v[168:171], v[214:217], v[70:73]
	v_mfma_f32_16x16x32_bf16 v[66:69], v[182:185], v[214:217], v[66:69]
	v_mfma_f32_16x16x32_bf16 v[118:121], v[178:181], v[194:197], v[118:121]
	v_mfma_f32_16x16x32_bf16 v[114:117], v[186:189], v[194:197], v[114:117]
	v_mfma_f32_16x16x32_bf16 v[102:105], v[178:181], v[202:205], v[102:105]
	v_mfma_f32_16x16x32_bf16 v[98:101], v[186:189], v[202:205], v[98:101]
	v_mfma_f32_16x16x32_bf16 v[86:89], v[178:181], v[210:213], v[86:89]
	v_mfma_f32_16x16x32_bf16 v[82:85], v[186:189], v[210:213], v[82:85]
	v_mfma_f32_16x16x32_bf16 v[70:73], v[178:181], v[218:221], v[70:73]
	v_mfma_f32_16x16x32_bf16 v[66:69], v[186:189], v[218:221], v[66:69]
	s_setprio 0
	s_barrier
	s_add_i32 s40, s59, s48
	v_lshl_add_u64 v[152:153], s[44:45], 0, v[132:133]
	s_mov_b32 m0, s40
	ds_read_b128 v[190:193], v158 offset:16384
	ds_read_b128 v[194:197], v158 offset:17408
	ds_read_b128 v[198:201], v158 offset:18432
	ds_read_b128 v[202:205], v158 offset:19456
	ds_read_b128 v[206:209], v158 offset:20480
	ds_read_b128 v[210:213], v158 offset:21504
	ds_read_b128 v[214:217], v158 offset:22528
	ds_read_b128 v[218:221], v158 offset:23552
	global_load_lds_dwordx4 v[152:153], off
	s_add_i32 m0, s40, 0x2000
	s_add_u32 s40, s44, 0x40000
	v_lshl_add_u64 v[172:173], s[44:45], 0, v[130:131]
	s_addc_u32 s41, s45, 0
	s_add_i32 s62, s60, s48
	global_load_lds_dwordx4 v[172:173], off
	v_lshl_add_u64 v[222:223], s[40:41], 0, v[132:133]
	s_mov_b32 m0, s62
	v_lshl_add_u64 v[224:225], s[46:47], 0, v[130:131]
	global_load_lds_dwordx4 v[222:223], off
	s_add_i32 m0, s62, 0x2000
	v_lshl_add_u64 v[222:223], s[40:41], 0, v[130:131]
	global_load_lds_dwordx4 v[222:223], off
	s_mov_b32 m0, s49
	v_lshl_add_u64 v[222:223], s[46:47], 0, v[132:133]
	global_load_lds_dwordx4 v[222:223], off
	s_mov_b32 m0, s50
	s_nop 0
	global_load_lds_dwordx4 v[224:225], off
	s_waitcnt vmcnt(8)
	s_waitcnt lgkmcnt(0)
	s_barrier
	s_setprio 1
	s_waitcnt lgkmcnt(0)
	v_mfma_f32_16x16x32_bf16 v[62:65], v[140:143], v[190:193], v[62:65]
	v_mfma_f32_16x16x32_bf16 v[58:61], v[148:151], v[190:193], v[58:61]
	v_mfma_f32_16x16x32_bf16 v[46:49], v[140:143], v[198:201], v[46:49]
	v_mfma_f32_16x16x32_bf16 v[42:45], v[148:151], v[198:201], v[42:45]
	v_mfma_f32_16x16x32_bf16 v[30:33], v[140:143], v[206:209], v[30:33]
	v_mfma_f32_16x16x32_bf16 v[26:29], v[148:151], v[206:209], v[26:29]
	v_mfma_f32_16x16x32_bf16 v[14:17], v[140:143], v[214:217], v[14:17]
	v_mfma_f32_16x16x32_bf16 v[10:13], v[148:151], v[214:217], v[10:13]
	v_mfma_f32_16x16x32_bf16 v[62:65], v[144:147], v[194:197], v[62:65]
	v_mfma_f32_16x16x32_bf16 v[58:61], v[164:167], v[194:197], v[58:61]
	v_mfma_f32_16x16x32_bf16 v[46:49], v[144:147], v[202:205], v[46:49]
	v_mfma_f32_16x16x32_bf16 v[42:45], v[164:167], v[202:205], v[42:45]
	v_mfma_f32_16x16x32_bf16 v[30:33], v[144:147], v[210:213], v[30:33]
	v_mfma_f32_16x16x32_bf16 v[26:29], v[164:167], v[210:213], v[26:29]
	v_mfma_f32_16x16x32_bf16 v[14:17], v[144:147], v[218:221], v[14:17]
	v_mfma_f32_16x16x32_bf16 v[10:13], v[164:167], v[218:221], v[10:13]
	s_setprio 0
	s_setprio 1
	v_mfma_f32_16x16x32_bf16 v[54:57], v[168:171], v[190:193], v[54:57]
	v_mfma_f32_16x16x32_bf16 v[50:53], v[182:185], v[190:193], v[50:53]
	v_mfma_f32_16x16x32_bf16 v[38:41], v[168:171], v[198:201], v[38:41]
	v_mfma_f32_16x16x32_bf16 v[34:37], v[182:185], v[198:201], v[34:37]
	v_mfma_f32_16x16x32_bf16 v[22:25], v[168:171], v[206:209], v[22:25]
	v_mfma_f32_16x16x32_bf16 v[18:21], v[182:185], v[206:209], v[18:21]
	v_mfma_f32_16x16x32_bf16 v[6:9], v[168:171], v[214:217], v[6:9]
	v_mfma_f32_16x16x32_bf16 v[2:5], v[182:185], v[214:217], v[2:5]
	v_mfma_f32_16x16x32_bf16 v[54:57], v[178:181], v[194:197], v[54:57]
	v_mfma_f32_16x16x32_bf16 v[50:53], v[186:189], v[194:197], v[50:53]
	v_mfma_f32_16x16x32_bf16 v[38:41], v[178:181], v[202:205], v[38:41]
	v_mfma_f32_16x16x32_bf16 v[34:37], v[186:189], v[202:205], v[34:37]
	v_mfma_f32_16x16x32_bf16 v[22:25], v[178:181], v[210:213], v[22:25]
	v_mfma_f32_16x16x32_bf16 v[18:21], v[186:189], v[210:213], v[18:21]
	v_mfma_f32_16x16x32_bf16 v[6:9], v[178:181], v[218:221], v[6:9]
	v_mfma_f32_16x16x32_bf16 v[2:5], v[186:189], v[218:221], v[2:5]
	s_setprio 0
	s_barrier
	s_add_i32 s62, 0, 0x18000
	v_add_u32_e32 v134, s62, v154
	s_add_i32 s63, 0, 0x1c000
	ds_read_b128 v[140:143], v134
	ds_read_b128 v[144:147], v134 offset:1024
	ds_read_b128 v[148:151], v134 offset:2048
	ds_read_b128 v[164:167], v134 offset:3072
	v_add_u32_e32 v134, s63, v154
	ds_read_b128 v[168:171], v134
	ds_read_b128 v[178:181], v134 offset:1024
	ds_read_b128 v[182:185], v134 offset:2048
	ds_read_b128 v[186:189], v134 offset:3072
	s_add_u32 s40, s46, 0x40000
	s_addc_u32 s41, s47, 0
	s_mov_b32 m0, s51
	v_lshl_add_u64 v[226:227], s[40:41], 0, v[132:133]
	ds_read_b128 v[190:193], v158 offset:32768
	ds_read_b128 v[194:197], v158 offset:33792
	ds_read_b128 v[198:201], v158 offset:34816
	ds_read_b128 v[202:205], v158 offset:35840
	ds_read_b128 v[206:209], v158 offset:36864
	ds_read_b128 v[210:213], v158 offset:37888
	ds_read_b128 v[214:217], v158 offset:38912
	ds_read_b128 v[218:221], v158 offset:39936
	global_load_lds_dwordx4 v[226:227], off
	s_mov_b32 m0, s52
	v_lshl_add_u64 v[226:227], s[40:41], 0, v[130:131]
	global_load_lds_dwordx4 v[226:227], off
	s_waitcnt vmcnt(8)
	s_waitcnt lgkmcnt(0)
	s_barrier
	s_setprio 1
	s_waitcnt lgkmcnt(0)
	v_mfma_f32_16x16x32_bf16 v[126:129], v[140:143], v[190:193], v[126:129]
	v_mfma_f32_16x16x32_bf16 v[122:125], v[148:151], v[190:193], v[122:125]
	v_mfma_f32_16x16x32_bf16 v[110:113], v[140:143], v[198:201], v[110:113]
	v_mfma_f32_16x16x32_bf16 v[106:109], v[148:151], v[198:201], v[106:109]
	v_mfma_f32_16x16x32_bf16 v[94:97], v[140:143], v[206:209], v[94:97]
	v_mfma_f32_16x16x32_bf16 v[90:93], v[148:151], v[206:209], v[90:93]
	v_mfma_f32_16x16x32_bf16 v[78:81], v[140:143], v[214:217], v[78:81]
	v_mfma_f32_16x16x32_bf16 v[74:77], v[148:151], v[214:217], v[74:77]
	v_mfma_f32_16x16x32_bf16 v[126:129], v[144:147], v[194:197], v[126:129]
	v_mfma_f32_16x16x32_bf16 v[122:125], v[164:167], v[194:197], v[122:125]
	v_mfma_f32_16x16x32_bf16 v[110:113], v[144:147], v[202:205], v[110:113]
	v_mfma_f32_16x16x32_bf16 v[106:109], v[164:167], v[202:205], v[106:109]
	v_mfma_f32_16x16x32_bf16 v[94:97], v[144:147], v[210:213], v[94:97]
	v_mfma_f32_16x16x32_bf16 v[90:93], v[164:167], v[210:213], v[90:93]
	v_mfma_f32_16x16x32_bf16 v[78:81], v[144:147], v[218:221], v[78:81]
	v_mfma_f32_16x16x32_bf16 v[74:77], v[164:167], v[218:221], v[74:77]
	s_setprio 0
	s_setprio 1
	v_mfma_f32_16x16x32_bf16 v[118:121], v[168:171], v[190:193], v[118:121]
	v_mfma_f32_16x16x32_bf16 v[114:117], v[182:185], v[190:193], v[114:117]
	v_mfma_f32_16x16x32_bf16 v[102:105], v[168:171], v[198:201], v[102:105]
	v_mfma_f32_16x16x32_bf16 v[98:101], v[182:185], v[198:201], v[98:101]
	v_mfma_f32_16x16x32_bf16 v[86:89], v[168:171], v[206:209], v[86:89]
	v_mfma_f32_16x16x32_bf16 v[82:85], v[182:185], v[206:209], v[82:85]
	v_mfma_f32_16x16x32_bf16 v[70:73], v[168:171], v[214:217], v[70:73]
	v_mfma_f32_16x16x32_bf16 v[66:69], v[182:185], v[214:217], v[66:69]
	v_mfma_f32_16x16x32_bf16 v[118:121], v[178:181], v[194:197], v[118:121]
	v_mfma_f32_16x16x32_bf16 v[114:117], v[186:189], v[194:197], v[114:117]
	v_mfma_f32_16x16x32_bf16 v[102:105], v[178:181], v[202:205], v[102:105]
	v_mfma_f32_16x16x32_bf16 v[98:101], v[186:189], v[202:205], v[98:101]
	v_mfma_f32_16x16x32_bf16 v[86:89], v[178:181], v[210:213], v[86:89]
	v_mfma_f32_16x16x32_bf16 v[82:85], v[186:189], v[210:213], v[82:85]
	v_mfma_f32_16x16x32_bf16 v[70:73], v[178:181], v[218:221], v[70:73]
	v_mfma_f32_16x16x32_bf16 v[66:69], v[186:189], v[218:221], v[66:69]
	s_setprio 0
	s_barrier
	s_add_i32 s40, s62, s48
	v_lshl_add_u64 v[152:153], v[152:153], 0, s[20:21]
	s_mov_b32 m0, s40
	ds_read_b128 v[190:193], v158 offset:49152
	ds_read_b128 v[194:197], v158 offset:50176
	ds_read_b128 v[198:201], v158 offset:51200
	ds_read_b128 v[202:205], v158 offset:52224
	ds_read_b128 v[206:209], v158 offset:53248
	ds_read_b128 v[210:213], v158 offset:54272
	ds_read_b128 v[214:217], v158 offset:55296
	ds_read_b128 v[218:221], v158 offset:56320
	global_load_lds_dwordx4 v[152:153], off
	s_add_i32 m0, s40, 0x2000
	s_add_u32 s40, s44, 0x40080
	v_lshl_add_u64 v[152:153], v[172:173], 0, s[20:21]
	s_addc_u32 s41, s45, 0
	s_add_i32 s44, s63, s48
	global_load_lds_dwordx4 v[152:153], off
	s_mov_b32 m0, s44
	v_lshl_add_u64 v[152:153], s[40:41], 0, v[132:133]
	global_load_lds_dwordx4 v[152:153], off
	s_add_i32 m0, s44, 0x2000
	v_lshl_add_u64 v[152:153], s[40:41], 0, v[130:131]
	global_load_lds_dwordx4 v[152:153], off
	s_mov_b32 m0, s55
	v_lshl_add_u64 v[152:153], v[222:223], 0, s[20:21]
	global_load_lds_dwordx4 v[152:153], off
	s_mov_b32 m0, s56
	v_lshl_add_u64 v[152:153], v[224:225], 0, s[20:21]
	global_load_lds_dwordx4 v[152:153], off
	s_waitcnt vmcnt(8)
	s_waitcnt lgkmcnt(0)
	s_barrier
	s_setprio 1
	s_waitcnt lgkmcnt(0)
	v_mfma_f32_16x16x32_bf16 v[62:65], v[140:143], v[190:193], v[62:65]
	v_mfma_f32_16x16x32_bf16 v[58:61], v[148:151], v[190:193], v[58:61]
	v_mfma_f32_16x16x32_bf16 v[46:49], v[140:143], v[198:201], v[46:49]
	v_mfma_f32_16x16x32_bf16 v[42:45], v[148:151], v[198:201], v[42:45]
	v_mfma_f32_16x16x32_bf16 v[30:33], v[140:143], v[206:209], v[30:33]
	v_mfma_f32_16x16x32_bf16 v[26:29], v[148:151], v[206:209], v[26:29]
	v_mfma_f32_16x16x32_bf16 v[14:17], v[140:143], v[214:217], v[14:17]
	v_mfma_f32_16x16x32_bf16 v[10:13], v[148:151], v[214:217], v[10:13]
	v_mfma_f32_16x16x32_bf16 v[62:65], v[144:147], v[194:197], v[62:65]
	v_mfma_f32_16x16x32_bf16 v[58:61], v[164:167], v[194:197], v[58:61]
	v_mfma_f32_16x16x32_bf16 v[46:49], v[144:147], v[202:205], v[46:49]
	v_mfma_f32_16x16x32_bf16 v[42:45], v[164:167], v[202:205], v[42:45]
	v_mfma_f32_16x16x32_bf16 v[30:33], v[144:147], v[210:213], v[30:33]
	v_mfma_f32_16x16x32_bf16 v[26:29], v[164:167], v[210:213], v[26:29]
	v_mfma_f32_16x16x32_bf16 v[14:17], v[144:147], v[218:221], v[14:17]
	v_mfma_f32_16x16x32_bf16 v[10:13], v[164:167], v[218:221], v[10:13]
	s_setprio 0
	s_setprio 1
	v_mfma_f32_16x16x32_bf16 v[54:57], v[168:171], v[190:193], v[54:57]
	v_mfma_f32_16x16x32_bf16 v[50:53], v[182:185], v[190:193], v[50:53]
	v_mfma_f32_16x16x32_bf16 v[38:41], v[168:171], v[198:201], v[38:41]
	v_mfma_f32_16x16x32_bf16 v[34:37], v[182:185], v[198:201], v[34:37]
	v_mfma_f32_16x16x32_bf16 v[22:25], v[168:171], v[206:209], v[22:25]
	v_mfma_f32_16x16x32_bf16 v[18:21], v[182:185], v[206:209], v[18:21]
	v_mfma_f32_16x16x32_bf16 v[6:9], v[168:171], v[214:217], v[6:9]
	v_mfma_f32_16x16x32_bf16 v[2:5], v[182:185], v[214:217], v[2:5]
	v_mfma_f32_16x16x32_bf16 v[54:57], v[178:181], v[194:197], v[54:57]
	v_mfma_f32_16x16x32_bf16 v[50:53], v[186:189], v[194:197], v[50:53]
	v_mfma_f32_16x16x32_bf16 v[38:41], v[178:181], v[202:205], v[38:41]
	v_mfma_f32_16x16x32_bf16 v[34:37], v[186:189], v[202:205], v[34:37]
	v_mfma_f32_16x16x32_bf16 v[22:25], v[178:181], v[210:213], v[22:25]
	v_mfma_f32_16x16x32_bf16 v[18:21], v[186:189], v[210:213], v[18:21]
	v_mfma_f32_16x16x32_bf16 v[6:9], v[178:181], v[218:221], v[6:9]
	v_mfma_f32_16x16x32_bf16 v[2:5], v[186:189], v[218:221], v[2:5]
	s_setprio 0
	s_barrier
	s_add_i32 s61, s61, 2
	s_add_u32 s35, s35, 0x100
	s_addc_u32 s39, s39, 0
	s_cmp_gt_u32 s61, 13
	s_mov_b64 s[40:41], s[42:43]
	s_cbranch_scc0 .LBB0_405

.LBB0_1029:
	v_add_u32_e32 v179, s28, v1
	ds_read_b128 v[180:183], v179
	ds_read_b128 v[184:187], v179 offset:1024
	ds_read_b128 v[188:191], v179 offset:2048
	ds_read_b128 v[192:195], v179 offset:3072
	v_add_u32_e32 v179, s29, v1
	ds_read_b128 v[196:199], v179
	ds_read_b128 v[200:203], v179 offset:1024
	ds_read_b128 v[204:207], v179 offset:2048
	ds_read_b128 v[208:211], v179 offset:3072
	s_add_u32 s22, s20, 0xfff80080
	s_addc_u32 s23, s21, -1
	s_cmp_eq_u32 s46, 4
	s_cselect_b32 s25, s7, s23
	s_cselect_b32 s24, s6, s22
	s_cselect_b32 s23, s1, s45
	s_cselect_b32 s22, s0, s44
	s_mov_b32 m0, s30
	v_lshl_add_u64 v[244:245], s[20:21], 0, v[170:171]
	ds_read_b128 v[212:215], v178
	ds_read_b128 v[216:219], v178 offset:1024
	ds_read_b128 v[220:223], v178 offset:2048
	ds_read_b128 v[224:227], v178 offset:3072
	ds_read_b128 v[228:231], v178 offset:4096
	ds_read_b128 v[232:235], v178 offset:5120
	ds_read_b128 v[236:239], v178 offset:6144
	ds_read_b128 v[240:243], v178 offset:7168
	global_load_lds_dwordx4 v[244:245], off
	s_mov_b32 m0, s31
	v_lshl_add_u64 v[244:245], s[20:21], 0, v[172:173]
	global_load_lds_dwordx4 v[244:245], off
	s_waitcnt vmcnt(8)
	s_waitcnt lgkmcnt(0)
	s_barrier
	s_setprio 1
	s_waitcnt lgkmcnt(0)
	v_mfma_f32_16x16x32_bf16 v[126:129], v[180:183], v[212:215], v[126:129]
	v_mfma_f32_16x16x32_bf16 v[122:125], v[188:191], v[212:215], v[122:125]
	v_mfma_f32_16x16x32_bf16 v[118:121], v[180:183], v[220:223], v[118:121]
	v_mfma_f32_16x16x32_bf16 v[114:117], v[188:191], v[220:223], v[114:117]
	v_mfma_f32_16x16x32_bf16 v[110:113], v[180:183], v[228:231], v[110:113]
	v_mfma_f32_16x16x32_bf16 v[106:109], v[188:191], v[228:231], v[106:109]
	v_mfma_f32_16x16x32_bf16 v[102:105], v[180:183], v[236:239], v[102:105]
	v_mfma_f32_16x16x32_bf16 v[98:101], v[188:191], v[236:239], v[98:101]
	v_mfma_f32_16x16x32_bf16 v[126:129], v[184:187], v[216:219], v[126:129]
	v_mfma_f32_16x16x32_bf16 v[122:125], v[192:195], v[216:219], v[122:125]
	v_mfma_f32_16x16x32_bf16 v[118:121], v[184:187], v[224:227], v[118:121]
	v_mfma_f32_16x16x32_bf16 v[114:117], v[192:195], v[224:227], v[114:117]
	v_mfma_f32_16x16x32_bf16 v[110:113], v[184:187], v[232:235], v[110:113]
	v_mfma_f32_16x16x32_bf16 v[106:109], v[192:195], v[232:235], v[106:109]
	v_mfma_f32_16x16x32_bf16 v[102:105], v[184:187], v[240:243], v[102:105]
	v_mfma_f32_16x16x32_bf16 v[98:101], v[192:195], v[240:243], v[98:101]
	s_setprio 0
	s_setprio 1
	v_mfma_f32_16x16x32_bf16 v[94:97], v[196:199], v[212:215], v[94:97]
	v_mfma_f32_16x16x32_bf16 v[90:93], v[204:207], v[212:215], v[90:93]
	v_mfma_f32_16x16x32_bf16 v[86:89], v[196:199], v[220:223], v[86:89]
	v_mfma_f32_16x16x32_bf16 v[82:85], v[204:207], v[220:223], v[82:85]
	v_mfma_f32_16x16x32_bf16 v[78:81], v[196:199], v[228:231], v[78:81]
	v_mfma_f32_16x16x32_bf16 v[74:77], v[204:207], v[228:231], v[74:77]
	v_mfma_f32_16x16x32_bf16 v[70:73], v[196:199], v[236:239], v[70:73]
	v_mfma_f32_16x16x32_bf16 v[66:69], v[204:207], v[236:239], v[66:69]
	v_mfma_f32_16x16x32_bf16 v[94:97], v[200:203], v[216:219], v[94:97]
	v_mfma_f32_16x16x32_bf16 v[90:93], v[208:211], v[216:219], v[90:93]
	v_mfma_f32_16x16x32_bf16 v[86:89], v[200:203], v[224:227], v[86:89]
	v_mfma_f32_16x16x32_bf16 v[82:85], v[208:211], v[224:227], v[82:85]
	v_mfma_f32_16x16x32_bf16 v[78:81], v[200:203], v[232:235], v[78:81]
	v_mfma_f32_16x16x32_bf16 v[74:77], v[208:211], v[232:235], v[74:77]
	v_mfma_f32_16x16x32_bf16 v[70:73], v[200:203], v[240:243], v[70:73]
	v_mfma_f32_16x16x32_bf16 v[66:69], v[208:211], v[240:243], v[66:69]
	s_setprio 0
	s_barrier
	s_mov_b32 m0, s34
	v_lshl_add_u64 v[244:245], s[22:23], 0, v[132:133]
	s_add_u32 s48, s22, 0x80000
	ds_read_b128 v[212:215], v178 offset:16384
	ds_read_b128 v[216:219], v178 offset:17408
	ds_read_b128 v[220:223], v178 offset:18432
	ds_read_b128 v[224:227], v178 offset:19456
	ds_read_b128 v[228:231], v178 offset:20480
	ds_read_b128 v[232:235], v178 offset:21504
	ds_read_b128 v[236:239], v178 offset:22528
	ds_read_b128 v[240:243], v178 offset:23552
	global_load_lds_dwordx4 v[244:245], off
	v_lshl_add_u64 v[246:247], s[22:23], 0, v[136:137]
	s_mov_b32 m0, s35
	s_addc_u32 s49, s23, 0
	global_load_lds_dwordx4 v[246:247], off
	v_lshl_add_u64 v[248:249], s[48:49], 0, v[132:133]
	s_mov_b32 m0, s36
	v_lshl_add_u64 v[250:251], s[24:25], 0, v[134:135]
	global_load_lds_dwordx4 v[248:249], off
	s_mov_b32 m0, s37
	v_lshl_add_u64 v[248:249], s[48:49], 0, v[136:137]
	global_load_lds_dwordx4 v[248:249], off
	s_mov_b32 m0, s3
	v_lshl_add_u64 v[248:249], s[24:25], 0, v[130:131]
	global_load_lds_dwordx4 v[248:249], off
	s_mov_b32 m0, s14
	s_nop 0
	global_load_lds_dwordx4 v[250:251], off
	s_waitcnt vmcnt(8)
	s_waitcnt lgkmcnt(0)
	s_barrier
	s_setprio 1
	s_waitcnt lgkmcnt(0)
	v_mfma_f32_16x16x32_bf16 v[62:65], v[180:183], v[212:215], v[62:65]
	v_mfma_f32_16x16x32_bf16 v[58:61], v[188:191], v[212:215], v[58:61]
	v_mfma_f32_16x16x32_bf16 v[54:57], v[180:183], v[220:223], v[54:57]
	v_mfma_f32_16x16x32_bf16 v[50:53], v[188:191], v[220:223], v[50:53]
	v_mfma_f32_16x16x32_bf16 v[46:49], v[180:183], v[228:231], v[46:49]
	v_mfma_f32_16x16x32_bf16 v[42:45], v[188:191], v[228:231], v[42:45]
	v_mfma_f32_16x16x32_bf16 v[38:41], v[180:183], v[236:239], v[38:41]
	v_mfma_f32_16x16x32_bf16 v[34:37], v[188:191], v[236:239], v[34:37]
	v_mfma_f32_16x16x32_bf16 v[62:65], v[184:187], v[216:219], v[62:65]
	v_mfma_f32_16x16x32_bf16 v[58:61], v[192:195], v[216:219], v[58:61]
	v_mfma_f32_16x16x32_bf16 v[54:57], v[184:187], v[224:227], v[54:57]
	v_mfma_f32_16x16x32_bf16 v[50:53], v[192:195], v[224:227], v[50:53]
	v_mfma_f32_16x16x32_bf16 v[46:49], v[184:187], v[232:235], v[46:49]
	v_mfma_f32_16x16x32_bf16 v[42:45], v[192:195], v[232:235], v[42:45]
	v_mfma_f32_16x16x32_bf16 v[38:41], v[184:187], v[240:243], v[38:41]
	v_mfma_f32_16x16x32_bf16 v[34:37], v[192:195], v[240:243], v[34:37]
	s_setprio 0
	s_setprio 1
	v_mfma_f32_16x16x32_bf16 v[30:33], v[196:199], v[212:215], v[30:33]
	v_mfma_f32_16x16x32_bf16 v[26:29], v[204:207], v[212:215], v[26:29]
	v_mfma_f32_16x16x32_bf16 v[22:25], v[196:199], v[220:223], v[22:25]
	v_mfma_f32_16x16x32_bf16 v[18:21], v[204:207], v[220:223], v[18:21]
	v_mfma_f32_16x16x32_bf16 v[14:17], v[196:199], v[228:231], v[14:17]
	v_mfma_f32_16x16x32_bf16 v[10:13], v[204:207], v[228:231], v[10:13]
	v_mfma_f32_16x16x32_bf16 v[6:9], v[196:199], v[236:239], v[6:9]
	v_mfma_f32_16x16x32_bf16 v[2:5], v[204:207], v[236:239], v[2:5]
	v_mfma_f32_16x16x32_bf16 v[30:33], v[200:203], v[216:219], v[30:33]
	v_mfma_f32_16x16x32_bf16 v[26:29], v[208:211], v[216:219], v[26:29]
	v_mfma_f32_16x16x32_bf16 v[22:25], v[200:203], v[224:227], v[22:25]
	v_mfma_f32_16x16x32_bf16 v[18:21], v[208:211], v[224:227], v[18:21]
	v_mfma_f32_16x16x32_bf16 v[14:17], v[200:203], v[232:235], v[14:17]
	v_mfma_f32_16x16x32_bf16 v[10:13], v[208:211], v[232:235], v[10:13]
	v_mfma_f32_16x16x32_bf16 v[6:9], v[200:203], v[240:243], v[6:9]
	v_mfma_f32_16x16x32_bf16 v[2:5], v[208:211], v[240:243], v[2:5]
	s_setprio 0
	s_barrier
	v_add_u32_e32 v179, s38, v1
	ds_read_b128 v[180:183], v179
	ds_read_b128 v[184:187], v179 offset:1024
	ds_read_b128 v[188:191], v179 offset:2048
	ds_read_b128 v[192:195], v179 offset:3072
	v_add_u32_e32 v179, s39, v1
	ds_read_b128 v[196:199], v179
	ds_read_b128 v[200:203], v179 offset:1024
	ds_read_b128 v[204:207], v179 offset:2048
	ds_read_b128 v[208:211], v179 offset:3072
	s_add_u32 s24, s24, 0x80000
	s_addc_u32 s25, s25, 0
	s_mov_b32 m0, s15
	v_lshl_add_u64 v[252:253], s[24:25], 0, v[130:131]
	ds_read_b128 v[212:215], v178 offset:32768
	ds_read_b128 v[216:219], v178 offset:33792
	ds_read_b128 v[220:223], v178 offset:34816
	ds_read_b128 v[224:227], v178 offset:35840
	ds_read_b128 v[228:231], v178 offset:36864
	ds_read_b128 v[232:235], v178 offset:37888
	ds_read_b128 v[236:239], v178 offset:38912
	ds_read_b128 v[240:243], v178 offset:39936
	global_load_lds_dwordx4 v[252:253], off
	s_mov_b32 m0, s16
	v_lshl_add_u64 v[252:253], s[24:25], 0, v[134:135]
	global_load_lds_dwordx4 v[252:253], off
	s_waitcnt vmcnt(8)
	s_waitcnt lgkmcnt(0)
	s_barrier
	s_setprio 1
	s_waitcnt lgkmcnt(0)
	v_mfma_f32_16x16x32_bf16 v[126:129], v[180:183], v[212:215], v[126:129]
	v_mfma_f32_16x16x32_bf16 v[122:125], v[188:191], v[212:215], v[122:125]
	v_mfma_f32_16x16x32_bf16 v[118:121], v[180:183], v[220:223], v[118:121]
	v_mfma_f32_16x16x32_bf16 v[114:117], v[188:191], v[220:223], v[114:117]
	v_mfma_f32_16x16x32_bf16 v[110:113], v[180:183], v[228:231], v[110:113]
	v_mfma_f32_16x16x32_bf16 v[106:109], v[188:191], v[228:231], v[106:109]
	v_mfma_f32_16x16x32_bf16 v[102:105], v[180:183], v[236:239], v[102:105]
	v_mfma_f32_16x16x32_bf16 v[98:101], v[188:191], v[236:239], v[98:101]
	v_mfma_f32_16x16x32_bf16 v[126:129], v[184:187], v[216:219], v[126:129]
	v_mfma_f32_16x16x32_bf16 v[122:125], v[192:195], v[216:219], v[122:125]
	v_mfma_f32_16x16x32_bf16 v[118:121], v[184:187], v[224:227], v[118:121]
	v_mfma_f32_16x16x32_bf16 v[114:117], v[192:195], v[224:227], v[114:117]
	v_mfma_f32_16x16x32_bf16 v[110:113], v[184:187], v[232:235], v[110:113]
	v_mfma_f32_16x16x32_bf16 v[106:109], v[192:195], v[232:235], v[106:109]
	v_mfma_f32_16x16x32_bf16 v[102:105], v[184:187], v[240:243], v[102:105]
	v_mfma_f32_16x16x32_bf16 v[98:101], v[192:195], v[240:243], v[98:101]
	s_setprio 0
	s_setprio 1
	v_mfma_f32_16x16x32_bf16 v[94:97], v[196:199], v[212:215], v[94:97]
	v_mfma_f32_16x16x32_bf16 v[90:93], v[204:207], v[212:215], v[90:93]
	v_mfma_f32_16x16x32_bf16 v[86:89], v[196:199], v[220:223], v[86:89]
	v_mfma_f32_16x16x32_bf16 v[82:85], v[204:207], v[220:223], v[82:85]
	v_mfma_f32_16x16x32_bf16 v[78:81], v[196:199], v[228:231], v[78:81]
	v_mfma_f32_16x16x32_bf16 v[74:77], v[204:207], v[228:231], v[74:77]
	v_mfma_f32_16x16x32_bf16 v[70:73], v[196:199], v[236:239], v[70:73]
	v_mfma_f32_16x16x32_bf16 v[66:69], v[204:207], v[236:239], v[66:69]
	v_mfma_f32_16x16x32_bf16 v[94:97], v[200:203], v[216:219], v[94:97]
	v_mfma_f32_16x16x32_bf16 v[90:93], v[208:211], v[216:219], v[90:93]
	v_mfma_f32_16x16x32_bf16 v[86:89], v[200:203], v[224:227], v[86:89]
	v_mfma_f32_16x16x32_bf16 v[82:85], v[208:211], v[224:227], v[82:85]
	v_mfma_f32_16x16x32_bf16 v[78:81], v[200:203], v[232:235], v[78:81]
	v_mfma_f32_16x16x32_bf16 v[74:77], v[208:211], v[232:235], v[74:77]
	v_mfma_f32_16x16x32_bf16 v[70:73], v[200:203], v[240:243], v[70:73]
	v_mfma_f32_16x16x32_bf16 v[66:69], v[208:211], v[240:243], v[66:69]
	s_setprio 0
	s_barrier
	s_mov_b32 m0, s40
	v_lshl_add_u64 v[244:245], v[244:245], 0, s[8:9]
	s_add_u32 s22, s22, 0x80080
	ds_read_b128 v[212:215], v178 offset:49152
	ds_read_b128 v[216:219], v178 offset:50176
	ds_read_b128 v[220:223], v178 offset:51200
	ds_read_b128 v[224:227], v178 offset:52224
	ds_read_b128 v[228:231], v178 offset:53248
	ds_read_b128 v[232:235], v178 offset:54272
	ds_read_b128 v[236:239], v178 offset:55296
	ds_read_b128 v[240:243], v178 offset:56320
	global_load_lds_dwordx4 v[244:245], off
	v_lshl_add_u64 v[244:245], v[246:247], 0, s[8:9]
	s_mov_b32 m0, s41
	s_addc_u32 s23, s23, 0
	global_load_lds_dwordx4 v[244:245], off
	s_mov_b32 m0, s42
	v_lshl_add_u64 v[244:245], s[22:23], 0, v[132:133]
	global_load_lds_dwordx4 v[244:245], off
	s_mov_b32 m0, s43
	v_lshl_add_u64 v[244:245], s[22:23], 0, v[136:137]
	global_load_lds_dwordx4 v[244:245], off
	s_mov_b32 m0, s17
	v_lshl_add_u64 v[244:245], v[248:249], 0, s[8:9]
	global_load_lds_dwordx4 v[244:245], off
	s_mov_b32 m0, s26
	v_lshl_add_u64 v[244:245], v[250:251], 0, s[8:9]
	global_load_lds_dwordx4 v[244:245], off
	s_waitcnt vmcnt(8)
	s_waitcnt lgkmcnt(0)
	s_barrier
	s_setprio 1
	s_waitcnt lgkmcnt(0)
	v_mfma_f32_16x16x32_bf16 v[62:65], v[180:183], v[212:215], v[62:65]
	v_mfma_f32_16x16x32_bf16 v[58:61], v[188:191], v[212:215], v[58:61]
	v_mfma_f32_16x16x32_bf16 v[54:57], v[180:183], v[220:223], v[54:57]
	v_mfma_f32_16x16x32_bf16 v[50:53], v[188:191], v[220:223], v[50:53]
	v_mfma_f32_16x16x32_bf16 v[46:49], v[180:183], v[228:231], v[46:49]
	v_mfma_f32_16x16x32_bf16 v[42:45], v[188:191], v[228:231], v[42:45]
	v_mfma_f32_16x16x32_bf16 v[38:41], v[180:183], v[236:239], v[38:41]
	v_mfma_f32_16x16x32_bf16 v[34:37], v[188:191], v[236:239], v[34:37]
	v_mfma_f32_16x16x32_bf16 v[62:65], v[184:187], v[216:219], v[62:65]
	v_mfma_f32_16x16x32_bf16 v[58:61], v[192:195], v[216:219], v[58:61]
	v_mfma_f32_16x16x32_bf16 v[54:57], v[184:187], v[224:227], v[54:57]
	v_mfma_f32_16x16x32_bf16 v[50:53], v[192:195], v[224:227], v[50:53]
	v_mfma_f32_16x16x32_bf16 v[46:49], v[184:187], v[232:235], v[46:49]
	v_mfma_f32_16x16x32_bf16 v[42:45], v[192:195], v[232:235], v[42:45]
	v_mfma_f32_16x16x32_bf16 v[38:41], v[184:187], v[240:243], v[38:41]
	v_mfma_f32_16x16x32_bf16 v[34:37], v[192:195], v[240:243], v[34:37]
	s_setprio 0
	s_setprio 1
	v_mfma_f32_16x16x32_bf16 v[30:33], v[196:199], v[212:215], v[30:33]
	v_mfma_f32_16x16x32_bf16 v[26:29], v[204:207], v[212:215], v[26:29]
	v_mfma_f32_16x16x32_bf16 v[22:25], v[196:199], v[220:223], v[22:25]
	v_mfma_f32_16x16x32_bf16 v[18:21], v[204:207], v[220:223], v[18:21]
	v_mfma_f32_16x16x32_bf16 v[14:17], v[196:199], v[228:231], v[14:17]
	v_mfma_f32_16x16x32_bf16 v[10:13], v[204:207], v[228:231], v[10:13]
	v_mfma_f32_16x16x32_bf16 v[6:9], v[196:199], v[236:239], v[6:9]
	v_mfma_f32_16x16x32_bf16 v[2:5], v[204:207], v[236:239], v[2:5]
	v_mfma_f32_16x16x32_bf16 v[30:33], v[200:203], v[216:219], v[30:33]
	v_mfma_f32_16x16x32_bf16 v[26:29], v[208:211], v[216:219], v[26:29]
	v_mfma_f32_16x16x32_bf16 v[22:25], v[200:203], v[224:227], v[22:25]
	v_mfma_f32_16x16x32_bf16 v[18:21], v[208:211], v[224:227], v[18:21]
	v_mfma_f32_16x16x32_bf16 v[14:17], v[200:203], v[232:235], v[14:17]
	v_mfma_f32_16x16x32_bf16 v[10:13], v[208:211], v[232:235], v[10:13]
	v_mfma_f32_16x16x32_bf16 v[6:9], v[200:203], v[240:243], v[6:9]
	v_mfma_f32_16x16x32_bf16 v[2:5], v[208:211], v[240:243], v[2:5]
	s_setprio 0
	s_barrier
	s_add_i32 s46, s46, 2
	s_add_u32 s20, s20, 0x100
	s_addc_u32 s21, s21, 0
	s_add_u32 s44, s44, 0x100
	s_addc_u32 s45, s45, 0
	s_cmp_gt_u32 s46, 5
	s_cbranch_scc0 .LBB0_1029
	s_and_b64 vcc, exec, s[10:11]
	s_cbranch_vccnz .LBB0_1034
	s_mov_b64 s[20:21], -1
	s_and_b64 vcc, exec, s[18:19]
	s_cbranch_vccnz .LBB0_1035

.LBB0_1134:
	s_ashr_i32 s29, s28, 31
	s_lshl_b64 s[30:31], s[28:29], 19
	s_add_u32 s30, s3, s30
	s_addc_u32 s31, s14, s31
	s_and_b64 s[34:35], s[0:1], exec
	s_cselect_b32 s29, s31, s39
	s_cselect_b32 s57, s30, s38
	s_ashr_i32 s27, s26, 31
	s_lshl_b64 s[34:35], s[26:27], 19
	s_add_u32 s34, s15, s34
	s_addc_u32 s35, s16, s35
	s_and_b64 s[42:43], s[0:1], exec
	s_cselect_b32 s27, s35, s41
	s_cselect_b32 s58, s34, s40
	s_add_u32 s59, s40, 0x100
	s_addc_u32 s60, s41, 0
	s_mov_b32 s61, -2
	ds_read_b128 v[146:149], v156
	ds_read_b128 v[150:153], v156 offset:1024
	ds_read_b128 v[160:163], v156 offset:2048
	ds_read_b128 v[164:167], v156 offset:3072
	ds_read_b128 v[168:171], v157
	ds_read_b128 v[178:181], v157 offset:1024
	ds_read_b128 v[182:185], v157 offset:2048
	ds_read_b128 v[186:189], v157 offset:3072
	s_add_u32 s40, s38, 0x100
	s_addc_u32 s41, s39, 0
	s_cmp_eq_u32 s61, 12
	s_cselect_b32 s45, s29, s41
	s_cselect_b32 s44, s57, s40
	s_cselect_b32 s43, s27, s60
	s_cselect_b32 s42, s58, s59
	v_lshl_add_u64 v[172:173], s[38:39], 0, v[138:139]
	s_add_i32 m0, s37, 0xc000
	ds_read_b128 v[190:193], v158
	ds_read_b128 v[194:197], v158 offset:1024
	ds_read_b128 v[198:201], v158 offset:2048
	ds_read_b128 v[202:205], v158 offset:3072
	ds_read_b128 v[206:209], v158 offset:4096
	ds_read_b128 v[210:213], v158 offset:5120
	ds_read_b128 v[214:217], v158 offset:6144
	ds_read_b128 v[218:221], v158 offset:7168
	global_load_lds_dwordx4 v[172:173], off
	s_add_i32 m0, s37, 0xe000
	v_lshl_add_u64 v[172:173], s[38:39], 0, v[140:141]
	global_load_lds_dwordx4 v[172:173], off
	s_waitcnt vmcnt(8)
	s_waitcnt lgkmcnt(0)
	s_barrier
	s_setprio 1
	s_waitcnt lgkmcnt(0)
	v_mfma_f32_16x16x32_bf16 v[126:129], v[146:149], v[190:193], 0
	v_mfma_f32_16x16x32_bf16 v[122:125], v[160:163], v[190:193], 0
	v_mfma_f32_16x16x32_bf16 v[110:113], v[146:149], v[198:201], 0
	v_mfma_f32_16x16x32_bf16 v[106:109], v[160:163], v[198:201], 0
	v_mfma_f32_16x16x32_bf16 v[94:97], v[146:149], v[206:209], 0
	v_mfma_f32_16x16x32_bf16 v[90:93], v[160:163], v[206:209], 0
	v_mfma_f32_16x16x32_bf16 v[78:81], v[146:149], v[214:217], 0
	v_mfma_f32_16x16x32_bf16 v[74:77], v[160:163], v[214:217], 0
	v_mfma_f32_16x16x32_bf16 v[126:129], v[150:153], v[194:197], v[126:129]
	v_mfma_f32_16x16x32_bf16 v[122:125], v[164:167], v[194:197], v[122:125]
	v_mfma_f32_16x16x32_bf16 v[110:113], v[150:153], v[202:205], v[110:113]
	v_mfma_f32_16x16x32_bf16 v[106:109], v[164:167], v[202:205], v[106:109]
	v_mfma_f32_16x16x32_bf16 v[94:97], v[150:153], v[210:213], v[94:97]
	v_mfma_f32_16x16x32_bf16 v[90:93], v[164:167], v[210:213], v[90:93]
	v_mfma_f32_16x16x32_bf16 v[78:81], v[150:153], v[218:221], v[78:81]
	v_mfma_f32_16x16x32_bf16 v[74:77], v[164:167], v[218:221], v[74:77]
	s_setprio 0
	s_setprio 1
	v_mfma_f32_16x16x32_bf16 v[118:121], v[168:171], v[190:193], 0
	v_mfma_f32_16x16x32_bf16 v[114:117], v[182:185], v[190:193], 0
	v_mfma_f32_16x16x32_bf16 v[102:105], v[168:171], v[198:201], 0
	v_mfma_f32_16x16x32_bf16 v[98:101], v[182:185], v[198:201], 0
	v_mfma_f32_16x16x32_bf16 v[86:89], v[168:171], v[206:209], 0
	v_mfma_f32_16x16x32_bf16 v[82:85], v[182:185], v[206:209], 0
	v_mfma_f32_16x16x32_bf16 v[70:73], v[168:171], v[214:217], 0
	v_mfma_f32_16x16x32_bf16 v[66:69], v[182:185], v[214:217], 0
	v_mfma_f32_16x16x32_bf16 v[118:121], v[178:181], v[194:197], v[118:121]
	v_mfma_f32_16x16x32_bf16 v[114:117], v[186:189], v[194:197], v[114:117]
	v_mfma_f32_16x16x32_bf16 v[102:105], v[178:181], v[202:205], v[102:105]
	v_mfma_f32_16x16x32_bf16 v[98:101], v[186:189], v[202:205], v[98:101]
	v_mfma_f32_16x16x32_bf16 v[86:89], v[178:181], v[210:213], v[86:89]
	v_mfma_f32_16x16x32_bf16 v[82:85], v[186:189], v[210:213], v[82:85]
	v_mfma_f32_16x16x32_bf16 v[70:73], v[178:181], v[218:221], v[70:73]
	v_mfma_f32_16x16x32_bf16 v[66:69], v[186:189], v[218:221], v[66:69]
	s_setprio 0
	s_barrier
	s_add_i32 s38, s54, s46
	v_lshl_add_u64 v[172:173], s[42:43], 0, v[132:133]
	s_mov_b32 m0, s38
	ds_read_b128 v[190:193], v158 offset:16384
	ds_read_b128 v[194:197], v158 offset:17408
	ds_read_b128 v[198:201], v158 offset:18432
	ds_read_b128 v[202:205], v158 offset:19456
	ds_read_b128 v[206:209], v158 offset:20480
	ds_read_b128 v[210:213], v158 offset:21504
	ds_read_b128 v[214:217], v158 offset:22528
	ds_read_b128 v[218:221], v158 offset:23552
	global_load_lds_dwordx4 v[172:173], off
	s_add_i32 m0, s38, 0x2000
	s_add_u32 s38, s42, 0x40000
	v_lshl_add_u64 v[222:223], s[42:43], 0, v[136:137]
	s_addc_u32 s39, s43, 0
	s_add_i32 s62, s55, s46
	global_load_lds_dwordx4 v[222:223], off
	v_lshl_add_u64 v[224:225], s[38:39], 0, v[132:133]
	s_mov_b32 m0, s62
	v_lshl_add_u64 v[226:227], s[44:45], 0, v[134:135]
	global_load_lds_dwordx4 v[224:225], off
	s_add_i32 m0, s62, 0x2000
	v_lshl_add_u64 v[224:225], s[38:39], 0, v[136:137]
	global_load_lds_dwordx4 v[224:225], off
	s_mov_b32 m0, s37
	v_lshl_add_u64 v[224:225], s[44:45], 0, v[130:131]
	global_load_lds_dwordx4 v[224:225], off
	s_mov_b32 m0, s47
	s_nop 0
	global_load_lds_dwordx4 v[226:227], off
	s_waitcnt vmcnt(8)
	s_waitcnt lgkmcnt(0)
	s_barrier
	s_setprio 1
	s_waitcnt lgkmcnt(0)
	v_mfma_f32_16x16x32_bf16 v[62:65], v[146:149], v[190:193], 0
	v_mfma_f32_16x16x32_bf16 v[58:61], v[160:163], v[190:193], 0
	v_mfma_f32_16x16x32_bf16 v[46:49], v[146:149], v[198:201], 0
	v_mfma_f32_16x16x32_bf16 v[42:45], v[160:163], v[198:201], 0
	v_mfma_f32_16x16x32_bf16 v[30:33], v[146:149], v[206:209], 0
	v_mfma_f32_16x16x32_bf16 v[26:29], v[160:163], v[206:209], 0
	v_mfma_f32_16x16x32_bf16 v[14:17], v[146:149], v[214:217], 0
	v_mfma_f32_16x16x32_bf16 v[10:13], v[160:163], v[214:217], 0
	v_mfma_f32_16x16x32_bf16 v[62:65], v[150:153], v[194:197], v[62:65]
	v_mfma_f32_16x16x32_bf16 v[58:61], v[164:167], v[194:197], v[58:61]
	v_mfma_f32_16x16x32_bf16 v[46:49], v[150:153], v[202:205], v[46:49]
	v_mfma_f32_16x16x32_bf16 v[42:45], v[164:167], v[202:205], v[42:45]
	v_mfma_f32_16x16x32_bf16 v[30:33], v[150:153], v[210:213], v[30:33]
	v_mfma_f32_16x16x32_bf16 v[26:29], v[164:167], v[210:213], v[26:29]
	v_mfma_f32_16x16x32_bf16 v[14:17], v[150:153], v[218:221], v[14:17]
	v_mfma_f32_16x16x32_bf16 v[10:13], v[164:167], v[218:221], v[10:13]
	s_setprio 0
	s_setprio 1
	v_mfma_f32_16x16x32_bf16 v[54:57], v[168:171], v[190:193], 0
	v_mfma_f32_16x16x32_bf16 v[50:53], v[182:185], v[190:193], 0
	v_mfma_f32_16x16x32_bf16 v[38:41], v[168:171], v[198:201], 0
	v_mfma_f32_16x16x32_bf16 v[34:37], v[182:185], v[198:201], 0
	v_mfma_f32_16x16x32_bf16 v[22:25], v[168:171], v[206:209], 0
	v_mfma_f32_16x16x32_bf16 v[18:21], v[182:185], v[206:209], 0
	v_mfma_f32_16x16x32_bf16 v[6:9], v[168:171], v[214:217], 0
	v_mfma_f32_16x16x32_bf16 v[2:5], v[182:185], v[214:217], 0
	v_mfma_f32_16x16x32_bf16 v[54:57], v[178:181], v[194:197], v[54:57]
	v_mfma_f32_16x16x32_bf16 v[50:53], v[186:189], v[194:197], v[50:53]
	v_mfma_f32_16x16x32_bf16 v[38:41], v[178:181], v[202:205], v[38:41]
	v_mfma_f32_16x16x32_bf16 v[34:37], v[186:189], v[202:205], v[34:37]
	v_mfma_f32_16x16x32_bf16 v[22:25], v[178:181], v[210:213], v[22:25]
	v_mfma_f32_16x16x32_bf16 v[18:21], v[186:189], v[210:213], v[18:21]
	v_mfma_f32_16x16x32_bf16 v[6:9], v[178:181], v[218:221], v[6:9]
	v_mfma_f32_16x16x32_bf16 v[2:5], v[186:189], v[218:221], v[2:5]
	s_setprio 0
	s_barrier
	s_add_i32 s62, 0, 0x18000
	v_add_u32_e32 v159, s62, v154
	s_add_i32 s63, 0, 0x1c000
	ds_read_b128 v[146:149], v159
	ds_read_b128 v[150:153], v159 offset:1024
	ds_read_b128 v[160:163], v159 offset:2048
	ds_read_b128 v[164:167], v159 offset:3072
	v_add_u32_e32 v159, s63, v154
	ds_read_b128 v[168:171], v159
	ds_read_b128 v[178:181], v159 offset:1024
	ds_read_b128 v[182:185], v159 offset:2048
	ds_read_b128 v[186:189], v159 offset:3072
	s_add_u32 s38, s44, 0x40000
	s_addc_u32 s39, s45, 0
	s_mov_b32 m0, s48
	v_lshl_add_u64 v[228:229], s[38:39], 0, v[130:131]
	ds_read_b128 v[190:193], v158 offset:32768
	ds_read_b128 v[194:197], v158 offset:33792
	ds_read_b128 v[198:201], v158 offset:34816
	ds_read_b128 v[202:205], v158 offset:35840
	ds_read_b128 v[206:209], v158 offset:36864
	ds_read_b128 v[210:213], v158 offset:37888
	ds_read_b128 v[214:217], v158 offset:38912
	ds_read_b128 v[218:221], v158 offset:39936
	global_load_lds_dwordx4 v[228:229], off
	s_mov_b32 m0, s49
	v_lshl_add_u64 v[228:229], s[38:39], 0, v[134:135]
	global_load_lds_dwordx4 v[228:229], off
	s_waitcnt vmcnt(8)
	s_waitcnt lgkmcnt(0)
	s_barrier
	s_setprio 1
	s_waitcnt lgkmcnt(0)
	v_mfma_f32_16x16x32_bf16 v[126:129], v[146:149], v[190:193], v[126:129]
	v_mfma_f32_16x16x32_bf16 v[122:125], v[160:163], v[190:193], v[122:125]
	v_mfma_f32_16x16x32_bf16 v[110:113], v[146:149], v[198:201], v[110:113]
	v_mfma_f32_16x16x32_bf16 v[106:109], v[160:163], v[198:201], v[106:109]
	v_mfma_f32_16x16x32_bf16 v[94:97], v[146:149], v[206:209], v[94:97]
	v_mfma_f32_16x16x32_bf16 v[90:93], v[160:163], v[206:209], v[90:93]
	v_mfma_f32_16x16x32_bf16 v[78:81], v[146:149], v[214:217], v[78:81]
	v_mfma_f32_16x16x32_bf16 v[74:77], v[160:163], v[214:217], v[74:77]
	v_mfma_f32_16x16x32_bf16 v[126:129], v[150:153], v[194:197], v[126:129]
	v_mfma_f32_16x16x32_bf16 v[122:125], v[164:167], v[194:197], v[122:125]
	v_mfma_f32_16x16x32_bf16 v[110:113], v[150:153], v[202:205], v[110:113]
	v_mfma_f32_16x16x32_bf16 v[106:109], v[164:167], v[202:205], v[106:109]
	v_mfma_f32_16x16x32_bf16 v[94:97], v[150:153], v[210:213], v[94:97]
	v_mfma_f32_16x16x32_bf16 v[90:93], v[164:167], v[210:213], v[90:93]
	v_mfma_f32_16x16x32_bf16 v[78:81], v[150:153], v[218:221], v[78:81]
	v_mfma_f32_16x16x32_bf16 v[74:77], v[164:167], v[218:221], v[74:77]
	s_setprio 0
	s_setprio 1
	v_mfma_f32_16x16x32_bf16 v[118:121], v[168:171], v[190:193], v[118:121]
	v_mfma_f32_16x16x32_bf16 v[114:117], v[182:185], v[190:193], v[114:117]
	v_mfma_f32_16x16x32_bf16 v[102:105], v[168:171], v[198:201], v[102:105]
	v_mfma_f32_16x16x32_bf16 v[98:101], v[182:185], v[198:201], v[98:101]
	v_mfma_f32_16x16x32_bf16 v[86:89], v[168:171], v[206:209], v[86:89]
	v_mfma_f32_16x16x32_bf16 v[82:85], v[182:185], v[206:209], v[82:85]
	v_mfma_f32_16x16x32_bf16 v[70:73], v[168:171], v[214:217], v[70:73]
	v_mfma_f32_16x16x32_bf16 v[66:69], v[182:185], v[214:217], v[66:69]
	v_mfma_f32_16x16x32_bf16 v[118:121], v[178:181], v[194:197], v[118:121]
	v_mfma_f32_16x16x32_bf16 v[114:117], v[186:189], v[194:197], v[114:117]
	v_mfma_f32_16x16x32_bf16 v[102:105], v[178:181], v[202:205], v[102:105]
	v_mfma_f32_16x16x32_bf16 v[98:101], v[186:189], v[202:205], v[98:101]
	v_mfma_f32_16x16x32_bf16 v[86:89], v[178:181], v[210:213], v[86:89]
	v_mfma_f32_16x16x32_bf16 v[82:85], v[186:189], v[210:213], v[82:85]
	v_mfma_f32_16x16x32_bf16 v[70:73], v[178:181], v[218:221], v[70:73]
	v_mfma_f32_16x16x32_bf16 v[66:69], v[186:189], v[218:221], v[66:69]
	s_setprio 0
	s_barrier
	s_add_i32 s38, s62, s46
	v_lshl_add_u64 v[172:173], v[172:173], 0, s[12:13]
	s_mov_b32 m0, s38
	ds_read_b128 v[190:193], v158 offset:49152
	ds_read_b128 v[194:197], v158 offset:50176
	ds_read_b128 v[198:201], v158 offset:51200
	ds_read_b128 v[202:205], v158 offset:52224
	ds_read_b128 v[206:209], v158 offset:53248
	ds_read_b128 v[210:213], v158 offset:54272
	ds_read_b128 v[214:217], v158 offset:55296
	ds_read_b128 v[218:221], v158 offset:56320
	global_load_lds_dwordx4 v[172:173], off
	s_add_i32 m0, s38, 0x2000
	s_add_u32 s38, s42, 0x40080
	v_lshl_add_u64 v[172:173], v[222:223], 0, s[12:13]
	s_addc_u32 s39, s43, 0
	s_add_i32 s42, s63, s46
	global_load_lds_dwordx4 v[172:173], off
	s_mov_b32 m0, s42
	v_lshl_add_u64 v[172:173], s[38:39], 0, v[132:133]
	global_load_lds_dwordx4 v[172:173], off
	s_add_i32 m0, s42, 0x2000
	v_lshl_add_u64 v[172:173], s[38:39], 0, v[136:137]
	global_load_lds_dwordx4 v[172:173], off
	s_mov_b32 m0, s51
	v_lshl_add_u64 v[172:173], v[224:225], 0, s[12:13]
	global_load_lds_dwordx4 v[172:173], off
	s_mov_b32 m0, s52
	v_lshl_add_u64 v[172:173], v[226:227], 0, s[12:13]
	global_load_lds_dwordx4 v[172:173], off
	s_waitcnt vmcnt(8)
	s_waitcnt lgkmcnt(0)
	s_barrier
	s_setprio 1
	s_waitcnt lgkmcnt(0)
	v_mfma_f32_16x16x32_bf16 v[62:65], v[146:149], v[190:193], v[62:65]
	v_mfma_f32_16x16x32_bf16 v[58:61], v[160:163], v[190:193], v[58:61]
	v_mfma_f32_16x16x32_bf16 v[46:49], v[146:149], v[198:201], v[46:49]
	v_mfma_f32_16x16x32_bf16 v[42:45], v[160:163], v[198:201], v[42:45]
	v_mfma_f32_16x16x32_bf16 v[30:33], v[146:149], v[206:209], v[30:33]
	v_mfma_f32_16x16x32_bf16 v[26:29], v[160:163], v[206:209], v[26:29]
	v_mfma_f32_16x16x32_bf16 v[14:17], v[146:149], v[214:217], v[14:17]
	v_mfma_f32_16x16x32_bf16 v[10:13], v[160:163], v[214:217], v[10:13]
	v_mfma_f32_16x16x32_bf16 v[62:65], v[150:153], v[194:197], v[62:65]
	v_mfma_f32_16x16x32_bf16 v[58:61], v[164:167], v[194:197], v[58:61]
	v_mfma_f32_16x16x32_bf16 v[46:49], v[150:153], v[202:205], v[46:49]
	v_mfma_f32_16x16x32_bf16 v[42:45], v[164:167], v[202:205], v[42:45]
	v_mfma_f32_16x16x32_bf16 v[30:33], v[150:153], v[210:213], v[30:33]
	v_mfma_f32_16x16x32_bf16 v[26:29], v[164:167], v[210:213], v[26:29]
	v_mfma_f32_16x16x32_bf16 v[14:17], v[150:153], v[218:221], v[14:17]
	v_mfma_f32_16x16x32_bf16 v[10:13], v[164:167], v[218:221], v[10:13]
	s_setprio 0
	s_setprio 1
	v_mfma_f32_16x16x32_bf16 v[54:57], v[168:171], v[190:193], v[54:57]
	v_mfma_f32_16x16x32_bf16 v[50:53], v[182:185], v[190:193], v[50:53]
	v_mfma_f32_16x16x32_bf16 v[38:41], v[168:171], v[198:201], v[38:41]
	v_mfma_f32_16x16x32_bf16 v[34:37], v[182:185], v[198:201], v[34:37]
	v_mfma_f32_16x16x32_bf16 v[22:25], v[168:171], v[206:209], v[22:25]
	v_mfma_f32_16x16x32_bf16 v[18:21], v[182:185], v[206:209], v[18:21]
	v_mfma_f32_16x16x32_bf16 v[6:9], v[168:171], v[214:217], v[6:9]
	v_mfma_f32_16x16x32_bf16 v[2:5], v[182:185], v[214:217], v[2:5]
	v_mfma_f32_16x16x32_bf16 v[54:57], v[178:181], v[194:197], v[54:57]
	v_mfma_f32_16x16x32_bf16 v[50:53], v[186:189], v[194:197], v[50:53]
	v_mfma_f32_16x16x32_bf16 v[38:41], v[178:181], v[202:205], v[38:41]
	v_mfma_f32_16x16x32_bf16 v[34:37], v[186:189], v[202:205], v[34:37]
	v_mfma_f32_16x16x32_bf16 v[22:25], v[178:181], v[210:213], v[22:25]
	v_mfma_f32_16x16x32_bf16 v[18:21], v[186:189], v[210:213], v[18:21]
	v_mfma_f32_16x16x32_bf16 v[6:9], v[178:181], v[218:221], v[6:9]
	v_mfma_f32_16x16x32_bf16 v[2:5], v[186:189], v[218:221], v[2:5]
	s_setprio 0
	s_barrier
	s_add_i32 s61, s61, 2
	s_add_u32 s59, s59, 0x100
	s_addc_u32 s60, s60, 0
	s_cmp_gt_u32 s61, 13
	s_mov_b64 s[38:39], s[40:41]
	s_cbranch_scc0 .LBB0_1135
	s_branch .Lpeel_exit_1135
.LBB0_1135:
	ds_read_b128 v[146:149], v156
	ds_read_b128 v[150:153], v156 offset:1024
	ds_read_b128 v[160:163], v156 offset:2048
	ds_read_b128 v[164:167], v156 offset:3072
	ds_read_b128 v[168:171], v157
	ds_read_b128 v[178:181], v157 offset:1024
	ds_read_b128 v[182:185], v157 offset:2048
	ds_read_b128 v[186:189], v157 offset:3072
	s_add_u32 s40, s38, 0x100
	s_addc_u32 s41, s39, 0
	s_cmp_eq_u32 s61, 12
	s_cselect_b32 s45, s29, s41
	s_cselect_b32 s44, s57, s40
	s_cselect_b32 s43, s27, s60
	s_cselect_b32 s42, s58, s59
	v_lshl_add_u64 v[172:173], s[38:39], 0, v[138:139]
	s_add_i32 m0, s37, 0xc000
	ds_read_b128 v[190:193], v158
	ds_read_b128 v[194:197], v158 offset:1024
	ds_read_b128 v[198:201], v158 offset:2048
	ds_read_b128 v[202:205], v158 offset:3072
	ds_read_b128 v[206:209], v158 offset:4096
	ds_read_b128 v[210:213], v158 offset:5120
	ds_read_b128 v[214:217], v158 offset:6144
	ds_read_b128 v[218:221], v158 offset:7168
	global_load_lds_dwordx4 v[172:173], off
	s_add_i32 m0, s37, 0xe000
	v_lshl_add_u64 v[172:173], s[38:39], 0, v[140:141]
	global_load_lds_dwordx4 v[172:173], off
	s_waitcnt vmcnt(8)
	s_waitcnt lgkmcnt(0)
	s_barrier
	s_setprio 1
	s_waitcnt lgkmcnt(0)
	v_mfma_f32_16x16x32_bf16 v[126:129], v[146:149], v[190:193], v[126:129]
	v_mfma_f32_16x16x32_bf16 v[122:125], v[160:163], v[190:193], v[122:125]
	v_mfma_f32_16x16x32_bf16 v[110:113], v[146:149], v[198:201], v[110:113]
	v_mfma_f32_16x16x32_bf16 v[106:109], v[160:163], v[198:201], v[106:109]
	v_mfma_f32_16x16x32_bf16 v[94:97], v[146:149], v[206:209], v[94:97]
	v_mfma_f32_16x16x32_bf16 v[90:93], v[160:163], v[206:209], v[90:93]
	v_mfma_f32_16x16x32_bf16 v[78:81], v[146:149], v[214:217], v[78:81]
	v_mfma_f32_16x16x32_bf16 v[74:77], v[160:163], v[214:217], v[74:77]
	v_mfma_f32_16x16x32_bf16 v[126:129], v[150:153], v[194:197], v[126:129]
	v_mfma_f32_16x16x32_bf16 v[122:125], v[164:167], v[194:197], v[122:125]
	v_mfma_f32_16x16x32_bf16 v[110:113], v[150:153], v[202:205], v[110:113]
	v_mfma_f32_16x16x32_bf16 v[106:109], v[164:167], v[202:205], v[106:109]
	v_mfma_f32_16x16x32_bf16 v[94:97], v[150:153], v[210:213], v[94:97]
	v_mfma_f32_16x16x32_bf16 v[90:93], v[164:167], v[210:213], v[90:93]
	v_mfma_f32_16x16x32_bf16 v[78:81], v[150:153], v[218:221], v[78:81]
	v_mfma_f32_16x16x32_bf16 v[74:77], v[164:167], v[218:221], v[74:77]
	s_setprio 0
	s_setprio 1
	v_mfma_f32_16x16x32_bf16 v[118:121], v[168:171], v[190:193], v[118:121]
	v_mfma_f32_16x16x32_bf16 v[114:117], v[182:185], v[190:193], v[114:117]
	v_mfma_f32_16x16x32_bf16 v[102:105], v[168:171], v[198:201], v[102:105]
	v_mfma_f32_16x16x32_bf16 v[98:101], v[182:185], v[198:201], v[98:101]
	v_mfma_f32_16x16x32_bf16 v[86:89], v[168:171], v[206:209], v[86:89]
	v_mfma_f32_16x16x32_bf16 v[82:85], v[182:185], v[206:209], v[82:85]
	v_mfma_f32_16x16x32_bf16 v[70:73], v[168:171], v[214:217], v[70:73]
	v_mfma_f32_16x16x32_bf16 v[66:69], v[182:185], v[214:217], v[66:69]
	v_mfma_f32_16x16x32_bf16 v[118:121], v[178:181], v[194:197], v[118:121]
	v_mfma_f32_16x16x32_bf16 v[114:117], v[186:189], v[194:197], v[114:117]
	v_mfma_f32_16x16x32_bf16 v[102:105], v[178:181], v[202:205], v[102:105]
	v_mfma_f32_16x16x32_bf16 v[98:101], v[186:189], v[202:205], v[98:101]
	v_mfma_f32_16x16x32_bf16 v[86:89], v[178:181], v[210:213], v[86:89]
	v_mfma_f32_16x16x32_bf16 v[82:85], v[186:189], v[210:213], v[82:85]
	v_mfma_f32_16x16x32_bf16 v[70:73], v[178:181], v[218:221], v[70:73]
	v_mfma_f32_16x16x32_bf16 v[66:69], v[186:189], v[218:221], v[66:69]
	s_setprio 0
	s_barrier
	s_add_i32 s38, s54, s46
	v_lshl_add_u64 v[172:173], s[42:43], 0, v[132:133]
	s_mov_b32 m0, s38
	ds_read_b128 v[190:193], v158 offset:16384
	ds_read_b128 v[194:197], v158 offset:17408
	ds_read_b128 v[198:201], v158 offset:18432
	ds_read_b128 v[202:205], v158 offset:19456
	ds_read_b128 v[206:209], v158 offset:20480
	ds_read_b128 v[210:213], v158 offset:21504
	ds_read_b128 v[214:217], v158 offset:22528
	ds_read_b128 v[218:221], v158 offset:23552
	global_load_lds_dwordx4 v[172:173], off
	s_add_i32 m0, s38, 0x2000
	s_add_u32 s38, s42, 0x40000
	v_lshl_add_u64 v[222:223], s[42:43], 0, v[136:137]
	s_addc_u32 s39, s43, 0
	s_add_i32 s62, s55, s46
	global_load_lds_dwordx4 v[222:223], off
	v_lshl_add_u64 v[224:225], s[38:39], 0, v[132:133]
	s_mov_b32 m0, s62
	v_lshl_add_u64 v[226:227], s[44:45], 0, v[134:135]
	global_load_lds_dwordx4 v[224:225], off
	s_add_i32 m0, s62, 0x2000
	v_lshl_add_u64 v[224:225], s[38:39], 0, v[136:137]
	global_load_lds_dwordx4 v[224:225], off
	s_mov_b32 m0, s37
	v_lshl_add_u64 v[224:225], s[44:45], 0, v[130:131]
	global_load_lds_dwordx4 v[224:225], off
	s_mov_b32 m0, s47
	s_nop 0
	global_load_lds_dwordx4 v[226:227], off
	s_waitcnt vmcnt(8)
	s_waitcnt lgkmcnt(0)
	s_barrier
	s_setprio 1
	s_waitcnt lgkmcnt(0)
	v_mfma_f32_16x16x32_bf16 v[62:65], v[146:149], v[190:193], v[62:65]
	v_mfma_f32_16x16x32_bf16 v[58:61], v[160:163], v[190:193], v[58:61]
	v_mfma_f32_16x16x32_bf16 v[46:49], v[146:149], v[198:201], v[46:49]
	v_mfma_f32_16x16x32_bf16 v[42:45], v[160:163], v[198:201], v[42:45]
	v_mfma_f32_16x16x32_bf16 v[30:33], v[146:149], v[206:209], v[30:33]
	v_mfma_f32_16x16x32_bf16 v[26:29], v[160:163], v[206:209], v[26:29]
	v_mfma_f32_16x16x32_bf16 v[14:17], v[146:149], v[214:217], v[14:17]
	v_mfma_f32_16x16x32_bf16 v[10:13], v[160:163], v[214:217], v[10:13]
	v_mfma_f32_16x16x32_bf16 v[62:65], v[150:153], v[194:197], v[62:65]
	v_mfma_f32_16x16x32_bf16 v[58:61], v[164:167], v[194:197], v[58:61]
	v_mfma_f32_16x16x32_bf16 v[46:49], v[150:153], v[202:205], v[46:49]
	v_mfma_f32_16x16x32_bf16 v[42:45], v[164:167], v[202:205], v[42:45]
	v_mfma_f32_16x16x32_bf16 v[30:33], v[150:153], v[210:213], v[30:33]
	v_mfma_f32_16x16x32_bf16 v[26:29], v[164:167], v[210:213], v[26:29]
	v_mfma_f32_16x16x32_bf16 v[14:17], v[150:153], v[218:221], v[14:17]
	v_mfma_f32_16x16x32_bf16 v[10:13], v[164:167], v[218:221], v[10:13]
	s_setprio 0
	s_setprio 1
	v_mfma_f32_16x16x32_bf16 v[54:57], v[168:171], v[190:193], v[54:57]
	v_mfma_f32_16x16x32_bf16 v[50:53], v[182:185], v[190:193], v[50:53]
	v_mfma_f32_16x16x32_bf16 v[38:41], v[168:171], v[198:201], v[38:41]
	v_mfma_f32_16x16x32_bf16 v[34:37], v[182:185], v[198:201], v[34:37]
	v_mfma_f32_16x16x32_bf16 v[22:25], v[168:171], v[206:209], v[22:25]
	v_mfma_f32_16x16x32_bf16 v[18:21], v[182:185], v[206:209], v[18:21]
	v_mfma_f32_16x16x32_bf16 v[6:9], v[168:171], v[214:217], v[6:9]
	v_mfma_f32_16x16x32_bf16 v[2:5], v[182:185], v[214:217], v[2:5]
	v_mfma_f32_16x16x32_bf16 v[54:57], v[178:181], v[194:197], v[54:57]
	v_mfma_f32_16x16x32_bf16 v[50:53], v[186:189], v[194:197], v[50:53]
	v_mfma_f32_16x16x32_bf16 v[38:41], v[178:181], v[202:205], v[38:41]
	v_mfma_f32_16x16x32_bf16 v[34:37], v[186:189], v[202:205], v[34:37]
	v_mfma_f32_16x16x32_bf16 v[22:25], v[178:181], v[210:213], v[22:25]
	v_mfma_f32_16x16x32_bf16 v[18:21], v[186:189], v[210:213], v[18:21]
	v_mfma_f32_16x16x32_bf16 v[6:9], v[178:181], v[218:221], v[6:9]
	v_mfma_f32_16x16x32_bf16 v[2:5], v[186:189], v[218:221], v[2:5]
	s_setprio 0
	s_barrier
	s_add_i32 s62, 0, 0x18000
	v_add_u32_e32 v159, s62, v154
	s_add_i32 s63, 0, 0x1c000
	ds_read_b128 v[146:149], v159
	ds_read_b128 v[150:153], v159 offset:1024
	ds_read_b128 v[160:163], v159 offset:2048
	ds_read_b128 v[164:167], v159 offset:3072
	v_add_u32_e32 v159, s63, v154
	ds_read_b128 v[168:171], v159
	ds_read_b128 v[178:181], v159 offset:1024
	ds_read_b128 v[182:185], v159 offset:2048
	ds_read_b128 v[186:189], v159 offset:3072
	s_add_u32 s38, s44, 0x40000
	s_addc_u32 s39, s45, 0
	s_mov_b32 m0, s48
	v_lshl_add_u64 v[228:229], s[38:39], 0, v[130:131]
	ds_read_b128 v[190:193], v158 offset:32768
	ds_read_b128 v[194:197], v158 offset:33792
	ds_read_b128 v[198:201], v158 offset:34816
	ds_read_b128 v[202:205], v158 offset:35840
	ds_read_b128 v[206:209], v158 offset:36864
	ds_read_b128 v[210:213], v158 offset:37888
	ds_read_b128 v[214:217], v158 offset:38912
	ds_read_b128 v[218:221], v158 offset:39936
	global_load_lds_dwordx4 v[228:229], off
	s_mov_b32 m0, s49
	v_lshl_add_u64 v[228:229], s[38:39], 0, v[134:135]
	global_load_lds_dwordx4 v[228:229], off
	s_waitcnt vmcnt(8)
	s_waitcnt lgkmcnt(0)
	s_barrier
	s_setprio 1
	s_waitcnt lgkmcnt(0)
	v_mfma_f32_16x16x32_bf16 v[126:129], v[146:149], v[190:193], v[126:129]
	v_mfma_f32_16x16x32_bf16 v[122:125], v[160:163], v[190:193], v[122:125]
	v_mfma_f32_16x16x32_bf16 v[110:113], v[146:149], v[198:201], v[110:113]
	v_mfma_f32_16x16x32_bf16 v[106:109], v[160:163], v[198:201], v[106:109]
	v_mfma_f32_16x16x32_bf16 v[94:97], v[146:149], v[206:209], v[94:97]
	v_mfma_f32_16x16x32_bf16 v[90:93], v[160:163], v[206:209], v[90:93]
	v_mfma_f32_16x16x32_bf16 v[78:81], v[146:149], v[214:217], v[78:81]
	v_mfma_f32_16x16x32_bf16 v[74:77], v[160:163], v[214:217], v[74:77]
	v_mfma_f32_16x16x32_bf16 v[126:129], v[150:153], v[194:197], v[126:129]
	v_mfma_f32_16x16x32_bf16 v[122:125], v[164:167], v[194:197], v[122:125]
	v_mfma_f32_16x16x32_bf16 v[110:113], v[150:153], v[202:205], v[110:113]
	v_mfma_f32_16x16x32_bf16 v[106:109], v[164:167], v[202:205], v[106:109]
	v_mfma_f32_16x16x32_bf16 v[94:97], v[150:153], v[210:213], v[94:97]
	v_mfma_f32_16x16x32_bf16 v[90:93], v[164:167], v[210:213], v[90:93]
	v_mfma_f32_16x16x32_bf16 v[78:81], v[150:153], v[218:221], v[78:81]
	v_mfma_f32_16x16x32_bf16 v[74:77], v[164:167], v[218:221], v[74:77]
	s_setprio 0
	s_setprio 1
	v_mfma_f32_16x16x32_bf16 v[118:121], v[168:171], v[190:193], v[118:121]
	v_mfma_f32_16x16x32_bf16 v[114:117], v[182:185], v[190:193], v[114:117]
	v_mfma_f32_16x16x32_bf16 v[102:105], v[168:171], v[198:201], v[102:105]
	v_mfma_f32_16x16x32_bf16 v[98:101], v[182:185], v[198:201], v[98:101]
	v_mfma_f32_16x16x32_bf16 v[86:89], v[168:171], v[206:209], v[86:89]
	v_mfma_f32_16x16x32_bf16 v[82:85], v[182:185], v[206:209], v[82:85]
	v_mfma_f32_16x16x32_bf16 v[70:73], v[168:171], v[214:217], v[70:73]
	v_mfma_f32_16x16x32_bf16 v[66:69], v[182:185], v[214:217], v[66:69]
	v_mfma_f32_16x16x32_bf16 v[118:121], v[178:181], v[194:197], v[118:121]
	v_mfma_f32_16x16x32_bf16 v[114:117], v[186:189], v[194:197], v[114:117]
	v_mfma_f32_16x16x32_bf16 v[102:105], v[178:181], v[202:205], v[102:105]
	v_mfma_f32_16x16x32_bf16 v[98:101], v[186:189], v[202:205], v[98:101]
	v_mfma_f32_16x16x32_bf16 v[86:89], v[178:181], v[210:213], v[86:89]
	v_mfma_f32_16x16x32_bf16 v[82:85], v[186:189], v[210:213], v[82:85]
	v_mfma_f32_16x16x32_bf16 v[70:73], v[178:181], v[218:221], v[70:73]
	v_mfma_f32_16x16x32_bf16 v[66:69], v[186:189], v[218:221], v[66:69]
	s_setprio 0
	s_barrier
	s_add_i32 s38, s62, s46
	v_lshl_add_u64 v[172:173], v[172:173], 0, s[12:13]
	s_mov_b32 m0, s38
	ds_read_b128 v[190:193], v158 offset:49152
	ds_read_b128 v[194:197], v158 offset:50176
	ds_read_b128 v[198:201], v158 offset:51200
	ds_read_b128 v[202:205], v158 offset:52224
	ds_read_b128 v[206:209], v158 offset:53248
	ds_read_b128 v[210:213], v158 offset:54272
	ds_read_b128 v[214:217], v158 offset:55296
	ds_read_b128 v[218:221], v158 offset:56320
	global_load_lds_dwordx4 v[172:173], off
	s_add_i32 m0, s38, 0x2000
	s_add_u32 s38, s42, 0x40080
	v_lshl_add_u64 v[172:173], v[222:223], 0, s[12:13]
	s_addc_u32 s39, s43, 0
	s_add_i32 s42, s63, s46
	global_load_lds_dwordx4 v[172:173], off
	s_mov_b32 m0, s42
	v_lshl_add_u64 v[172:173], s[38:39], 0, v[132:133]
	global_load_lds_dwordx4 v[172:173], off
	s_add_i32 m0, s42, 0x2000
	v_lshl_add_u64 v[172:173], s[38:39], 0, v[136:137]
	global_load_lds_dwordx4 v[172:173], off
	s_mov_b32 m0, s51
	v_lshl_add_u64 v[172:173], v[224:225], 0, s[12:13]
	global_load_lds_dwordx4 v[172:173], off
	s_mov_b32 m0, s52
	v_lshl_add_u64 v[172:173], v[226:227], 0, s[12:13]
	global_load_lds_dwordx4 v[172:173], off
	s_waitcnt vmcnt(8)
	s_waitcnt lgkmcnt(0)
	s_barrier
	s_setprio 1
	s_waitcnt lgkmcnt(0)
	v_mfma_f32_16x16x32_bf16 v[62:65], v[146:149], v[190:193], v[62:65]
	v_mfma_f32_16x16x32_bf16 v[58:61], v[160:163], v[190:193], v[58:61]
	v_mfma_f32_16x16x32_bf16 v[46:49], v[146:149], v[198:201], v[46:49]
	v_mfma_f32_16x16x32_bf16 v[42:45], v[160:163], v[198:201], v[42:45]
	v_mfma_f32_16x16x32_bf16 v[30:33], v[146:149], v[206:209], v[30:33]
	v_mfma_f32_16x16x32_bf16 v[26:29], v[160:163], v[206:209], v[26:29]
	v_mfma_f32_16x16x32_bf16 v[14:17], v[146:149], v[214:217], v[14:17]
	v_mfma_f32_16x16x32_bf16 v[10:13], v[160:163], v[214:217], v[10:13]
	v_mfma_f32_16x16x32_bf16 v[62:65], v[150:153], v[194:197], v[62:65]
	v_mfma_f32_16x16x32_bf16 v[58:61], v[164:167], v[194:197], v[58:61]
	v_mfma_f32_16x16x32_bf16 v[46:49], v[150:153], v[202:205], v[46:49]
	v_mfma_f32_16x16x32_bf16 v[42:45], v[164:167], v[202:205], v[42:45]
	v_mfma_f32_16x16x32_bf16 v[30:33], v[150:153], v[210:213], v[30:33]
	v_mfma_f32_16x16x32_bf16 v[26:29], v[164:167], v[210:213], v[26:29]
	v_mfma_f32_16x16x32_bf16 v[14:17], v[150:153], v[218:221], v[14:17]
	v_mfma_f32_16x16x32_bf16 v[10:13], v[164:167], v[218:221], v[10:13]
	s_setprio 0
	s_setprio 1
	v_mfma_f32_16x16x32_bf16 v[54:57], v[168:171], v[190:193], v[54:57]
	v_mfma_f32_16x16x32_bf16 v[50:53], v[182:185], v[190:193], v[50:53]
	v_mfma_f32_16x16x32_bf16 v[38:41], v[168:171], v[198:201], v[38:41]
	v_mfma_f32_16x16x32_bf16 v[34:37], v[182:185], v[198:201], v[34:37]
	v_mfma_f32_16x16x32_bf16 v[22:25], v[168:171], v[206:209], v[22:25]
	v_mfma_f32_16x16x32_bf16 v[18:21], v[182:185], v[206:209], v[18:21]
	v_mfma_f32_16x16x32_bf16 v[6:9], v[168:171], v[214:217], v[6:9]
	v_mfma_f32_16x16x32_bf16 v[2:5], v[182:185], v[214:217], v[2:5]
	v_mfma_f32_16x16x32_bf16 v[54:57], v[178:181], v[194:197], v[54:57]
	v_mfma_f32_16x16x32_bf16 v[50:53], v[186:189], v[194:197], v[50:53]
	v_mfma_f32_16x16x32_bf16 v[38:41], v[178:181], v[202:205], v[38:41]
	v_mfma_f32_16x16x32_bf16 v[34:37], v[186:189], v[202:205], v[34:37]
	v_mfma_f32_16x16x32_bf16 v[22:25], v[178:181], v[210:213], v[22:25]
	v_mfma_f32_16x16x32_bf16 v[18:21], v[186:189], v[210:213], v[18:21]
	v_mfma_f32_16x16x32_bf16 v[6:9], v[178:181], v[218:221], v[6:9]
	v_mfma_f32_16x16x32_bf16 v[2:5], v[186:189], v[218:221], v[2:5]
	s_setprio 0
	s_barrier
	s_add_i32 s61, s61, 2
	s_add_u32 s59, s59, 0x100
	s_addc_u32 s60, s60, 0
	s_cmp_gt_u32 s61, 13
	s_mov_b64 s[38:39], s[40:41]
	s_cbranch_scc0 .LBB0_1135

.LBB0_1223:
	s_ashr_i32 s27, s26, 31
	s_lshl_b64 s[28:29], s[26:27], 19
	s_add_u32 s28, s3, s28
	s_addc_u32 s29, s14, s29
	s_and_b64 s[30:31], s[4:5], exec
	s_cselect_b32 s27, s29, s37
	s_cselect_b32 s35, s28, s36
	s_ashr_i32 s25, s24, 31
	s_lshl_b64 s[30:31], s[24:25], 19
	s_add_u32 s30, s15, s30
	s_addc_u32 s31, s16, s31
	s_and_b64 s[40:41], s[4:5], exec
	s_cselect_b32 s25, s31, s39
	s_cselect_b32 s56, s30, s38
	s_add_u32 s57, s38, 0x100
	s_addc_u32 s58, s39, 0
	s_mov_b32 s59, -2
	s_waitcnt lgkmcnt(0)
	ds_read_b128 v[146:149], v154
	ds_read_b128 v[158:161], v154 offset:1024
	ds_read_b128 v[162:165], v154 offset:2048
	ds_read_b128 v[166:169], v154 offset:3072
	ds_read_b128 v[170:173], v155
	ds_read_b128 v[178:181], v155 offset:1024
	ds_read_b128 v[182:185], v155 offset:2048
	ds_read_b128 v[186:189], v155 offset:3072
	s_add_u32 s38, s36, 0x100
	s_addc_u32 s39, s37, 0
	s_cmp_eq_u32 s59, 12
	s_cselect_b32 s43, s27, s39
	s_cselect_b32 s42, s35, s38
	s_cselect_b32 s41, s25, s58
	s_cselect_b32 s40, s56, s57
	v_lshl_add_u64 v[150:151], s[36:37], 0, v[138:139]
	s_add_i32 m0, s44, 0xc000
	ds_read_b128 v[190:193], v156
	ds_read_b128 v[194:197], v156 offset:1024
	ds_read_b128 v[198:201], v156 offset:2048
	ds_read_b128 v[202:205], v156 offset:3072
	ds_read_b128 v[206:209], v156 offset:4096
	ds_read_b128 v[210:213], v156 offset:5120
	ds_read_b128 v[214:217], v156 offset:6144
	ds_read_b128 v[218:221], v156 offset:7168
	global_load_lds_dwordx4 v[150:151], off
	s_add_i32 m0, s44, 0xe000
	v_lshl_add_u64 v[150:151], s[36:37], 0, v[140:141]
	global_load_lds_dwordx4 v[150:151], off
	s_waitcnt vmcnt(8)
	s_waitcnt lgkmcnt(0)
	s_barrier
	s_setprio 1
	s_waitcnt lgkmcnt(0)
	v_mfma_f32_16x16x32_bf16 v[126:129], v[146:149], v[190:193], 0
	v_mfma_f32_16x16x32_bf16 v[122:125], v[162:165], v[190:193], 0
	v_mfma_f32_16x16x32_bf16 v[110:113], v[146:149], v[198:201], 0
	v_mfma_f32_16x16x32_bf16 v[106:109], v[162:165], v[198:201], 0
	v_mfma_f32_16x16x32_bf16 v[94:97], v[146:149], v[206:209], 0
	v_mfma_f32_16x16x32_bf16 v[90:93], v[162:165], v[206:209], 0
	v_mfma_f32_16x16x32_bf16 v[78:81], v[146:149], v[214:217], 0
	v_mfma_f32_16x16x32_bf16 v[74:77], v[162:165], v[214:217], 0
	v_mfma_f32_16x16x32_bf16 v[126:129], v[158:161], v[194:197], v[126:129]
	v_mfma_f32_16x16x32_bf16 v[122:125], v[166:169], v[194:197], v[122:125]
	v_mfma_f32_16x16x32_bf16 v[110:113], v[158:161], v[202:205], v[110:113]
	v_mfma_f32_16x16x32_bf16 v[106:109], v[166:169], v[202:205], v[106:109]
	v_mfma_f32_16x16x32_bf16 v[94:97], v[158:161], v[210:213], v[94:97]
	v_mfma_f32_16x16x32_bf16 v[90:93], v[166:169], v[210:213], v[90:93]
	v_mfma_f32_16x16x32_bf16 v[78:81], v[158:161], v[218:221], v[78:81]
	v_mfma_f32_16x16x32_bf16 v[74:77], v[166:169], v[218:221], v[74:77]
	s_setprio 0
	s_setprio 1
	v_mfma_f32_16x16x32_bf16 v[118:121], v[170:173], v[190:193], 0
	v_mfma_f32_16x16x32_bf16 v[114:117], v[182:185], v[190:193], 0
	v_mfma_f32_16x16x32_bf16 v[102:105], v[170:173], v[198:201], 0
	v_mfma_f32_16x16x32_bf16 v[98:101], v[182:185], v[198:201], 0
	v_mfma_f32_16x16x32_bf16 v[86:89], v[170:173], v[206:209], 0
	v_mfma_f32_16x16x32_bf16 v[82:85], v[182:185], v[206:209], 0
	v_mfma_f32_16x16x32_bf16 v[70:73], v[170:173], v[214:217], 0
	v_mfma_f32_16x16x32_bf16 v[66:69], v[182:185], v[214:217], 0
	v_mfma_f32_16x16x32_bf16 v[118:121], v[178:181], v[194:197], v[118:121]
	v_mfma_f32_16x16x32_bf16 v[114:117], v[186:189], v[194:197], v[114:117]
	v_mfma_f32_16x16x32_bf16 v[102:105], v[178:181], v[202:205], v[102:105]
	v_mfma_f32_16x16x32_bf16 v[98:101], v[186:189], v[202:205], v[98:101]
	v_mfma_f32_16x16x32_bf16 v[86:89], v[178:181], v[210:213], v[86:89]
	v_mfma_f32_16x16x32_bf16 v[82:85], v[186:189], v[210:213], v[82:85]
	v_mfma_f32_16x16x32_bf16 v[70:73], v[178:181], v[218:221], v[70:73]
	v_mfma_f32_16x16x32_bf16 v[66:69], v[186:189], v[218:221], v[66:69]
	s_setprio 0
	s_barrier
	s_add_i32 s36, s53, s17
	v_lshl_add_u64 v[150:151], s[40:41], 0, v[132:133]
	s_mov_b32 m0, s36
	ds_read_b128 v[190:193], v156 offset:16384
	ds_read_b128 v[194:197], v156 offset:17408
	ds_read_b128 v[198:201], v156 offset:18432
	ds_read_b128 v[202:205], v156 offset:19456
	ds_read_b128 v[206:209], v156 offset:20480
	ds_read_b128 v[210:213], v156 offset:21504
	ds_read_b128 v[214:217], v156 offset:22528
	ds_read_b128 v[218:221], v156 offset:23552
	global_load_lds_dwordx4 v[150:151], off
	s_add_i32 m0, s36, 0x2000
	s_add_u32 s36, s40, 0x40000
	v_lshl_add_u64 v[222:223], s[40:41], 0, v[136:137]
	s_addc_u32 s37, s41, 0
	s_add_i32 s60, s54, s17
	global_load_lds_dwordx4 v[222:223], off
	v_lshl_add_u64 v[224:225], s[36:37], 0, v[132:133]
	s_mov_b32 m0, s60
	v_lshl_add_u64 v[226:227], s[42:43], 0, v[134:135]
	global_load_lds_dwordx4 v[224:225], off
	s_add_i32 m0, s60, 0x2000
	v_lshl_add_u64 v[224:225], s[36:37], 0, v[136:137]
	global_load_lds_dwordx4 v[224:225], off
	s_mov_b32 m0, s44
	v_lshl_add_u64 v[224:225], s[42:43], 0, v[130:131]
	global_load_lds_dwordx4 v[224:225], off
	s_mov_b32 m0, s45
	s_nop 0
	global_load_lds_dwordx4 v[226:227], off
	s_waitcnt vmcnt(8)
	s_waitcnt lgkmcnt(0)
	s_barrier
	s_setprio 1
	s_waitcnt lgkmcnt(0)
	v_mfma_f32_16x16x32_bf16 v[62:65], v[146:149], v[190:193], 0
	v_mfma_f32_16x16x32_bf16 v[58:61], v[162:165], v[190:193], 0
	v_mfma_f32_16x16x32_bf16 v[46:49], v[146:149], v[198:201], 0
	v_mfma_f32_16x16x32_bf16 v[42:45], v[162:165], v[198:201], 0
	v_mfma_f32_16x16x32_bf16 v[30:33], v[146:149], v[206:209], 0
	v_mfma_f32_16x16x32_bf16 v[26:29], v[162:165], v[206:209], 0
	v_mfma_f32_16x16x32_bf16 v[14:17], v[146:149], v[214:217], 0
	v_mfma_f32_16x16x32_bf16 v[10:13], v[162:165], v[214:217], 0
	v_mfma_f32_16x16x32_bf16 v[62:65], v[158:161], v[194:197], v[62:65]
	v_mfma_f32_16x16x32_bf16 v[58:61], v[166:169], v[194:197], v[58:61]
	v_mfma_f32_16x16x32_bf16 v[46:49], v[158:161], v[202:205], v[46:49]
	v_mfma_f32_16x16x32_bf16 v[42:45], v[166:169], v[202:205], v[42:45]
	v_mfma_f32_16x16x32_bf16 v[30:33], v[158:161], v[210:213], v[30:33]
	v_mfma_f32_16x16x32_bf16 v[26:29], v[166:169], v[210:213], v[26:29]
	v_mfma_f32_16x16x32_bf16 v[14:17], v[158:161], v[218:221], v[14:17]
	v_mfma_f32_16x16x32_bf16 v[10:13], v[166:169], v[218:221], v[10:13]
	s_setprio 0
	s_setprio 1
	v_mfma_f32_16x16x32_bf16 v[54:57], v[170:173], v[190:193], 0
	v_mfma_f32_16x16x32_bf16 v[50:53], v[182:185], v[190:193], 0
	v_mfma_f32_16x16x32_bf16 v[38:41], v[170:173], v[198:201], 0
	v_mfma_f32_16x16x32_bf16 v[34:37], v[182:185], v[198:201], 0
	v_mfma_f32_16x16x32_bf16 v[22:25], v[170:173], v[206:209], 0
	v_mfma_f32_16x16x32_bf16 v[18:21], v[182:185], v[206:209], 0
	v_mfma_f32_16x16x32_bf16 v[6:9], v[170:173], v[214:217], 0
	v_mfma_f32_16x16x32_bf16 v[2:5], v[182:185], v[214:217], 0
	v_mfma_f32_16x16x32_bf16 v[54:57], v[178:181], v[194:197], v[54:57]
	v_mfma_f32_16x16x32_bf16 v[50:53], v[186:189], v[194:197], v[50:53]
	v_mfma_f32_16x16x32_bf16 v[38:41], v[178:181], v[202:205], v[38:41]
	v_mfma_f32_16x16x32_bf16 v[34:37], v[186:189], v[202:205], v[34:37]
	v_mfma_f32_16x16x32_bf16 v[22:25], v[178:181], v[210:213], v[22:25]
	v_mfma_f32_16x16x32_bf16 v[18:21], v[186:189], v[210:213], v[18:21]
	v_mfma_f32_16x16x32_bf16 v[6:9], v[178:181], v[218:221], v[6:9]
	v_mfma_f32_16x16x32_bf16 v[2:5], v[186:189], v[218:221], v[2:5]
	s_setprio 0
	s_barrier
	s_add_i32 s60, 0, 0x18000
	s_add_i32 s61, 0, 0x1c000
	v_add_u32_e32 v166, s60, v152
	v_add_u32_e32 v177, s61, v152
	ds_read_b128 v[146:149], v166
	ds_read_b128 v[158:161], v166 offset:1024
	ds_read_b128 v[162:165], v166 offset:2048
	ds_read_b128 v[166:169], v166 offset:3072
	ds_read_b128 v[170:173], v177
	ds_read_b128 v[178:181], v177 offset:1024
	ds_read_b128 v[182:185], v177 offset:2048
	ds_read_b128 v[186:189], v177 offset:3072
	s_add_u32 s36, s42, 0x40000
	s_addc_u32 s37, s43, 0
	s_mov_b32 m0, s46
	v_lshl_add_u64 v[228:229], s[36:37], 0, v[130:131]
	ds_read_b128 v[190:193], v156 offset:32768
	ds_read_b128 v[194:197], v156 offset:33792
	ds_read_b128 v[198:201], v156 offset:34816
	ds_read_b128 v[202:205], v156 offset:35840
	ds_read_b128 v[206:209], v156 offset:36864
	ds_read_b128 v[210:213], v156 offset:37888
	ds_read_b128 v[214:217], v156 offset:38912
	ds_read_b128 v[218:221], v156 offset:39936
	global_load_lds_dwordx4 v[228:229], off
	s_mov_b32 m0, s47
	v_lshl_add_u64 v[228:229], s[36:37], 0, v[134:135]
	global_load_lds_dwordx4 v[228:229], off
	s_waitcnt vmcnt(8)
	s_waitcnt lgkmcnt(0)
	s_barrier
	s_setprio 1
	s_waitcnt lgkmcnt(0)
	v_mfma_f32_16x16x32_bf16 v[126:129], v[146:149], v[190:193], v[126:129]
	v_mfma_f32_16x16x32_bf16 v[122:125], v[162:165], v[190:193], v[122:125]
	v_mfma_f32_16x16x32_bf16 v[110:113], v[146:149], v[198:201], v[110:113]
	v_mfma_f32_16x16x32_bf16 v[106:109], v[162:165], v[198:201], v[106:109]
	v_mfma_f32_16x16x32_bf16 v[94:97], v[146:149], v[206:209], v[94:97]
	v_mfma_f32_16x16x32_bf16 v[90:93], v[162:165], v[206:209], v[90:93]
	v_mfma_f32_16x16x32_bf16 v[78:81], v[146:149], v[214:217], v[78:81]
	v_mfma_f32_16x16x32_bf16 v[74:77], v[162:165], v[214:217], v[74:77]
	v_mfma_f32_16x16x32_bf16 v[126:129], v[158:161], v[194:197], v[126:129]
	v_mfma_f32_16x16x32_bf16 v[122:125], v[166:169], v[194:197], v[122:125]
	v_mfma_f32_16x16x32_bf16 v[110:113], v[158:161], v[202:205], v[110:113]
	v_mfma_f32_16x16x32_bf16 v[106:109], v[166:169], v[202:205], v[106:109]
	v_mfma_f32_16x16x32_bf16 v[94:97], v[158:161], v[210:213], v[94:97]
	v_mfma_f32_16x16x32_bf16 v[90:93], v[166:169], v[210:213], v[90:93]
	v_mfma_f32_16x16x32_bf16 v[78:81], v[158:161], v[218:221], v[78:81]
	v_mfma_f32_16x16x32_bf16 v[74:77], v[166:169], v[218:221], v[74:77]
	s_setprio 0
	s_setprio 1
	v_mfma_f32_16x16x32_bf16 v[118:121], v[170:173], v[190:193], v[118:121]
	v_mfma_f32_16x16x32_bf16 v[114:117], v[182:185], v[190:193], v[114:117]
	v_mfma_f32_16x16x32_bf16 v[102:105], v[170:173], v[198:201], v[102:105]
	v_mfma_f32_16x16x32_bf16 v[98:101], v[182:185], v[198:201], v[98:101]
	v_mfma_f32_16x16x32_bf16 v[86:89], v[170:173], v[206:209], v[86:89]
	v_mfma_f32_16x16x32_bf16 v[82:85], v[182:185], v[206:209], v[82:85]
	v_mfma_f32_16x16x32_bf16 v[70:73], v[170:173], v[214:217], v[70:73]
	v_mfma_f32_16x16x32_bf16 v[66:69], v[182:185], v[214:217], v[66:69]
	v_mfma_f32_16x16x32_bf16 v[118:121], v[178:181], v[194:197], v[118:121]
	v_mfma_f32_16x16x32_bf16 v[114:117], v[186:189], v[194:197], v[114:117]
	v_mfma_f32_16x16x32_bf16 v[102:105], v[178:181], v[202:205], v[102:105]
	v_mfma_f32_16x16x32_bf16 v[98:101], v[186:189], v[202:205], v[98:101]
	v_mfma_f32_16x16x32_bf16 v[86:89], v[178:181], v[210:213], v[86:89]
	v_mfma_f32_16x16x32_bf16 v[82:85], v[186:189], v[210:213], v[82:85]
	v_mfma_f32_16x16x32_bf16 v[70:73], v[178:181], v[218:221], v[70:73]
	v_mfma_f32_16x16x32_bf16 v[66:69], v[186:189], v[218:221], v[66:69]
	s_setprio 0
	s_barrier
	s_add_i32 s36, s60, s17
	v_lshl_add_u64 v[150:151], v[150:151], 0, s[20:21]
	s_mov_b32 m0, s36
	ds_read_b128 v[190:193], v156 offset:49152
	ds_read_b128 v[194:197], v156 offset:50176
	ds_read_b128 v[198:201], v156 offset:51200
	ds_read_b128 v[202:205], v156 offset:52224
	ds_read_b128 v[206:209], v156 offset:53248
	ds_read_b128 v[210:213], v156 offset:54272
	ds_read_b128 v[214:217], v156 offset:55296
	ds_read_b128 v[218:221], v156 offset:56320
	global_load_lds_dwordx4 v[150:151], off
	s_add_i32 m0, s36, 0x2000
	s_add_u32 s36, s40, 0x40080
	v_lshl_add_u64 v[150:151], v[222:223], 0, s[20:21]
	s_addc_u32 s37, s41, 0
	s_add_i32 s40, s61, s17
	global_load_lds_dwordx4 v[150:151], off
	s_mov_b32 m0, s40
	v_lshl_add_u64 v[150:151], s[36:37], 0, v[132:133]
	global_load_lds_dwordx4 v[150:151], off
	s_add_i32 m0, s40, 0x2000
	v_lshl_add_u64 v[150:151], s[36:37], 0, v[136:137]
	global_load_lds_dwordx4 v[150:151], off
	s_mov_b32 m0, s49
	v_lshl_add_u64 v[150:151], v[224:225], 0, s[20:21]
	global_load_lds_dwordx4 v[150:151], off
	s_mov_b32 m0, s50
	v_lshl_add_u64 v[150:151], v[226:227], 0, s[20:21]
	global_load_lds_dwordx4 v[150:151], off
	s_waitcnt vmcnt(8)
	s_waitcnt lgkmcnt(0)
	s_barrier
	s_setprio 1
	s_waitcnt lgkmcnt(0)
	v_mfma_f32_16x16x32_bf16 v[62:65], v[146:149], v[190:193], v[62:65]
	v_mfma_f32_16x16x32_bf16 v[58:61], v[162:165], v[190:193], v[58:61]
	v_mfma_f32_16x16x32_bf16 v[46:49], v[146:149], v[198:201], v[46:49]
	v_mfma_f32_16x16x32_bf16 v[42:45], v[162:165], v[198:201], v[42:45]
	v_mfma_f32_16x16x32_bf16 v[30:33], v[146:149], v[206:209], v[30:33]
	v_mfma_f32_16x16x32_bf16 v[26:29], v[162:165], v[206:209], v[26:29]
	v_mfma_f32_16x16x32_bf16 v[14:17], v[146:149], v[214:217], v[14:17]
	v_mfma_f32_16x16x32_bf16 v[10:13], v[162:165], v[214:217], v[10:13]
	v_mfma_f32_16x16x32_bf16 v[62:65], v[158:161], v[194:197], v[62:65]
	v_mfma_f32_16x16x32_bf16 v[58:61], v[166:169], v[194:197], v[58:61]
	v_mfma_f32_16x16x32_bf16 v[46:49], v[158:161], v[202:205], v[46:49]
	v_mfma_f32_16x16x32_bf16 v[42:45], v[166:169], v[202:205], v[42:45]
	v_mfma_f32_16x16x32_bf16 v[30:33], v[158:161], v[210:213], v[30:33]
	v_mfma_f32_16x16x32_bf16 v[26:29], v[166:169], v[210:213], v[26:29]
	v_mfma_f32_16x16x32_bf16 v[14:17], v[158:161], v[218:221], v[14:17]
	v_mfma_f32_16x16x32_bf16 v[10:13], v[166:169], v[218:221], v[10:13]
	s_setprio 0
	s_setprio 1
	v_mfma_f32_16x16x32_bf16 v[54:57], v[170:173], v[190:193], v[54:57]
	v_mfma_f32_16x16x32_bf16 v[50:53], v[182:185], v[190:193], v[50:53]
	v_mfma_f32_16x16x32_bf16 v[38:41], v[170:173], v[198:201], v[38:41]
	v_mfma_f32_16x16x32_bf16 v[34:37], v[182:185], v[198:201], v[34:37]
	v_mfma_f32_16x16x32_bf16 v[22:25], v[170:173], v[206:209], v[22:25]
	v_mfma_f32_16x16x32_bf16 v[18:21], v[182:185], v[206:209], v[18:21]
	v_mfma_f32_16x16x32_bf16 v[6:9], v[170:173], v[214:217], v[6:9]
	v_mfma_f32_16x16x32_bf16 v[2:5], v[182:185], v[214:217], v[2:5]
	v_mfma_f32_16x16x32_bf16 v[54:57], v[178:181], v[194:197], v[54:57]
	v_mfma_f32_16x16x32_bf16 v[50:53], v[186:189], v[194:197], v[50:53]
	v_mfma_f32_16x16x32_bf16 v[38:41], v[178:181], v[202:205], v[38:41]
	v_mfma_f32_16x16x32_bf16 v[34:37], v[186:189], v[202:205], v[34:37]
	v_mfma_f32_16x16x32_bf16 v[22:25], v[178:181], v[210:213], v[22:25]
	v_mfma_f32_16x16x32_bf16 v[18:21], v[186:189], v[210:213], v[18:21]
	v_mfma_f32_16x16x32_bf16 v[6:9], v[178:181], v[218:221], v[6:9]
	v_mfma_f32_16x16x32_bf16 v[2:5], v[186:189], v[218:221], v[2:5]
	s_setprio 0
	s_barrier
	s_add_i32 s59, s59, 2
	s_add_u32 s57, s57, 0x100
	s_addc_u32 s58, s58, 0
	s_cmp_gt_u32 s59, 13
	s_mov_b64 s[36:37], s[38:39]
	s_cbranch_scc0 .LBB0_1224
	s_branch .Lpeel_exit_1224
.LBB0_1224:
	ds_read_b128 v[146:149], v154
	ds_read_b128 v[158:161], v154 offset:1024
	ds_read_b128 v[162:165], v154 offset:2048
	ds_read_b128 v[166:169], v154 offset:3072
	ds_read_b128 v[170:173], v155
	ds_read_b128 v[178:181], v155 offset:1024
	ds_read_b128 v[182:185], v155 offset:2048
	ds_read_b128 v[186:189], v155 offset:3072
	s_add_u32 s38, s36, 0x100
	s_addc_u32 s39, s37, 0
	s_cmp_eq_u32 s59, 12
	s_cselect_b32 s43, s27, s39
	s_cselect_b32 s42, s35, s38
	s_cselect_b32 s41, s25, s58
	s_cselect_b32 s40, s56, s57
	v_lshl_add_u64 v[150:151], s[36:37], 0, v[138:139]
	s_add_i32 m0, s44, 0xc000
	ds_read_b128 v[190:193], v156
	ds_read_b128 v[194:197], v156 offset:1024
	ds_read_b128 v[198:201], v156 offset:2048
	ds_read_b128 v[202:205], v156 offset:3072
	ds_read_b128 v[206:209], v156 offset:4096
	ds_read_b128 v[210:213], v156 offset:5120
	ds_read_b128 v[214:217], v156 offset:6144
	ds_read_b128 v[218:221], v156 offset:7168
	global_load_lds_dwordx4 v[150:151], off
	s_add_i32 m0, s44, 0xe000
	v_lshl_add_u64 v[150:151], s[36:37], 0, v[140:141]
	global_load_lds_dwordx4 v[150:151], off
	s_waitcnt vmcnt(8)
	s_waitcnt lgkmcnt(0)
	s_barrier
	s_setprio 1
	s_waitcnt lgkmcnt(0)
	v_mfma_f32_16x16x32_bf16 v[126:129], v[146:149], v[190:193], v[126:129]
	v_mfma_f32_16x16x32_bf16 v[122:125], v[162:165], v[190:193], v[122:125]
	v_mfma_f32_16x16x32_bf16 v[110:113], v[146:149], v[198:201], v[110:113]
	v_mfma_f32_16x16x32_bf16 v[106:109], v[162:165], v[198:201], v[106:109]
	v_mfma_f32_16x16x32_bf16 v[94:97], v[146:149], v[206:209], v[94:97]
	v_mfma_f32_16x16x32_bf16 v[90:93], v[162:165], v[206:209], v[90:93]
	v_mfma_f32_16x16x32_bf16 v[78:81], v[146:149], v[214:217], v[78:81]
	v_mfma_f32_16x16x32_bf16 v[74:77], v[162:165], v[214:217], v[74:77]
	v_mfma_f32_16x16x32_bf16 v[126:129], v[158:161], v[194:197], v[126:129]
	v_mfma_f32_16x16x32_bf16 v[122:125], v[166:169], v[194:197], v[122:125]
	v_mfma_f32_16x16x32_bf16 v[110:113], v[158:161], v[202:205], v[110:113]
	v_mfma_f32_16x16x32_bf16 v[106:109], v[166:169], v[202:205], v[106:109]
	v_mfma_f32_16x16x32_bf16 v[94:97], v[158:161], v[210:213], v[94:97]
	v_mfma_f32_16x16x32_bf16 v[90:93], v[166:169], v[210:213], v[90:93]
	v_mfma_f32_16x16x32_bf16 v[78:81], v[158:161], v[218:221], v[78:81]
	v_mfma_f32_16x16x32_bf16 v[74:77], v[166:169], v[218:221], v[74:77]
	s_setprio 0
	s_setprio 1
	v_mfma_f32_16x16x32_bf16 v[118:121], v[170:173], v[190:193], v[118:121]
	v_mfma_f32_16x16x32_bf16 v[114:117], v[182:185], v[190:193], v[114:117]
	v_mfma_f32_16x16x32_bf16 v[102:105], v[170:173], v[198:201], v[102:105]
	v_mfma_f32_16x16x32_bf16 v[98:101], v[182:185], v[198:201], v[98:101]
	v_mfma_f32_16x16x32_bf16 v[86:89], v[170:173], v[206:209], v[86:89]
	v_mfma_f32_16x16x32_bf16 v[82:85], v[182:185], v[206:209], v[82:85]
	v_mfma_f32_16x16x32_bf16 v[70:73], v[170:173], v[214:217], v[70:73]
	v_mfma_f32_16x16x32_bf16 v[66:69], v[182:185], v[214:217], v[66:69]
	v_mfma_f32_16x16x32_bf16 v[118:121], v[178:181], v[194:197], v[118:121]
	v_mfma_f32_16x16x32_bf16 v[114:117], v[186:189], v[194:197], v[114:117]
	v_mfma_f32_16x16x32_bf16 v[102:105], v[178:181], v[202:205], v[102:105]
	v_mfma_f32_16x16x32_bf16 v[98:101], v[186:189], v[202:205], v[98:101]
	v_mfma_f32_16x16x32_bf16 v[86:89], v[178:181], v[210:213], v[86:89]
	v_mfma_f32_16x16x32_bf16 v[82:85], v[186:189], v[210:213], v[82:85]
	v_mfma_f32_16x16x32_bf16 v[70:73], v[178:181], v[218:221], v[70:73]
	v_mfma_f32_16x16x32_bf16 v[66:69], v[186:189], v[218:221], v[66:69]
	s_setprio 0
	s_barrier
	s_add_i32 s36, s53, s17
	v_lshl_add_u64 v[150:151], s[40:41], 0, v[132:133]
	s_mov_b32 m0, s36
	ds_read_b128 v[190:193], v156 offset:16384
	ds_read_b128 v[194:197], v156 offset:17408
	ds_read_b128 v[198:201], v156 offset:18432
	ds_read_b128 v[202:205], v156 offset:19456
	ds_read_b128 v[206:209], v156 offset:20480
	ds_read_b128 v[210:213], v156 offset:21504
	ds_read_b128 v[214:217], v156 offset:22528
	ds_read_b128 v[218:221], v156 offset:23552
	global_load_lds_dwordx4 v[150:151], off
	s_add_i32 m0, s36, 0x2000
	s_add_u32 s36, s40, 0x40000
	v_lshl_add_u64 v[222:223], s[40:41], 0, v[136:137]
	s_addc_u32 s37, s41, 0
	s_add_i32 s60, s54, s17
	global_load_lds_dwordx4 v[222:223], off
	v_lshl_add_u64 v[224:225], s[36:37], 0, v[132:133]
	s_mov_b32 m0, s60
	v_lshl_add_u64 v[226:227], s[42:43], 0, v[134:135]
	global_load_lds_dwordx4 v[224:225], off
	s_add_i32 m0, s60, 0x2000
	v_lshl_add_u64 v[224:225], s[36:37], 0, v[136:137]
	global_load_lds_dwordx4 v[224:225], off
	s_mov_b32 m0, s44
	v_lshl_add_u64 v[224:225], s[42:43], 0, v[130:131]
	global_load_lds_dwordx4 v[224:225], off
	s_mov_b32 m0, s45
	s_nop 0
	global_load_lds_dwordx4 v[226:227], off
	s_waitcnt vmcnt(8)
	s_waitcnt lgkmcnt(0)
	s_barrier
	s_setprio 1
	s_waitcnt lgkmcnt(0)
	v_mfma_f32_16x16x32_bf16 v[62:65], v[146:149], v[190:193], v[62:65]
	v_mfma_f32_16x16x32_bf16 v[58:61], v[162:165], v[190:193], v[58:61]
	v_mfma_f32_16x16x32_bf16 v[46:49], v[146:149], v[198:201], v[46:49]
	v_mfma_f32_16x16x32_bf16 v[42:45], v[162:165], v[198:201], v[42:45]
	v_mfma_f32_16x16x32_bf16 v[30:33], v[146:149], v[206:209], v[30:33]
	v_mfma_f32_16x16x32_bf16 v[26:29], v[162:165], v[206:209], v[26:29]
	v_mfma_f32_16x16x32_bf16 v[14:17], v[146:149], v[214:217], v[14:17]
	v_mfma_f32_16x16x32_bf16 v[10:13], v[162:165], v[214:217], v[10:13]
	v_mfma_f32_16x16x32_bf16 v[62:65], v[158:161], v[194:197], v[62:65]
	v_mfma_f32_16x16x32_bf16 v[58:61], v[166:169], v[194:197], v[58:61]
	v_mfma_f32_16x16x32_bf16 v[46:49], v[158:161], v[202:205], v[46:49]
	v_mfma_f32_16x16x32_bf16 v[42:45], v[166:169], v[202:205], v[42:45]
	v_mfma_f32_16x16x32_bf16 v[30:33], v[158:161], v[210:213], v[30:33]
	v_mfma_f32_16x16x32_bf16 v[26:29], v[166:169], v[210:213], v[26:29]
	v_mfma_f32_16x16x32_bf16 v[14:17], v[158:161], v[218:221], v[14:17]
	v_mfma_f32_16x16x32_bf16 v[10:13], v[166:169], v[218:221], v[10:13]
	s_setprio 0
	s_setprio 1
	v_mfma_f32_16x16x32_bf16 v[54:57], v[170:173], v[190:193], v[54:57]
	v_mfma_f32_16x16x32_bf16 v[50:53], v[182:185], v[190:193], v[50:53]
	v_mfma_f32_16x16x32_bf16 v[38:41], v[170:173], v[198:201], v[38:41]
	v_mfma_f32_16x16x32_bf16 v[34:37], v[182:185], v[198:201], v[34:37]
	v_mfma_f32_16x16x32_bf16 v[22:25], v[170:173], v[206:209], v[22:25]
	v_mfma_f32_16x16x32_bf16 v[18:21], v[182:185], v[206:209], v[18:21]
	v_mfma_f32_16x16x32_bf16 v[6:9], v[170:173], v[214:217], v[6:9]
	v_mfma_f32_16x16x32_bf16 v[2:5], v[182:185], v[214:217], v[2:5]
	v_mfma_f32_16x16x32_bf16 v[54:57], v[178:181], v[194:197], v[54:57]
	v_mfma_f32_16x16x32_bf16 v[50:53], v[186:189], v[194:197], v[50:53]
	v_mfma_f32_16x16x32_bf16 v[38:41], v[178:181], v[202:205], v[38:41]
	v_mfma_f32_16x16x32_bf16 v[34:37], v[186:189], v[202:205], v[34:37]
	v_mfma_f32_16x16x32_bf16 v[22:25], v[178:181], v[210:213], v[22:25]
	v_mfma_f32_16x16x32_bf16 v[18:21], v[186:189], v[210:213], v[18:21]
	v_mfma_f32_16x16x32_bf16 v[6:9], v[178:181], v[218:221], v[6:9]
	v_mfma_f32_16x16x32_bf16 v[2:5], v[186:189], v[218:221], v[2:5]
	s_setprio 0
	s_barrier
	s_add_i32 s60, 0, 0x18000
	s_add_i32 s61, 0, 0x1c000
	v_add_u32_e32 v166, s60, v152
	v_add_u32_e32 v177, s61, v152
	ds_read_b128 v[146:149], v166
	ds_read_b128 v[158:161], v166 offset:1024
	ds_read_b128 v[162:165], v166 offset:2048
	ds_read_b128 v[166:169], v166 offset:3072
	ds_read_b128 v[170:173], v177
	ds_read_b128 v[178:181], v177 offset:1024
	ds_read_b128 v[182:185], v177 offset:2048
	ds_read_b128 v[186:189], v177 offset:3072
	s_add_u32 s36, s42, 0x40000
	s_addc_u32 s37, s43, 0
	s_mov_b32 m0, s46
	v_lshl_add_u64 v[228:229], s[36:37], 0, v[130:131]
	ds_read_b128 v[190:193], v156 offset:32768
	ds_read_b128 v[194:197], v156 offset:33792
	ds_read_b128 v[198:201], v156 offset:34816
	ds_read_b128 v[202:205], v156 offset:35840
	ds_read_b128 v[206:209], v156 offset:36864
	ds_read_b128 v[210:213], v156 offset:37888
	ds_read_b128 v[214:217], v156 offset:38912
	ds_read_b128 v[218:221], v156 offset:39936
	global_load_lds_dwordx4 v[228:229], off
	s_mov_b32 m0, s47
	v_lshl_add_u64 v[228:229], s[36:37], 0, v[134:135]
	global_load_lds_dwordx4 v[228:229], off
	s_waitcnt vmcnt(8)
	s_waitcnt lgkmcnt(0)
	s_barrier
	s_setprio 1
	s_waitcnt lgkmcnt(0)
	v_mfma_f32_16x16x32_bf16 v[126:129], v[146:149], v[190:193], v[126:129]
	v_mfma_f32_16x16x32_bf16 v[122:125], v[162:165], v[190:193], v[122:125]
	v_mfma_f32_16x16x32_bf16 v[110:113], v[146:149], v[198:201], v[110:113]
	v_mfma_f32_16x16x32_bf16 v[106:109], v[162:165], v[198:201], v[106:109]
	v_mfma_f32_16x16x32_bf16 v[94:97], v[146:149], v[206:209], v[94:97]
	v_mfma_f32_16x16x32_bf16 v[90:93], v[162:165], v[206:209], v[90:93]
	v_mfma_f32_16x16x32_bf16 v[78:81], v[146:149], v[214:217], v[78:81]
	v_mfma_f32_16x16x32_bf16 v[74:77], v[162:165], v[214:217], v[74:77]
	v_mfma_f32_16x16x32_bf16 v[126:129], v[158:161], v[194:197], v[126:129]
	v_mfma_f32_16x16x32_bf16 v[122:125], v[166:169], v[194:197], v[122:125]
	v_mfma_f32_16x16x32_bf16 v[110:113], v[158:161], v[202:205], v[110:113]
	v_mfma_f32_16x16x32_bf16 v[106:109], v[166:169], v[202:205], v[106:109]
	v_mfma_f32_16x16x32_bf16 v[94:97], v[158:161], v[210:213], v[94:97]
	v_mfma_f32_16x16x32_bf16 v[90:93], v[166:169], v[210:213], v[90:93]
	v_mfma_f32_16x16x32_bf16 v[78:81], v[158:161], v[218:221], v[78:81]
	v_mfma_f32_16x16x32_bf16 v[74:77], v[166:169], v[218:221], v[74:77]
	s_setprio 0
	s_setprio 1
	v_mfma_f32_16x16x32_bf16 v[118:121], v[170:173], v[190:193], v[118:121]
	v_mfma_f32_16x16x32_bf16 v[114:117], v[182:185], v[190:193], v[114:117]
	v_mfma_f32_16x16x32_bf16 v[102:105], v[170:173], v[198:201], v[102:105]
	v_mfma_f32_16x16x32_bf16 v[98:101], v[182:185], v[198:201], v[98:101]
	v_mfma_f32_16x16x32_bf16 v[86:89], v[170:173], v[206:209], v[86:89]
	v_mfma_f32_16x16x32_bf16 v[82:85], v[182:185], v[206:209], v[82:85]
	v_mfma_f32_16x16x32_bf16 v[70:73], v[170:173], v[214:217], v[70:73]
	v_mfma_f32_16x16x32_bf16 v[66:69], v[182:185], v[214:217], v[66:69]
	v_mfma_f32_16x16x32_bf16 v[118:121], v[178:181], v[194:197], v[118:121]
	v_mfma_f32_16x16x32_bf16 v[114:117], v[186:189], v[194:197], v[114:117]
	v_mfma_f32_16x16x32_bf16 v[102:105], v[178:181], v[202:205], v[102:105]
	v_mfma_f32_16x16x32_bf16 v[98:101], v[186:189], v[202:205], v[98:101]
	v_mfma_f32_16x16x32_bf16 v[86:89], v[178:181], v[210:213], v[86:89]
	v_mfma_f32_16x16x32_bf16 v[82:85], v[186:189], v[210:213], v[82:85]
	v_mfma_f32_16x16x32_bf16 v[70:73], v[178:181], v[218:221], v[70:73]
	v_mfma_f32_16x16x32_bf16 v[66:69], v[186:189], v[218:221], v[66:69]
	s_setprio 0
	s_barrier
	s_add_i32 s36, s60, s17
	v_lshl_add_u64 v[150:151], v[150:151], 0, s[20:21]
	s_mov_b32 m0, s36
	ds_read_b128 v[190:193], v156 offset:49152
	ds_read_b128 v[194:197], v156 offset:50176
	ds_read_b128 v[198:201], v156 offset:51200
	ds_read_b128 v[202:205], v156 offset:52224
	ds_read_b128 v[206:209], v156 offset:53248
	ds_read_b128 v[210:213], v156 offset:54272
	ds_read_b128 v[214:217], v156 offset:55296
	ds_read_b128 v[218:221], v156 offset:56320
	global_load_lds_dwordx4 v[150:151], off
	s_add_i32 m0, s36, 0x2000
	s_add_u32 s36, s40, 0x40080
	v_lshl_add_u64 v[150:151], v[222:223], 0, s[20:21]
	s_addc_u32 s37, s41, 0
	s_add_i32 s40, s61, s17
	global_load_lds_dwordx4 v[150:151], off
	s_mov_b32 m0, s40
	v_lshl_add_u64 v[150:151], s[36:37], 0, v[132:133]
	global_load_lds_dwordx4 v[150:151], off
	s_add_i32 m0, s40, 0x2000
	v_lshl_add_u64 v[150:151], s[36:37], 0, v[136:137]
	global_load_lds_dwordx4 v[150:151], off
	s_mov_b32 m0, s49
	v_lshl_add_u64 v[150:151], v[224:225], 0, s[20:21]
	global_load_lds_dwordx4 v[150:151], off
	s_mov_b32 m0, s50
	v_lshl_add_u64 v[150:151], v[226:227], 0, s[20:21]
	global_load_lds_dwordx4 v[150:151], off
	s_waitcnt vmcnt(8)
	s_waitcnt lgkmcnt(0)
	s_barrier
	s_setprio 1
	s_waitcnt lgkmcnt(0)
	v_mfma_f32_16x16x32_bf16 v[62:65], v[146:149], v[190:193], v[62:65]
	v_mfma_f32_16x16x32_bf16 v[58:61], v[162:165], v[190:193], v[58:61]
	v_mfma_f32_16x16x32_bf16 v[46:49], v[146:149], v[198:201], v[46:49]
	v_mfma_f32_16x16x32_bf16 v[42:45], v[162:165], v[198:201], v[42:45]
	v_mfma_f32_16x16x32_bf16 v[30:33], v[146:149], v[206:209], v[30:33]
	v_mfma_f32_16x16x32_bf16 v[26:29], v[162:165], v[206:209], v[26:29]
	v_mfma_f32_16x16x32_bf16 v[14:17], v[146:149], v[214:217], v[14:17]
	v_mfma_f32_16x16x32_bf16 v[10:13], v[162:165], v[214:217], v[10:13]
	v_mfma_f32_16x16x32_bf16 v[62:65], v[158:161], v[194:197], v[62:65]
	v_mfma_f32_16x16x32_bf16 v[58:61], v[166:169], v[194:197], v[58:61]
	v_mfma_f32_16x16x32_bf16 v[46:49], v[158:161], v[202:205], v[46:49]
	v_mfma_f32_16x16x32_bf16 v[42:45], v[166:169], v[202:205], v[42:45]
	v_mfma_f32_16x16x32_bf16 v[30:33], v[158:161], v[210:213], v[30:33]
	v_mfma_f32_16x16x32_bf16 v[26:29], v[166:169], v[210:213], v[26:29]
	v_mfma_f32_16x16x32_bf16 v[14:17], v[158:161], v[218:221], v[14:17]
	v_mfma_f32_16x16x32_bf16 v[10:13], v[166:169], v[218:221], v[10:13]
	s_setprio 0
	s_setprio 1
	v_mfma_f32_16x16x32_bf16 v[54:57], v[170:173], v[190:193], v[54:57]
	v_mfma_f32_16x16x32_bf16 v[50:53], v[182:185], v[190:193], v[50:53]
	v_mfma_f32_16x16x32_bf16 v[38:41], v[170:173], v[198:201], v[38:41]
	v_mfma_f32_16x16x32_bf16 v[34:37], v[182:185], v[198:201], v[34:37]
	v_mfma_f32_16x16x32_bf16 v[22:25], v[170:173], v[206:209], v[22:25]
	v_mfma_f32_16x16x32_bf16 v[18:21], v[182:185], v[206:209], v[18:21]
	v_mfma_f32_16x16x32_bf16 v[6:9], v[170:173], v[214:217], v[6:9]
	v_mfma_f32_16x16x32_bf16 v[2:5], v[182:185], v[214:217], v[2:5]
	v_mfma_f32_16x16x32_bf16 v[54:57], v[178:181], v[194:197], v[54:57]
	v_mfma_f32_16x16x32_bf16 v[50:53], v[186:189], v[194:197], v[50:53]
	v_mfma_f32_16x16x32_bf16 v[38:41], v[178:181], v[202:205], v[38:41]
	v_mfma_f32_16x16x32_bf16 v[34:37], v[186:189], v[202:205], v[34:37]
	v_mfma_f32_16x16x32_bf16 v[22:25], v[178:181], v[210:213], v[22:25]
	v_mfma_f32_16x16x32_bf16 v[18:21], v[186:189], v[210:213], v[18:21]
	v_mfma_f32_16x16x32_bf16 v[6:9], v[178:181], v[218:221], v[6:9]
	v_mfma_f32_16x16x32_bf16 v[2:5], v[186:189], v[218:221], v[2:5]
	s_setprio 0
	s_barrier
	s_add_i32 s59, s59, 2
	s_add_u32 s57, s57, 0x100
	s_addc_u32 s58, s58, 0
	s_cmp_gt_u32 s59, 13
	s_mov_b64 s[36:37], s[38:39]
	s_cbranch_scc0 .LBB0_1224

.LBB0_1322:
	s_ashr_i32 s23, s22, 31
	s_lshl_b64 s[24:25], s[22:23], 19
	s_add_u32 s24, s3, s24
	s_addc_u32 s25, s14, s25
	s_and_b64 s[26:27], s[0:1], exec
	s_cselect_b32 s23, s25, s29
	s_cselect_b32 s50, s24, s28
	s_ashr_i32 s21, s20, 31
	s_lshl_b64 s[26:27], s[20:21], 19
	s_add_u32 s26, s15, s26
	s_addc_u32 s27, s16, s27
	s_and_b64 s[34:35], s[0:1], exec
	s_cselect_b32 s21, s27, s31
	s_cselect_b32 s51, s26, s30
	s_add_u32 s52, s30, 0x100
	s_addc_u32 s53, s31, 0
	s_mov_b32 s54, -2
	ds_read_b128 v[148:151], v154
	ds_read_b128 v[160:163], v154 offset:1024
	ds_read_b128 v[164:167], v154 offset:2048
	ds_read_b128 v[168:171], v154 offset:3072
	ds_read_b128 v[178:181], v155
	ds_read_b128 v[182:185], v155 offset:1024
	ds_read_b128 v[186:189], v155 offset:2048
	ds_read_b128 v[190:193], v155 offset:3072
	s_add_u32 s30, s28, 0x100
	s_addc_u32 s31, s29, 0
	s_cmp_eq_u32 s54, 12
	s_cselect_b32 s37, s23, s31
	s_cselect_b32 s36, s50, s30
	s_cselect_b32 s35, s21, s53
	s_cselect_b32 s34, s51, s52
	v_lshl_add_u64 v[172:173], s[28:29], 0, v[140:141]
	s_add_i32 m0, s39, 0xc000
	ds_read_b128 v[194:197], v156
	ds_read_b128 v[198:201], v156 offset:1024
	ds_read_b128 v[202:205], v156 offset:2048
	ds_read_b128 v[206:209], v156 offset:3072
	ds_read_b128 v[210:213], v156 offset:4096
	ds_read_b128 v[214:217], v156 offset:5120
	ds_read_b128 v[218:221], v156 offset:6144
	ds_read_b128 v[222:225], v156 offset:7168
	global_load_lds_dwordx4 v[172:173], off
	s_add_i32 m0, s39, 0xe000
	v_lshl_add_u64 v[172:173], s[28:29], 0, v[142:143]
	global_load_lds_dwordx4 v[172:173], off
	s_waitcnt vmcnt(8)
	s_waitcnt lgkmcnt(0)
	s_barrier
	s_setprio 1
	s_waitcnt lgkmcnt(0)
	v_mfma_f32_16x16x32_bf16 v[126:129], v[148:151], v[194:197], 0
	v_mfma_f32_16x16x32_bf16 v[122:125], v[164:167], v[194:197], 0
	v_mfma_f32_16x16x32_bf16 v[110:113], v[148:151], v[202:205], 0
	v_mfma_f32_16x16x32_bf16 v[106:109], v[164:167], v[202:205], 0
	v_mfma_f32_16x16x32_bf16 v[94:97], v[148:151], v[210:213], 0
	v_mfma_f32_16x16x32_bf16 v[90:93], v[164:167], v[210:213], 0
	v_mfma_f32_16x16x32_bf16 v[78:81], v[148:151], v[218:221], 0
	v_mfma_f32_16x16x32_bf16 v[74:77], v[164:167], v[218:221], 0
	v_mfma_f32_16x16x32_bf16 v[126:129], v[160:163], v[198:201], v[126:129]
	v_mfma_f32_16x16x32_bf16 v[122:125], v[168:171], v[198:201], v[122:125]
	v_mfma_f32_16x16x32_bf16 v[110:113], v[160:163], v[206:209], v[110:113]
	v_mfma_f32_16x16x32_bf16 v[106:109], v[168:171], v[206:209], v[106:109]
	v_mfma_f32_16x16x32_bf16 v[94:97], v[160:163], v[214:217], v[94:97]
	v_mfma_f32_16x16x32_bf16 v[90:93], v[168:171], v[214:217], v[90:93]
	v_mfma_f32_16x16x32_bf16 v[78:81], v[160:163], v[222:225], v[78:81]
	v_mfma_f32_16x16x32_bf16 v[74:77], v[168:171], v[222:225], v[74:77]
	s_setprio 0
	s_setprio 1
	v_mfma_f32_16x16x32_bf16 v[118:121], v[178:181], v[194:197], 0
	v_mfma_f32_16x16x32_bf16 v[114:117], v[186:189], v[194:197], 0
	v_mfma_f32_16x16x32_bf16 v[102:105], v[178:181], v[202:205], 0
	v_mfma_f32_16x16x32_bf16 v[98:101], v[186:189], v[202:205], 0
	v_mfma_f32_16x16x32_bf16 v[86:89], v[178:181], v[210:213], 0
	v_mfma_f32_16x16x32_bf16 v[82:85], v[186:189], v[210:213], 0
	v_mfma_f32_16x16x32_bf16 v[70:73], v[178:181], v[218:221], 0
	v_mfma_f32_16x16x32_bf16 v[66:69], v[186:189], v[218:221], 0
	v_mfma_f32_16x16x32_bf16 v[118:121], v[182:185], v[198:201], v[118:121]
	v_mfma_f32_16x16x32_bf16 v[114:117], v[190:193], v[198:201], v[114:117]
	v_mfma_f32_16x16x32_bf16 v[102:105], v[182:185], v[206:209], v[102:105]
	v_mfma_f32_16x16x32_bf16 v[98:101], v[190:193], v[206:209], v[98:101]
	v_mfma_f32_16x16x32_bf16 v[86:89], v[182:185], v[214:217], v[86:89]
	v_mfma_f32_16x16x32_bf16 v[82:85], v[190:193], v[214:217], v[82:85]
	v_mfma_f32_16x16x32_bf16 v[70:73], v[182:185], v[222:225], v[70:73]
	v_mfma_f32_16x16x32_bf16 v[66:69], v[190:193], v[222:225], v[66:69]
	s_setprio 0
	s_barrier
	s_add_i32 s28, s47, s38
	v_lshl_add_u64 v[172:173], s[34:35], 0, v[132:133]
	s_mov_b32 m0, s28
	ds_read_b128 v[194:197], v156 offset:16384
	ds_read_b128 v[198:201], v156 offset:17408
	ds_read_b128 v[202:205], v156 offset:18432
	ds_read_b128 v[206:209], v156 offset:19456
	ds_read_b128 v[210:213], v156 offset:20480
	ds_read_b128 v[214:217], v156 offset:21504
	ds_read_b128 v[218:221], v156 offset:22528
	ds_read_b128 v[222:225], v156 offset:23552
	global_load_lds_dwordx4 v[172:173], off
	s_add_i32 m0, s28, 0x2000
	s_add_u32 s28, s34, 0x40000
	v_lshl_add_u64 v[226:227], s[34:35], 0, v[136:137]
	s_addc_u32 s29, s35, 0
	s_add_i32 s55, s48, s38
	global_load_lds_dwordx4 v[226:227], off
	v_lshl_add_u64 v[228:229], s[28:29], 0, v[132:133]
	s_mov_b32 m0, s55
	v_lshl_add_u64 v[230:231], s[36:37], 0, v[134:135]
	global_load_lds_dwordx4 v[228:229], off
	s_add_i32 m0, s55, 0x2000
	v_lshl_add_u64 v[228:229], s[28:29], 0, v[136:137]
	global_load_lds_dwordx4 v[228:229], off
	s_mov_b32 m0, s39
	v_lshl_add_u64 v[228:229], s[36:37], 0, v[130:131]
	global_load_lds_dwordx4 v[228:229], off
	s_mov_b32 m0, s40
	s_nop 0
	global_load_lds_dwordx4 v[230:231], off
	s_waitcnt vmcnt(8)
	s_waitcnt lgkmcnt(0)
	s_barrier
	s_setprio 1
	s_waitcnt lgkmcnt(0)
	v_mfma_f32_16x16x32_bf16 v[62:65], v[148:151], v[194:197], 0
	v_mfma_f32_16x16x32_bf16 v[58:61], v[164:167], v[194:197], 0
	v_mfma_f32_16x16x32_bf16 v[46:49], v[148:151], v[202:205], 0
	v_mfma_f32_16x16x32_bf16 v[42:45], v[164:167], v[202:205], 0
	v_mfma_f32_16x16x32_bf16 v[30:33], v[148:151], v[210:213], 0
	v_mfma_f32_16x16x32_bf16 v[26:29], v[164:167], v[210:213], 0
	v_mfma_f32_16x16x32_bf16 v[14:17], v[148:151], v[218:221], 0
	v_mfma_f32_16x16x32_bf16 v[10:13], v[164:167], v[218:221], 0
	v_mfma_f32_16x16x32_bf16 v[62:65], v[160:163], v[198:201], v[62:65]
	v_mfma_f32_16x16x32_bf16 v[58:61], v[168:171], v[198:201], v[58:61]
	v_mfma_f32_16x16x32_bf16 v[46:49], v[160:163], v[206:209], v[46:49]
	v_mfma_f32_16x16x32_bf16 v[42:45], v[168:171], v[206:209], v[42:45]
	v_mfma_f32_16x16x32_bf16 v[30:33], v[160:163], v[214:217], v[30:33]
	v_mfma_f32_16x16x32_bf16 v[26:29], v[168:171], v[214:217], v[26:29]
	v_mfma_f32_16x16x32_bf16 v[14:17], v[160:163], v[222:225], v[14:17]
	v_mfma_f32_16x16x32_bf16 v[10:13], v[168:171], v[222:225], v[10:13]
	s_setprio 0
	s_setprio 1
	v_mfma_f32_16x16x32_bf16 v[54:57], v[178:181], v[194:197], 0
	v_mfma_f32_16x16x32_bf16 v[50:53], v[186:189], v[194:197], 0
	v_mfma_f32_16x16x32_bf16 v[38:41], v[178:181], v[202:205], 0
	v_mfma_f32_16x16x32_bf16 v[34:37], v[186:189], v[202:205], 0
	v_mfma_f32_16x16x32_bf16 v[22:25], v[178:181], v[210:213], 0
	v_mfma_f32_16x16x32_bf16 v[18:21], v[186:189], v[210:213], 0
	v_mfma_f32_16x16x32_bf16 v[6:9], v[178:181], v[218:221], 0
	v_mfma_f32_16x16x32_bf16 v[2:5], v[186:189], v[218:221], 0
	v_mfma_f32_16x16x32_bf16 v[54:57], v[182:185], v[198:201], v[54:57]
	v_mfma_f32_16x16x32_bf16 v[50:53], v[190:193], v[198:201], v[50:53]
	v_mfma_f32_16x16x32_bf16 v[38:41], v[182:185], v[206:209], v[38:41]
	v_mfma_f32_16x16x32_bf16 v[34:37], v[190:193], v[206:209], v[34:37]
	v_mfma_f32_16x16x32_bf16 v[22:25], v[182:185], v[214:217], v[22:25]
	v_mfma_f32_16x16x32_bf16 v[18:21], v[190:193], v[214:217], v[18:21]
	v_mfma_f32_16x16x32_bf16 v[6:9], v[182:185], v[222:225], v[6:9]
	v_mfma_f32_16x16x32_bf16 v[2:5], v[190:193], v[222:225], v[2:5]
	s_setprio 0
	s_barrier
	s_add_i32 s55, 0, 0x18000
	v_add_u32_e32 v138, s55, v152
	s_add_i32 s56, 0, 0x1c000
	ds_read_b128 v[148:151], v138
	ds_read_b128 v[160:163], v138 offset:1024
	ds_read_b128 v[164:167], v138 offset:2048
	ds_read_b128 v[168:171], v138 offset:3072
	v_add_u32_e32 v138, s56, v152
	ds_read_b128 v[178:181], v138
	ds_read_b128 v[182:185], v138 offset:1024
	ds_read_b128 v[186:189], v138 offset:2048
	ds_read_b128 v[190:193], v138 offset:3072
	s_add_u32 s28, s36, 0x40000
	s_addc_u32 s29, s37, 0
	s_mov_b32 m0, s41
	v_lshl_add_u64 v[232:233], s[28:29], 0, v[130:131]
	ds_read_b128 v[194:197], v156 offset:32768
	ds_read_b128 v[198:201], v156 offset:33792
	ds_read_b128 v[202:205], v156 offset:34816
	ds_read_b128 v[206:209], v156 offset:35840
	ds_read_b128 v[210:213], v156 offset:36864
	ds_read_b128 v[214:217], v156 offset:37888
	ds_read_b128 v[218:221], v156 offset:38912
	ds_read_b128 v[222:225], v156 offset:39936
	global_load_lds_dwordx4 v[232:233], off
	s_mov_b32 m0, s42
	v_lshl_add_u64 v[232:233], s[28:29], 0, v[134:135]
	global_load_lds_dwordx4 v[232:233], off
	s_waitcnt vmcnt(8)
	s_waitcnt lgkmcnt(0)
	s_barrier
	s_setprio 1
	s_waitcnt lgkmcnt(0)
	v_mfma_f32_16x16x32_bf16 v[126:129], v[148:151], v[194:197], v[126:129]
	v_mfma_f32_16x16x32_bf16 v[122:125], v[164:167], v[194:197], v[122:125]
	v_mfma_f32_16x16x32_bf16 v[110:113], v[148:151], v[202:205], v[110:113]
	v_mfma_f32_16x16x32_bf16 v[106:109], v[164:167], v[202:205], v[106:109]
	v_mfma_f32_16x16x32_bf16 v[94:97], v[148:151], v[210:213], v[94:97]
	v_mfma_f32_16x16x32_bf16 v[90:93], v[164:167], v[210:213], v[90:93]
	v_mfma_f32_16x16x32_bf16 v[78:81], v[148:151], v[218:221], v[78:81]
	v_mfma_f32_16x16x32_bf16 v[74:77], v[164:167], v[218:221], v[74:77]
	v_mfma_f32_16x16x32_bf16 v[126:129], v[160:163], v[198:201], v[126:129]
	v_mfma_f32_16x16x32_bf16 v[122:125], v[168:171], v[198:201], v[122:125]
	v_mfma_f32_16x16x32_bf16 v[110:113], v[160:163], v[206:209], v[110:113]
	v_mfma_f32_16x16x32_bf16 v[106:109], v[168:171], v[206:209], v[106:109]
	v_mfma_f32_16x16x32_bf16 v[94:97], v[160:163], v[214:217], v[94:97]
	v_mfma_f32_16x16x32_bf16 v[90:93], v[168:171], v[214:217], v[90:93]
	v_mfma_f32_16x16x32_bf16 v[78:81], v[160:163], v[222:225], v[78:81]
	v_mfma_f32_16x16x32_bf16 v[74:77], v[168:171], v[222:225], v[74:77]
	s_setprio 0
	s_setprio 1
	v_mfma_f32_16x16x32_bf16 v[118:121], v[178:181], v[194:197], v[118:121]
	v_mfma_f32_16x16x32_bf16 v[114:117], v[186:189], v[194:197], v[114:117]
	v_mfma_f32_16x16x32_bf16 v[102:105], v[178:181], v[202:205], v[102:105]
	v_mfma_f32_16x16x32_bf16 v[98:101], v[186:189], v[202:205], v[98:101]
	v_mfma_f32_16x16x32_bf16 v[86:89], v[178:181], v[210:213], v[86:89]
	v_mfma_f32_16x16x32_bf16 v[82:85], v[186:189], v[210:213], v[82:85]
	v_mfma_f32_16x16x32_bf16 v[70:73], v[178:181], v[218:221], v[70:73]
	v_mfma_f32_16x16x32_bf16 v[66:69], v[186:189], v[218:221], v[66:69]
	v_mfma_f32_16x16x32_bf16 v[118:121], v[182:185], v[198:201], v[118:121]
	v_mfma_f32_16x16x32_bf16 v[114:117], v[190:193], v[198:201], v[114:117]
	v_mfma_f32_16x16x32_bf16 v[102:105], v[182:185], v[206:209], v[102:105]
	v_mfma_f32_16x16x32_bf16 v[98:101], v[190:193], v[206:209], v[98:101]
	v_mfma_f32_16x16x32_bf16 v[86:89], v[182:185], v[214:217], v[86:89]
	v_mfma_f32_16x16x32_bf16 v[82:85], v[190:193], v[214:217], v[82:85]
	v_mfma_f32_16x16x32_bf16 v[70:73], v[182:185], v[222:225], v[70:73]
	v_mfma_f32_16x16x32_bf16 v[66:69], v[190:193], v[222:225], v[66:69]
	s_setprio 0
	s_barrier
	s_add_i32 s28, s55, s38
	v_lshl_add_u64 v[172:173], v[172:173], 0, s[12:13]
	s_mov_b32 m0, s28
	ds_read_b128 v[194:197], v156 offset:49152
	ds_read_b128 v[198:201], v156 offset:50176
	ds_read_b128 v[202:205], v156 offset:51200
	ds_read_b128 v[206:209], v156 offset:52224
	ds_read_b128 v[210:213], v156 offset:53248
	ds_read_b128 v[214:217], v156 offset:54272
	ds_read_b128 v[218:221], v156 offset:55296
	ds_read_b128 v[222:225], v156 offset:56320
	global_load_lds_dwordx4 v[172:173], off
	s_add_i32 m0, s28, 0x2000
	s_add_u32 s28, s34, 0x40080
	v_lshl_add_u64 v[172:173], v[226:227], 0, s[12:13]
	s_addc_u32 s29, s35, 0
	s_add_i32 s34, s56, s38
	global_load_lds_dwordx4 v[172:173], off
	s_mov_b32 m0, s34
	v_lshl_add_u64 v[172:173], s[28:29], 0, v[132:133]
	global_load_lds_dwordx4 v[172:173], off
	s_add_i32 m0, s34, 0x2000
	v_lshl_add_u64 v[172:173], s[28:29], 0, v[136:137]
	global_load_lds_dwordx4 v[172:173], off
	s_mov_b32 m0, s44
	v_lshl_add_u64 v[172:173], v[228:229], 0, s[12:13]
	global_load_lds_dwordx4 v[172:173], off
	s_mov_b32 m0, s45
	v_lshl_add_u64 v[172:173], v[230:231], 0, s[12:13]
	global_load_lds_dwordx4 v[172:173], off
	s_waitcnt vmcnt(8)
	s_waitcnt lgkmcnt(0)
	s_barrier
	s_setprio 1
	s_waitcnt lgkmcnt(0)
	v_mfma_f32_16x16x32_bf16 v[62:65], v[148:151], v[194:197], v[62:65]
	v_mfma_f32_16x16x32_bf16 v[58:61], v[164:167], v[194:197], v[58:61]
	v_mfma_f32_16x16x32_bf16 v[46:49], v[148:151], v[202:205], v[46:49]
	v_mfma_f32_16x16x32_bf16 v[42:45], v[164:167], v[202:205], v[42:45]
	v_mfma_f32_16x16x32_bf16 v[30:33], v[148:151], v[210:213], v[30:33]
	v_mfma_f32_16x16x32_bf16 v[26:29], v[164:167], v[210:213], v[26:29]
	v_mfma_f32_16x16x32_bf16 v[14:17], v[148:151], v[218:221], v[14:17]
	v_mfma_f32_16x16x32_bf16 v[10:13], v[164:167], v[218:221], v[10:13]
	v_mfma_f32_16x16x32_bf16 v[62:65], v[160:163], v[198:201], v[62:65]
	v_mfma_f32_16x16x32_bf16 v[58:61], v[168:171], v[198:201], v[58:61]
	v_mfma_f32_16x16x32_bf16 v[46:49], v[160:163], v[206:209], v[46:49]
	v_mfma_f32_16x16x32_bf16 v[42:45], v[168:171], v[206:209], v[42:45]
	v_mfma_f32_16x16x32_bf16 v[30:33], v[160:163], v[214:217], v[30:33]
	v_mfma_f32_16x16x32_bf16 v[26:29], v[168:171], v[214:217], v[26:29]
	v_mfma_f32_16x16x32_bf16 v[14:17], v[160:163], v[222:225], v[14:17]
	v_mfma_f32_16x16x32_bf16 v[10:13], v[168:171], v[222:225], v[10:13]
	s_setprio 0
	s_setprio 1
	v_mfma_f32_16x16x32_bf16 v[54:57], v[178:181], v[194:197], v[54:57]
	v_mfma_f32_16x16x32_bf16 v[50:53], v[186:189], v[194:197], v[50:53]
	v_mfma_f32_16x16x32_bf16 v[38:41], v[178:181], v[202:205], v[38:41]
	v_mfma_f32_16x16x32_bf16 v[34:37], v[186:189], v[202:205], v[34:37]
	v_mfma_f32_16x16x32_bf16 v[22:25], v[178:181], v[210:213], v[22:25]
	v_mfma_f32_16x16x32_bf16 v[18:21], v[186:189], v[210:213], v[18:21]
	v_mfma_f32_16x16x32_bf16 v[6:9], v[178:181], v[218:221], v[6:9]
	v_mfma_f32_16x16x32_bf16 v[2:5], v[186:189], v[218:221], v[2:5]
	v_mfma_f32_16x16x32_bf16 v[54:57], v[182:185], v[198:201], v[54:57]
	v_mfma_f32_16x16x32_bf16 v[50:53], v[190:193], v[198:201], v[50:53]
	v_mfma_f32_16x16x32_bf16 v[38:41], v[182:185], v[206:209], v[38:41]
	v_mfma_f32_16x16x32_bf16 v[34:37], v[190:193], v[206:209], v[34:37]
	v_mfma_f32_16x16x32_bf16 v[22:25], v[182:185], v[214:217], v[22:25]
	v_mfma_f32_16x16x32_bf16 v[18:21], v[190:193], v[214:217], v[18:21]
	v_mfma_f32_16x16x32_bf16 v[6:9], v[182:185], v[222:225], v[6:9]
	v_mfma_f32_16x16x32_bf16 v[2:5], v[190:193], v[222:225], v[2:5]
	s_setprio 0
	s_barrier
	s_add_i32 s54, s54, 2
	s_add_u32 s52, s52, 0x100
	s_addc_u32 s53, s53, 0
	s_cmp_gt_u32 s54, 13
	s_mov_b64 s[28:29], s[30:31]
	s_cbranch_scc0 .LBB0_1323
	s_branch .Lpeel_exit_1323
.LBB0_1323:
	ds_read_b128 v[148:151], v154
	ds_read_b128 v[160:163], v154 offset:1024
	ds_read_b128 v[164:167], v154 offset:2048
	ds_read_b128 v[168:171], v154 offset:3072
	ds_read_b128 v[178:181], v155
	ds_read_b128 v[182:185], v155 offset:1024
	ds_read_b128 v[186:189], v155 offset:2048
	ds_read_b128 v[190:193], v155 offset:3072
	s_add_u32 s30, s28, 0x100
	s_addc_u32 s31, s29, 0
	s_cmp_eq_u32 s54, 12
	s_cselect_b32 s37, s23, s31
	s_cselect_b32 s36, s50, s30
	s_cselect_b32 s35, s21, s53
	s_cselect_b32 s34, s51, s52
	v_lshl_add_u64 v[172:173], s[28:29], 0, v[140:141]
	s_add_i32 m0, s39, 0xc000
	ds_read_b128 v[194:197], v156
	ds_read_b128 v[198:201], v156 offset:1024
	ds_read_b128 v[202:205], v156 offset:2048
	ds_read_b128 v[206:209], v156 offset:3072
	ds_read_b128 v[210:213], v156 offset:4096
	ds_read_b128 v[214:217], v156 offset:5120
	ds_read_b128 v[218:221], v156 offset:6144
	ds_read_b128 v[222:225], v156 offset:7168
	global_load_lds_dwordx4 v[172:173], off
	s_add_i32 m0, s39, 0xe000
	v_lshl_add_u64 v[172:173], s[28:29], 0, v[142:143]
	global_load_lds_dwordx4 v[172:173], off
	s_waitcnt vmcnt(8)
	s_waitcnt lgkmcnt(0)
	s_barrier
	s_setprio 1
	s_waitcnt lgkmcnt(0)
	v_mfma_f32_16x16x32_bf16 v[126:129], v[148:151], v[194:197], v[126:129]
	v_mfma_f32_16x16x32_bf16 v[122:125], v[164:167], v[194:197], v[122:125]
	v_mfma_f32_16x16x32_bf16 v[110:113], v[148:151], v[202:205], v[110:113]
	v_mfma_f32_16x16x32_bf16 v[106:109], v[164:167], v[202:205], v[106:109]
	v_mfma_f32_16x16x32_bf16 v[94:97], v[148:151], v[210:213], v[94:97]
	v_mfma_f32_16x16x32_bf16 v[90:93], v[164:167], v[210:213], v[90:93]
	v_mfma_f32_16x16x32_bf16 v[78:81], v[148:151], v[218:221], v[78:81]
	v_mfma_f32_16x16x32_bf16 v[74:77], v[164:167], v[218:221], v[74:77]
	v_mfma_f32_16x16x32_bf16 v[126:129], v[160:163], v[198:201], v[126:129]
	v_mfma_f32_16x16x32_bf16 v[122:125], v[168:171], v[198:201], v[122:125]
	v_mfma_f32_16x16x32_bf16 v[110:113], v[160:163], v[206:209], v[110:113]
	v_mfma_f32_16x16x32_bf16 v[106:109], v[168:171], v[206:209], v[106:109]
	v_mfma_f32_16x16x32_bf16 v[94:97], v[160:163], v[214:217], v[94:97]
	v_mfma_f32_16x16x32_bf16 v[90:93], v[168:171], v[214:217], v[90:93]
	v_mfma_f32_16x16x32_bf16 v[78:81], v[160:163], v[222:225], v[78:81]
	v_mfma_f32_16x16x32_bf16 v[74:77], v[168:171], v[222:225], v[74:77]
	s_setprio 0
	s_setprio 1
	v_mfma_f32_16x16x32_bf16 v[118:121], v[178:181], v[194:197], v[118:121]
	v_mfma_f32_16x16x32_bf16 v[114:117], v[186:189], v[194:197], v[114:117]
	v_mfma_f32_16x16x32_bf16 v[102:105], v[178:181], v[202:205], v[102:105]
	v_mfma_f32_16x16x32_bf16 v[98:101], v[186:189], v[202:205], v[98:101]
	v_mfma_f32_16x16x32_bf16 v[86:89], v[178:181], v[210:213], v[86:89]
	v_mfma_f32_16x16x32_bf16 v[82:85], v[186:189], v[210:213], v[82:85]
	v_mfma_f32_16x16x32_bf16 v[70:73], v[178:181], v[218:221], v[70:73]
	v_mfma_f32_16x16x32_bf16 v[66:69], v[186:189], v[218:221], v[66:69]
	v_mfma_f32_16x16x32_bf16 v[118:121], v[182:185], v[198:201], v[118:121]
	v_mfma_f32_16x16x32_bf16 v[114:117], v[190:193], v[198:201], v[114:117]
	v_mfma_f32_16x16x32_bf16 v[102:105], v[182:185], v[206:209], v[102:105]
	v_mfma_f32_16x16x32_bf16 v[98:101], v[190:193], v[206:209], v[98:101]
	v_mfma_f32_16x16x32_bf16 v[86:89], v[182:185], v[214:217], v[86:89]
	v_mfma_f32_16x16x32_bf16 v[82:85], v[190:193], v[214:217], v[82:85]
	v_mfma_f32_16x16x32_bf16 v[70:73], v[182:185], v[222:225], v[70:73]
	v_mfma_f32_16x16x32_bf16 v[66:69], v[190:193], v[222:225], v[66:69]
	s_setprio 0
	s_barrier
	s_add_i32 s28, s47, s38
	v_lshl_add_u64 v[172:173], s[34:35], 0, v[132:133]
	s_mov_b32 m0, s28
	ds_read_b128 v[194:197], v156 offset:16384
	ds_read_b128 v[198:201], v156 offset:17408
	ds_read_b128 v[202:205], v156 offset:18432
	ds_read_b128 v[206:209], v156 offset:19456
	ds_read_b128 v[210:213], v156 offset:20480
	ds_read_b128 v[214:217], v156 offset:21504
	ds_read_b128 v[218:221], v156 offset:22528
	ds_read_b128 v[222:225], v156 offset:23552
	global_load_lds_dwordx4 v[172:173], off
	s_add_i32 m0, s28, 0x2000
	s_add_u32 s28, s34, 0x40000
	v_lshl_add_u64 v[226:227], s[34:35], 0, v[136:137]
	s_addc_u32 s29, s35, 0
	s_add_i32 s55, s48, s38
	global_load_lds_dwordx4 v[226:227], off
	v_lshl_add_u64 v[228:229], s[28:29], 0, v[132:133]
	s_mov_b32 m0, s55
	v_lshl_add_u64 v[230:231], s[36:37], 0, v[134:135]
	global_load_lds_dwordx4 v[228:229], off
	s_add_i32 m0, s55, 0x2000
	v_lshl_add_u64 v[228:229], s[28:29], 0, v[136:137]
	global_load_lds_dwordx4 v[228:229], off
	s_mov_b32 m0, s39
	v_lshl_add_u64 v[228:229], s[36:37], 0, v[130:131]
	global_load_lds_dwordx4 v[228:229], off
	s_mov_b32 m0, s40
	s_nop 0
	global_load_lds_dwordx4 v[230:231], off
	s_waitcnt vmcnt(8)
	s_waitcnt lgkmcnt(0)
	s_barrier
	s_setprio 1
	s_waitcnt lgkmcnt(0)
	v_mfma_f32_16x16x32_bf16 v[62:65], v[148:151], v[194:197], v[62:65]
	v_mfma_f32_16x16x32_bf16 v[58:61], v[164:167], v[194:197], v[58:61]
	v_mfma_f32_16x16x32_bf16 v[46:49], v[148:151], v[202:205], v[46:49]
	v_mfma_f32_16x16x32_bf16 v[42:45], v[164:167], v[202:205], v[42:45]
	v_mfma_f32_16x16x32_bf16 v[30:33], v[148:151], v[210:213], v[30:33]
	v_mfma_f32_16x16x32_bf16 v[26:29], v[164:167], v[210:213], v[26:29]
	v_mfma_f32_16x16x32_bf16 v[14:17], v[148:151], v[218:221], v[14:17]
	v_mfma_f32_16x16x32_bf16 v[10:13], v[164:167], v[218:221], v[10:13]
	v_mfma_f32_16x16x32_bf16 v[62:65], v[160:163], v[198:201], v[62:65]
	v_mfma_f32_16x16x32_bf16 v[58:61], v[168:171], v[198:201], v[58:61]
	v_mfma_f32_16x16x32_bf16 v[46:49], v[160:163], v[206:209], v[46:49]
	v_mfma_f32_16x16x32_bf16 v[42:45], v[168:171], v[206:209], v[42:45]
	v_mfma_f32_16x16x32_bf16 v[30:33], v[160:163], v[214:217], v[30:33]
	v_mfma_f32_16x16x32_bf16 v[26:29], v[168:171], v[214:217], v[26:29]
	v_mfma_f32_16x16x32_bf16 v[14:17], v[160:163], v[222:225], v[14:17]
	v_mfma_f32_16x16x32_bf16 v[10:13], v[168:171], v[222:225], v[10:13]
	s_setprio 0
	s_setprio 1
	v_mfma_f32_16x16x32_bf16 v[54:57], v[178:181], v[194:197], v[54:57]
	v_mfma_f32_16x16x32_bf16 v[50:53], v[186:189], v[194:197], v[50:53]
	v_mfma_f32_16x16x32_bf16 v[38:41], v[178:181], v[202:205], v[38:41]
	v_mfma_f32_16x16x32_bf16 v[34:37], v[186:189], v[202:205], v[34:37]
	v_mfma_f32_16x16x32_bf16 v[22:25], v[178:181], v[210:213], v[22:25]
	v_mfma_f32_16x16x32_bf16 v[18:21], v[186:189], v[210:213], v[18:21]
	v_mfma_f32_16x16x32_bf16 v[6:9], v[178:181], v[218:221], v[6:9]
	v_mfma_f32_16x16x32_bf16 v[2:5], v[186:189], v[218:221], v[2:5]
	v_mfma_f32_16x16x32_bf16 v[54:57], v[182:185], v[198:201], v[54:57]
	v_mfma_f32_16x16x32_bf16 v[50:53], v[190:193], v[198:201], v[50:53]
	v_mfma_f32_16x16x32_bf16 v[38:41], v[182:185], v[206:209], v[38:41]
	v_mfma_f32_16x16x32_bf16 v[34:37], v[190:193], v[206:209], v[34:37]
	v_mfma_f32_16x16x32_bf16 v[22:25], v[182:185], v[214:217], v[22:25]
	v_mfma_f32_16x16x32_bf16 v[18:21], v[190:193], v[214:217], v[18:21]
	v_mfma_f32_16x16x32_bf16 v[6:9], v[182:185], v[222:225], v[6:9]
	v_mfma_f32_16x16x32_bf16 v[2:5], v[190:193], v[222:225], v[2:5]
	s_setprio 0
	s_barrier
	s_add_i32 s55, 0, 0x18000
	v_add_u32_e32 v138, s55, v152
	s_add_i32 s56, 0, 0x1c000
	ds_read_b128 v[148:151], v138
	ds_read_b128 v[160:163], v138 offset:1024
	ds_read_b128 v[164:167], v138 offset:2048
	ds_read_b128 v[168:171], v138 offset:3072
	v_add_u32_e32 v138, s56, v152
	ds_read_b128 v[178:181], v138
	ds_read_b128 v[182:185], v138 offset:1024
	ds_read_b128 v[186:189], v138 offset:2048
	ds_read_b128 v[190:193], v138 offset:3072
	s_add_u32 s28, s36, 0x40000
	s_addc_u32 s29, s37, 0
	s_mov_b32 m0, s41
	v_lshl_add_u64 v[232:233], s[28:29], 0, v[130:131]
	ds_read_b128 v[194:197], v156 offset:32768
	ds_read_b128 v[198:201], v156 offset:33792
	ds_read_b128 v[202:205], v156 offset:34816
	ds_read_b128 v[206:209], v156 offset:35840
	ds_read_b128 v[210:213], v156 offset:36864
	ds_read_b128 v[214:217], v156 offset:37888
	ds_read_b128 v[218:221], v156 offset:38912
	ds_read_b128 v[222:225], v156 offset:39936
	global_load_lds_dwordx4 v[232:233], off
	s_mov_b32 m0, s42
	v_lshl_add_u64 v[232:233], s[28:29], 0, v[134:135]
	global_load_lds_dwordx4 v[232:233], off
	s_waitcnt vmcnt(8)
	s_waitcnt lgkmcnt(0)
	s_barrier
	s_setprio 1
	s_waitcnt lgkmcnt(0)
	v_mfma_f32_16x16x32_bf16 v[126:129], v[148:151], v[194:197], v[126:129]
	v_mfma_f32_16x16x32_bf16 v[122:125], v[164:167], v[194:197], v[122:125]
	v_mfma_f32_16x16x32_bf16 v[110:113], v[148:151], v[202:205], v[110:113]
	v_mfma_f32_16x16x32_bf16 v[106:109], v[164:167], v[202:205], v[106:109]
	v_mfma_f32_16x16x32_bf16 v[94:97], v[148:151], v[210:213], v[94:97]
	v_mfma_f32_16x16x32_bf16 v[90:93], v[164:167], v[210:213], v[90:93]
	v_mfma_f32_16x16x32_bf16 v[78:81], v[148:151], v[218:221], v[78:81]
	v_mfma_f32_16x16x32_bf16 v[74:77], v[164:167], v[218:221], v[74:77]
	v_mfma_f32_16x16x32_bf16 v[126:129], v[160:163], v[198:201], v[126:129]
	v_mfma_f32_16x16x32_bf16 v[122:125], v[168:171], v[198:201], v[122:125]
	v_mfma_f32_16x16x32_bf16 v[110:113], v[160:163], v[206:209], v[110:113]
	v_mfma_f32_16x16x32_bf16 v[106:109], v[168:171], v[206:209], v[106:109]
	v_mfma_f32_16x16x32_bf16 v[94:97], v[160:163], v[214:217], v[94:97]
	v_mfma_f32_16x16x32_bf16 v[90:93], v[168:171], v[214:217], v[90:93]
	v_mfma_f32_16x16x32_bf16 v[78:81], v[160:163], v[222:225], v[78:81]
	v_mfma_f32_16x16x32_bf16 v[74:77], v[168:171], v[222:225], v[74:77]
	s_setprio 0
	s_setprio 1
	v_mfma_f32_16x16x32_bf16 v[118:121], v[178:181], v[194:197], v[118:121]
	v_mfma_f32_16x16x32_bf16 v[114:117], v[186:189], v[194:197], v[114:117]
	v_mfma_f32_16x16x32_bf16 v[102:105], v[178:181], v[202:205], v[102:105]
	v_mfma_f32_16x16x32_bf16 v[98:101], v[186:189], v[202:205], v[98:101]
	v_mfma_f32_16x16x32_bf16 v[86:89], v[178:181], v[210:213], v[86:89]
	v_mfma_f32_16x16x32_bf16 v[82:85], v[186:189], v[210:213], v[82:85]
	v_mfma_f32_16x16x32_bf16 v[70:73], v[178:181], v[218:221], v[70:73]
	v_mfma_f32_16x16x32_bf16 v[66:69], v[186:189], v[218:221], v[66:69]
	v_mfma_f32_16x16x32_bf16 v[118:121], v[182:185], v[198:201], v[118:121]
	v_mfma_f32_16x16x32_bf16 v[114:117], v[190:193], v[198:201], v[114:117]
	v_mfma_f32_16x16x32_bf16 v[102:105], v[182:185], v[206:209], v[102:105]
	v_mfma_f32_16x16x32_bf16 v[98:101], v[190:193], v[206:209], v[98:101]
	v_mfma_f32_16x16x32_bf16 v[86:89], v[182:185], v[214:217], v[86:89]
	v_mfma_f32_16x16x32_bf16 v[82:85], v[190:193], v[214:217], v[82:85]
	v_mfma_f32_16x16x32_bf16 v[70:73], v[182:185], v[222:225], v[70:73]
	v_mfma_f32_16x16x32_bf16 v[66:69], v[190:193], v[222:225], v[66:69]
	s_setprio 0
	s_barrier
	s_add_i32 s28, s55, s38
	v_lshl_add_u64 v[172:173], v[172:173], 0, s[12:13]
	s_mov_b32 m0, s28
	ds_read_b128 v[194:197], v156 offset:49152
	ds_read_b128 v[198:201], v156 offset:50176
	ds_read_b128 v[202:205], v156 offset:51200
	ds_read_b128 v[206:209], v156 offset:52224
	ds_read_b128 v[210:213], v156 offset:53248
	ds_read_b128 v[214:217], v156 offset:54272
	ds_read_b128 v[218:221], v156 offset:55296
	ds_read_b128 v[222:225], v156 offset:56320
	global_load_lds_dwordx4 v[172:173], off
	s_add_i32 m0, s28, 0x2000
	s_add_u32 s28, s34, 0x40080
	v_lshl_add_u64 v[172:173], v[226:227], 0, s[12:13]
	s_addc_u32 s29, s35, 0
	s_add_i32 s34, s56, s38
	global_load_lds_dwordx4 v[172:173], off
	s_mov_b32 m0, s34
	v_lshl_add_u64 v[172:173], s[28:29], 0, v[132:133]
	global_load_lds_dwordx4 v[172:173], off
	s_add_i32 m0, s34, 0x2000
	v_lshl_add_u64 v[172:173], s[28:29], 0, v[136:137]
	global_load_lds_dwordx4 v[172:173], off
	s_mov_b32 m0, s44
	v_lshl_add_u64 v[172:173], v[228:229], 0, s[12:13]
	global_load_lds_dwordx4 v[172:173], off
	s_mov_b32 m0, s45
	v_lshl_add_u64 v[172:173], v[230:231], 0, s[12:13]
	global_load_lds_dwordx4 v[172:173], off
	s_waitcnt vmcnt(8)
	s_waitcnt lgkmcnt(0)
	s_barrier
	s_setprio 1
	s_waitcnt lgkmcnt(0)
	v_mfma_f32_16x16x32_bf16 v[62:65], v[148:151], v[194:197], v[62:65]
	v_mfma_f32_16x16x32_bf16 v[58:61], v[164:167], v[194:197], v[58:61]
	v_mfma_f32_16x16x32_bf16 v[46:49], v[148:151], v[202:205], v[46:49]
	v_mfma_f32_16x16x32_bf16 v[42:45], v[164:167], v[202:205], v[42:45]
	v_mfma_f32_16x16x32_bf16 v[30:33], v[148:151], v[210:213], v[30:33]
	v_mfma_f32_16x16x32_bf16 v[26:29], v[164:167], v[210:213], v[26:29]
	v_mfma_f32_16x16x32_bf16 v[14:17], v[148:151], v[218:221], v[14:17]
	v_mfma_f32_16x16x32_bf16 v[10:13], v[164:167], v[218:221], v[10:13]
	v_mfma_f32_16x16x32_bf16 v[62:65], v[160:163], v[198:201], v[62:65]
	v_mfma_f32_16x16x32_bf16 v[58:61], v[168:171], v[198:201], v[58:61]
	v_mfma_f32_16x16x32_bf16 v[46:49], v[160:163], v[206:209], v[46:49]
	v_mfma_f32_16x16x32_bf16 v[42:45], v[168:171], v[206:209], v[42:45]
	v_mfma_f32_16x16x32_bf16 v[30:33], v[160:163], v[214:217], v[30:33]
	v_mfma_f32_16x16x32_bf16 v[26:29], v[168:171], v[214:217], v[26:29]
	v_mfma_f32_16x16x32_bf16 v[14:17], v[160:163], v[222:225], v[14:17]
	v_mfma_f32_16x16x32_bf16 v[10:13], v[168:171], v[222:225], v[10:13]
	s_setprio 0
	s_setprio 1
	v_mfma_f32_16x16x32_bf16 v[54:57], v[178:181], v[194:197], v[54:57]
	v_mfma_f32_16x16x32_bf16 v[50:53], v[186:189], v[194:197], v[50:53]
	v_mfma_f32_16x16x32_bf16 v[38:41], v[178:181], v[202:205], v[38:41]
	v_mfma_f32_16x16x32_bf16 v[34:37], v[186:189], v[202:205], v[34:37]
	v_mfma_f32_16x16x32_bf16 v[22:25], v[178:181], v[210:213], v[22:25]
	v_mfma_f32_16x16x32_bf16 v[18:21], v[186:189], v[210:213], v[18:21]
	v_mfma_f32_16x16x32_bf16 v[6:9], v[178:181], v[218:221], v[6:9]
	v_mfma_f32_16x16x32_bf16 v[2:5], v[186:189], v[218:221], v[2:5]
	v_mfma_f32_16x16x32_bf16 v[54:57], v[182:185], v[198:201], v[54:57]
	v_mfma_f32_16x16x32_bf16 v[50:53], v[190:193], v[198:201], v[50:53]
	v_mfma_f32_16x16x32_bf16 v[38:41], v[182:185], v[206:209], v[38:41]
	v_mfma_f32_16x16x32_bf16 v[34:37], v[190:193], v[206:209], v[34:37]
	v_mfma_f32_16x16x32_bf16 v[22:25], v[182:185], v[214:217], v[22:25]
	v_mfma_f32_16x16x32_bf16 v[18:21], v[190:193], v[214:217], v[18:21]
	v_mfma_f32_16x16x32_bf16 v[6:9], v[182:185], v[222:225], v[6:9]
	v_mfma_f32_16x16x32_bf16 v[2:5], v[190:193], v[222:225], v[2:5]
	s_setprio 0
	s_barrier
	s_add_i32 s54, s54, 2
	s_add_u32 s52, s52, 0x100
	s_addc_u32 s53, s53, 0
	s_cmp_gt_u32 s54, 13
	s_mov_b64 s[28:29], s[30:31]
	s_cbranch_scc0 .LBB0_1323

.LBB0_1495:
	s_ashr_i32 s25, s24, 31
	s_lshl_b64 s[26:27], s[24:25], 19
	s_add_u32 s26, s3, s26
	s_addc_u32 s27, s14, s27
	s_and_b64 s[28:29], s[4:5], exec
	s_cselect_b32 s25, s27, s35
	s_cselect_b32 s31, s26, s34
	s_ashr_i32 s23, s22, 31
	s_lshl_b64 s[28:29], s[22:23], 19
	s_add_u32 s28, s15, s28
	s_addc_u32 s29, s16, s29
	s_and_b64 s[38:39], s[4:5], exec
	s_cselect_b32 s23, s29, s37
	s_cselect_b32 s54, s28, s36
	s_add_u32 s55, s36, 0x100
	s_addc_u32 s56, s37, 0
	s_mov_b32 s57, -2
	s_waitcnt lgkmcnt(0)
	ds_read_b128 v[146:149], v153
	ds_read_b128 v[158:161], v153 offset:1024
	ds_read_b128 v[162:165], v153 offset:2048
	ds_read_b128 v[166:169], v153 offset:3072
	ds_read_b128 v[170:173], v154
	ds_read_b128 v[178:181], v154 offset:1024
	ds_read_b128 v[182:185], v154 offset:2048
	ds_read_b128 v[186:189], v154 offset:3072
	s_add_u32 s36, s34, 0x100
	s_addc_u32 s37, s35, 0
	s_cmp_eq_u32 s57, 12
	s_cselect_b32 s41, s25, s37
	s_cselect_b32 s40, s31, s36
	s_cselect_b32 s39, s23, s56
	s_cselect_b32 s38, s54, s55
	v_lshl_add_u64 v[222:223], s[34:35], 0, v[138:139]
	s_add_i32 m0, s42, 0xc000
	ds_read_b128 v[190:193], v155
	ds_read_b128 v[194:197], v155 offset:1024
	ds_read_b128 v[198:201], v155 offset:2048
	ds_read_b128 v[202:205], v155 offset:3072
	ds_read_b128 v[206:209], v155 offset:4096
	ds_read_b128 v[210:213], v155 offset:5120
	ds_read_b128 v[214:217], v155 offset:6144
	ds_read_b128 v[218:221], v155 offset:7168
	global_load_lds_dwordx4 v[222:223], off
	s_add_i32 m0, s42, 0xe000
	v_lshl_add_u64 v[222:223], s[34:35], 0, v[140:141]
	global_load_lds_dwordx4 v[222:223], off
	s_waitcnt vmcnt(8)
	s_waitcnt lgkmcnt(0)
	s_barrier
	s_setprio 1
	s_waitcnt lgkmcnt(0)
	v_mfma_f32_16x16x32_bf16 v[126:129], v[146:149], v[190:193], 0
	v_mfma_f32_16x16x32_bf16 v[122:125], v[162:165], v[190:193], 0
	v_mfma_f32_16x16x32_bf16 v[110:113], v[146:149], v[198:201], 0
	v_mfma_f32_16x16x32_bf16 v[106:109], v[162:165], v[198:201], 0
	v_mfma_f32_16x16x32_bf16 v[94:97], v[146:149], v[206:209], 0
	v_mfma_f32_16x16x32_bf16 v[90:93], v[162:165], v[206:209], 0
	v_mfma_f32_16x16x32_bf16 v[78:81], v[146:149], v[214:217], 0
	v_mfma_f32_16x16x32_bf16 v[74:77], v[162:165], v[214:217], 0
	v_mfma_f32_16x16x32_bf16 v[126:129], v[158:161], v[194:197], v[126:129]
	v_mfma_f32_16x16x32_bf16 v[122:125], v[166:169], v[194:197], v[122:125]
	v_mfma_f32_16x16x32_bf16 v[110:113], v[158:161], v[202:205], v[110:113]
	v_mfma_f32_16x16x32_bf16 v[106:109], v[166:169], v[202:205], v[106:109]
	v_mfma_f32_16x16x32_bf16 v[94:97], v[158:161], v[210:213], v[94:97]
	v_mfma_f32_16x16x32_bf16 v[90:93], v[166:169], v[210:213], v[90:93]
	v_mfma_f32_16x16x32_bf16 v[78:81], v[158:161], v[218:221], v[78:81]
	v_mfma_f32_16x16x32_bf16 v[74:77], v[166:169], v[218:221], v[74:77]
	s_setprio 0
	s_setprio 1
	v_mfma_f32_16x16x32_bf16 v[118:121], v[170:173], v[190:193], 0
	v_mfma_f32_16x16x32_bf16 v[114:117], v[182:185], v[190:193], 0
	v_mfma_f32_16x16x32_bf16 v[102:105], v[170:173], v[198:201], 0
	v_mfma_f32_16x16x32_bf16 v[98:101], v[182:185], v[198:201], 0
	v_mfma_f32_16x16x32_bf16 v[86:89], v[170:173], v[206:209], 0
	v_mfma_f32_16x16x32_bf16 v[82:85], v[182:185], v[206:209], 0
	v_mfma_f32_16x16x32_bf16 v[70:73], v[170:173], v[214:217], 0
	v_mfma_f32_16x16x32_bf16 v[66:69], v[182:185], v[214:217], 0
	v_mfma_f32_16x16x32_bf16 v[118:121], v[178:181], v[194:197], v[118:121]
	v_mfma_f32_16x16x32_bf16 v[114:117], v[186:189], v[194:197], v[114:117]
	v_mfma_f32_16x16x32_bf16 v[102:105], v[178:181], v[202:205], v[102:105]
	v_mfma_f32_16x16x32_bf16 v[98:101], v[186:189], v[202:205], v[98:101]
	v_mfma_f32_16x16x32_bf16 v[86:89], v[178:181], v[210:213], v[86:89]
	v_mfma_f32_16x16x32_bf16 v[82:85], v[186:189], v[210:213], v[82:85]
	v_mfma_f32_16x16x32_bf16 v[70:73], v[178:181], v[218:221], v[70:73]
	v_mfma_f32_16x16x32_bf16 v[66:69], v[186:189], v[218:221], v[66:69]
	s_setprio 0
	s_barrier
	s_add_i32 s34, s51, s17
	v_lshl_add_u64 v[222:223], s[38:39], 0, v[132:133]
	s_mov_b32 m0, s34
	ds_read_b128 v[190:193], v155 offset:16384
	ds_read_b128 v[194:197], v155 offset:17408
	ds_read_b128 v[198:201], v155 offset:18432
	ds_read_b128 v[202:205], v155 offset:19456
	ds_read_b128 v[206:209], v155 offset:20480
	ds_read_b128 v[210:213], v155 offset:21504
	ds_read_b128 v[214:217], v155 offset:22528
	ds_read_b128 v[218:221], v155 offset:23552
	global_load_lds_dwordx4 v[222:223], off
	s_add_i32 m0, s34, 0x2000
	s_add_u32 s34, s38, 0x40000
	v_lshl_add_u64 v[224:225], s[38:39], 0, v[136:137]
	s_addc_u32 s35, s39, 0
	s_add_i32 s58, s52, s17
	global_load_lds_dwordx4 v[224:225], off
	v_lshl_add_u64 v[226:227], s[34:35], 0, v[132:133]
	s_mov_b32 m0, s58
	v_lshl_add_u64 v[228:229], s[40:41], 0, v[134:135]
	global_load_lds_dwordx4 v[226:227], off
	s_add_i32 m0, s58, 0x2000
	v_lshl_add_u64 v[226:227], s[34:35], 0, v[136:137]
	global_load_lds_dwordx4 v[226:227], off
	s_mov_b32 m0, s42
	v_lshl_add_u64 v[226:227], s[40:41], 0, v[130:131]
	global_load_lds_dwordx4 v[226:227], off
	s_mov_b32 m0, s43
	s_nop 0
	global_load_lds_dwordx4 v[228:229], off
	s_waitcnt vmcnt(8)
	s_waitcnt lgkmcnt(0)
	s_barrier
	s_setprio 1
	s_waitcnt lgkmcnt(0)
	v_mfma_f32_16x16x32_bf16 v[62:65], v[146:149], v[190:193], 0
	v_mfma_f32_16x16x32_bf16 v[58:61], v[162:165], v[190:193], 0
	v_mfma_f32_16x16x32_bf16 v[46:49], v[146:149], v[198:201], 0
	v_mfma_f32_16x16x32_bf16 v[42:45], v[162:165], v[198:201], 0
	v_mfma_f32_16x16x32_bf16 v[30:33], v[146:149], v[206:209], 0
	v_mfma_f32_16x16x32_bf16 v[26:29], v[162:165], v[206:209], 0
	v_mfma_f32_16x16x32_bf16 v[14:17], v[146:149], v[214:217], 0
	v_mfma_f32_16x16x32_bf16 v[10:13], v[162:165], v[214:217], 0
	v_mfma_f32_16x16x32_bf16 v[62:65], v[158:161], v[194:197], v[62:65]
	v_mfma_f32_16x16x32_bf16 v[58:61], v[166:169], v[194:197], v[58:61]
	v_mfma_f32_16x16x32_bf16 v[46:49], v[158:161], v[202:205], v[46:49]
	v_mfma_f32_16x16x32_bf16 v[42:45], v[166:169], v[202:205], v[42:45]
	v_mfma_f32_16x16x32_bf16 v[30:33], v[158:161], v[210:213], v[30:33]
	v_mfma_f32_16x16x32_bf16 v[26:29], v[166:169], v[210:213], v[26:29]
	v_mfma_f32_16x16x32_bf16 v[14:17], v[158:161], v[218:221], v[14:17]
	v_mfma_f32_16x16x32_bf16 v[10:13], v[166:169], v[218:221], v[10:13]
	s_setprio 0
	s_setprio 1
	v_mfma_f32_16x16x32_bf16 v[54:57], v[170:173], v[190:193], 0
	v_mfma_f32_16x16x32_bf16 v[50:53], v[182:185], v[190:193], 0
	v_mfma_f32_16x16x32_bf16 v[38:41], v[170:173], v[198:201], 0
	v_mfma_f32_16x16x32_bf16 v[34:37], v[182:185], v[198:201], 0
	v_mfma_f32_16x16x32_bf16 v[22:25], v[170:173], v[206:209], 0
	v_mfma_f32_16x16x32_bf16 v[18:21], v[182:185], v[206:209], 0
	v_mfma_f32_16x16x32_bf16 v[6:9], v[170:173], v[214:217], 0
	v_mfma_f32_16x16x32_bf16 v[2:5], v[182:185], v[214:217], 0
	v_mfma_f32_16x16x32_bf16 v[54:57], v[178:181], v[194:197], v[54:57]
	v_mfma_f32_16x16x32_bf16 v[50:53], v[186:189], v[194:197], v[50:53]
	v_mfma_f32_16x16x32_bf16 v[38:41], v[178:181], v[202:205], v[38:41]
	v_mfma_f32_16x16x32_bf16 v[34:37], v[186:189], v[202:205], v[34:37]
	v_mfma_f32_16x16x32_bf16 v[22:25], v[178:181], v[210:213], v[22:25]
	v_mfma_f32_16x16x32_bf16 v[18:21], v[186:189], v[210:213], v[18:21]
	v_mfma_f32_16x16x32_bf16 v[6:9], v[178:181], v[218:221], v[6:9]
	v_mfma_f32_16x16x32_bf16 v[2:5], v[186:189], v[218:221], v[2:5]
	s_setprio 0
	s_barrier
	s_add_i32 s58, 0, 0x18000
	v_add_u32_e32 v157, s58, v151
	s_add_i32 s59, 0, 0x1c000
	ds_read_b128 v[146:149], v157
	ds_read_b128 v[158:161], v157 offset:1024
	ds_read_b128 v[162:165], v157 offset:2048
	ds_read_b128 v[166:169], v157 offset:3072
	v_add_u32_e32 v157, s59, v151
	ds_read_b128 v[170:173], v157
	ds_read_b128 v[178:181], v157 offset:1024
	ds_read_b128 v[182:185], v157 offset:2048
	ds_read_b128 v[186:189], v157 offset:3072
	s_add_u32 s34, s40, 0x40000
	s_addc_u32 s35, s41, 0
	s_mov_b32 m0, s44
	v_lshl_add_u64 v[230:231], s[34:35], 0, v[130:131]
	ds_read_b128 v[190:193], v155 offset:32768
	ds_read_b128 v[194:197], v155 offset:33792
	ds_read_b128 v[198:201], v155 offset:34816
	ds_read_b128 v[202:205], v155 offset:35840
	ds_read_b128 v[206:209], v155 offset:36864
	ds_read_b128 v[210:213], v155 offset:37888
	ds_read_b128 v[214:217], v155 offset:38912
	ds_read_b128 v[218:221], v155 offset:39936
	global_load_lds_dwordx4 v[230:231], off
	s_mov_b32 m0, s45
	v_lshl_add_u64 v[230:231], s[34:35], 0, v[134:135]
	global_load_lds_dwordx4 v[230:231], off
	s_waitcnt vmcnt(8)
	s_waitcnt lgkmcnt(0)
	s_barrier
	s_setprio 1
	s_waitcnt lgkmcnt(0)
	v_mfma_f32_16x16x32_bf16 v[126:129], v[146:149], v[190:193], v[126:129]
	v_mfma_f32_16x16x32_bf16 v[122:125], v[162:165], v[190:193], v[122:125]
	v_mfma_f32_16x16x32_bf16 v[110:113], v[146:149], v[198:201], v[110:113]
	v_mfma_f32_16x16x32_bf16 v[106:109], v[162:165], v[198:201], v[106:109]
	v_mfma_f32_16x16x32_bf16 v[94:97], v[146:149], v[206:209], v[94:97]
	v_mfma_f32_16x16x32_bf16 v[90:93], v[162:165], v[206:209], v[90:93]
	v_mfma_f32_16x16x32_bf16 v[78:81], v[146:149], v[214:217], v[78:81]
	v_mfma_f32_16x16x32_bf16 v[74:77], v[162:165], v[214:217], v[74:77]
	v_mfma_f32_16x16x32_bf16 v[126:129], v[158:161], v[194:197], v[126:129]
	v_mfma_f32_16x16x32_bf16 v[122:125], v[166:169], v[194:197], v[122:125]
	v_mfma_f32_16x16x32_bf16 v[110:113], v[158:161], v[202:205], v[110:113]
	v_mfma_f32_16x16x32_bf16 v[106:109], v[166:169], v[202:205], v[106:109]
	v_mfma_f32_16x16x32_bf16 v[94:97], v[158:161], v[210:213], v[94:97]
	v_mfma_f32_16x16x32_bf16 v[90:93], v[166:169], v[210:213], v[90:93]
	v_mfma_f32_16x16x32_bf16 v[78:81], v[158:161], v[218:221], v[78:81]
	v_mfma_f32_16x16x32_bf16 v[74:77], v[166:169], v[218:221], v[74:77]
	s_setprio 0
	s_setprio 1
	v_mfma_f32_16x16x32_bf16 v[118:121], v[170:173], v[190:193], v[118:121]
	v_mfma_f32_16x16x32_bf16 v[114:117], v[182:185], v[190:193], v[114:117]
	v_mfma_f32_16x16x32_bf16 v[102:105], v[170:173], v[198:201], v[102:105]
	v_mfma_f32_16x16x32_bf16 v[98:101], v[182:185], v[198:201], v[98:101]
	v_mfma_f32_16x16x32_bf16 v[86:89], v[170:173], v[206:209], v[86:89]
	v_mfma_f32_16x16x32_bf16 v[82:85], v[182:185], v[206:209], v[82:85]
	v_mfma_f32_16x16x32_bf16 v[70:73], v[170:173], v[214:217], v[70:73]
	v_mfma_f32_16x16x32_bf16 v[66:69], v[182:185], v[214:217], v[66:69]
	v_mfma_f32_16x16x32_bf16 v[118:121], v[178:181], v[194:197], v[118:121]
	v_mfma_f32_16x16x32_bf16 v[114:117], v[186:189], v[194:197], v[114:117]
	v_mfma_f32_16x16x32_bf16 v[102:105], v[178:181], v[202:205], v[102:105]
	v_mfma_f32_16x16x32_bf16 v[98:101], v[186:189], v[202:205], v[98:101]
	v_mfma_f32_16x16x32_bf16 v[86:89], v[178:181], v[210:213], v[86:89]
	v_mfma_f32_16x16x32_bf16 v[82:85], v[186:189], v[210:213], v[82:85]
	v_mfma_f32_16x16x32_bf16 v[70:73], v[178:181], v[218:221], v[70:73]
	v_mfma_f32_16x16x32_bf16 v[66:69], v[186:189], v[218:221], v[66:69]
	s_setprio 0
	s_barrier
	s_add_i32 s34, s58, s17
	v_lshl_add_u64 v[222:223], v[222:223], 0, s[18:19]
	s_mov_b32 m0, s34
	ds_read_b128 v[190:193], v155 offset:49152
	ds_read_b128 v[194:197], v155 offset:50176
	ds_read_b128 v[198:201], v155 offset:51200
	ds_read_b128 v[202:205], v155 offset:52224
	ds_read_b128 v[206:209], v155 offset:53248
	ds_read_b128 v[210:213], v155 offset:54272
	ds_read_b128 v[214:217], v155 offset:55296
	ds_read_b128 v[218:221], v155 offset:56320
	global_load_lds_dwordx4 v[222:223], off
	s_add_i32 m0, s34, 0x2000
	s_add_u32 s34, s38, 0x40080
	v_lshl_add_u64 v[222:223], v[224:225], 0, s[18:19]
	s_addc_u32 s35, s39, 0
	s_add_i32 s38, s59, s17
	global_load_lds_dwordx4 v[222:223], off
	s_mov_b32 m0, s38
	v_lshl_add_u64 v[222:223], s[34:35], 0, v[132:133]
	global_load_lds_dwordx4 v[222:223], off
	s_add_i32 m0, s38, 0x2000
	v_lshl_add_u64 v[222:223], s[34:35], 0, v[136:137]
	global_load_lds_dwordx4 v[222:223], off
	s_mov_b32 m0, s47
	v_lshl_add_u64 v[222:223], v[226:227], 0, s[18:19]
	global_load_lds_dwordx4 v[222:223], off
	s_mov_b32 m0, s48
	v_lshl_add_u64 v[222:223], v[228:229], 0, s[18:19]
	global_load_lds_dwordx4 v[222:223], off
	s_waitcnt vmcnt(8)
	s_waitcnt lgkmcnt(0)
	s_barrier
	s_setprio 1
	s_waitcnt lgkmcnt(0)
	v_mfma_f32_16x16x32_bf16 v[62:65], v[146:149], v[190:193], v[62:65]
	v_mfma_f32_16x16x32_bf16 v[58:61], v[162:165], v[190:193], v[58:61]
	v_mfma_f32_16x16x32_bf16 v[46:49], v[146:149], v[198:201], v[46:49]
	v_mfma_f32_16x16x32_bf16 v[42:45], v[162:165], v[198:201], v[42:45]
	v_mfma_f32_16x16x32_bf16 v[30:33], v[146:149], v[206:209], v[30:33]
	v_mfma_f32_16x16x32_bf16 v[26:29], v[162:165], v[206:209], v[26:29]
	v_mfma_f32_16x16x32_bf16 v[14:17], v[146:149], v[214:217], v[14:17]
	v_mfma_f32_16x16x32_bf16 v[10:13], v[162:165], v[214:217], v[10:13]
	v_mfma_f32_16x16x32_bf16 v[62:65], v[158:161], v[194:197], v[62:65]
	v_mfma_f32_16x16x32_bf16 v[58:61], v[166:169], v[194:197], v[58:61]
	v_mfma_f32_16x16x32_bf16 v[46:49], v[158:161], v[202:205], v[46:49]
	v_mfma_f32_16x16x32_bf16 v[42:45], v[166:169], v[202:205], v[42:45]
	v_mfma_f32_16x16x32_bf16 v[30:33], v[158:161], v[210:213], v[30:33]
	v_mfma_f32_16x16x32_bf16 v[26:29], v[166:169], v[210:213], v[26:29]
	v_mfma_f32_16x16x32_bf16 v[14:17], v[158:161], v[218:221], v[14:17]
	v_mfma_f32_16x16x32_bf16 v[10:13], v[166:169], v[218:221], v[10:13]
	s_setprio 0
	s_setprio 1
	v_mfma_f32_16x16x32_bf16 v[54:57], v[170:173], v[190:193], v[54:57]
	v_mfma_f32_16x16x32_bf16 v[50:53], v[182:185], v[190:193], v[50:53]
	v_mfma_f32_16x16x32_bf16 v[38:41], v[170:173], v[198:201], v[38:41]
	v_mfma_f32_16x16x32_bf16 v[34:37], v[182:185], v[198:201], v[34:37]
	v_mfma_f32_16x16x32_bf16 v[22:25], v[170:173], v[206:209], v[22:25]
	v_mfma_f32_16x16x32_bf16 v[18:21], v[182:185], v[206:209], v[18:21]
	v_mfma_f32_16x16x32_bf16 v[6:9], v[170:173], v[214:217], v[6:9]
	v_mfma_f32_16x16x32_bf16 v[2:5], v[182:185], v[214:217], v[2:5]
	v_mfma_f32_16x16x32_bf16 v[54:57], v[178:181], v[194:197], v[54:57]
	v_mfma_f32_16x16x32_bf16 v[50:53], v[186:189], v[194:197], v[50:53]
	v_mfma_f32_16x16x32_bf16 v[38:41], v[178:181], v[202:205], v[38:41]
	v_mfma_f32_16x16x32_bf16 v[34:37], v[186:189], v[202:205], v[34:37]
	v_mfma_f32_16x16x32_bf16 v[22:25], v[178:181], v[210:213], v[22:25]
	v_mfma_f32_16x16x32_bf16 v[18:21], v[186:189], v[210:213], v[18:21]
	v_mfma_f32_16x16x32_bf16 v[6:9], v[178:181], v[218:221], v[6:9]
	v_mfma_f32_16x16x32_bf16 v[2:5], v[186:189], v[218:221], v[2:5]
	s_setprio 0
	s_barrier
	s_add_i32 s57, s57, 2
	s_add_u32 s55, s55, 0x100
	s_addc_u32 s56, s56, 0
	s_cmp_gt_u32 s57, 13
	s_mov_b64 s[34:35], s[36:37]
	s_cbranch_scc0 .LBB0_1496
	s_branch .Lpeel_exit_1496
.LBB0_1496:
	ds_read_b128 v[146:149], v153
	ds_read_b128 v[158:161], v153 offset:1024
	ds_read_b128 v[162:165], v153 offset:2048
	ds_read_b128 v[166:169], v153 offset:3072
	ds_read_b128 v[170:173], v154
	ds_read_b128 v[178:181], v154 offset:1024
	ds_read_b128 v[182:185], v154 offset:2048
	ds_read_b128 v[186:189], v154 offset:3072
	s_add_u32 s36, s34, 0x100
	s_addc_u32 s37, s35, 0
	s_cmp_eq_u32 s57, 12
	s_cselect_b32 s41, s25, s37
	s_cselect_b32 s40, s31, s36
	s_cselect_b32 s39, s23, s56
	s_cselect_b32 s38, s54, s55
	v_lshl_add_u64 v[222:223], s[34:35], 0, v[138:139]
	s_add_i32 m0, s42, 0xc000
	ds_read_b128 v[190:193], v155
	ds_read_b128 v[194:197], v155 offset:1024
	ds_read_b128 v[198:201], v155 offset:2048
	ds_read_b128 v[202:205], v155 offset:3072
	ds_read_b128 v[206:209], v155 offset:4096
	ds_read_b128 v[210:213], v155 offset:5120
	ds_read_b128 v[214:217], v155 offset:6144
	ds_read_b128 v[218:221], v155 offset:7168
	global_load_lds_dwordx4 v[222:223], off
	s_add_i32 m0, s42, 0xe000
	v_lshl_add_u64 v[222:223], s[34:35], 0, v[140:141]
	global_load_lds_dwordx4 v[222:223], off
	s_waitcnt vmcnt(8)
	s_waitcnt lgkmcnt(0)
	s_barrier
	s_setprio 1
	s_waitcnt lgkmcnt(0)
	v_mfma_f32_16x16x32_bf16 v[126:129], v[146:149], v[190:193], v[126:129]
	v_mfma_f32_16x16x32_bf16 v[122:125], v[162:165], v[190:193], v[122:125]
	v_mfma_f32_16x16x32_bf16 v[110:113], v[146:149], v[198:201], v[110:113]
	v_mfma_f32_16x16x32_bf16 v[106:109], v[162:165], v[198:201], v[106:109]
	v_mfma_f32_16x16x32_bf16 v[94:97], v[146:149], v[206:209], v[94:97]
	v_mfma_f32_16x16x32_bf16 v[90:93], v[162:165], v[206:209], v[90:93]
	v_mfma_f32_16x16x32_bf16 v[78:81], v[146:149], v[214:217], v[78:81]
	v_mfma_f32_16x16x32_bf16 v[74:77], v[162:165], v[214:217], v[74:77]
	v_mfma_f32_16x16x32_bf16 v[126:129], v[158:161], v[194:197], v[126:129]
	v_mfma_f32_16x16x32_bf16 v[122:125], v[166:169], v[194:197], v[122:125]
	v_mfma_f32_16x16x32_bf16 v[110:113], v[158:161], v[202:205], v[110:113]
	v_mfma_f32_16x16x32_bf16 v[106:109], v[166:169], v[202:205], v[106:109]
	v_mfma_f32_16x16x32_bf16 v[94:97], v[158:161], v[210:213], v[94:97]
	v_mfma_f32_16x16x32_bf16 v[90:93], v[166:169], v[210:213], v[90:93]
	v_mfma_f32_16x16x32_bf16 v[78:81], v[158:161], v[218:221], v[78:81]
	v_mfma_f32_16x16x32_bf16 v[74:77], v[166:169], v[218:221], v[74:77]
	s_setprio 0
	s_setprio 1
	v_mfma_f32_16x16x32_bf16 v[118:121], v[170:173], v[190:193], v[118:121]
	v_mfma_f32_16x16x32_bf16 v[114:117], v[182:185], v[190:193], v[114:117]
	v_mfma_f32_16x16x32_bf16 v[102:105], v[170:173], v[198:201], v[102:105]
	v_mfma_f32_16x16x32_bf16 v[98:101], v[182:185], v[198:201], v[98:101]
	v_mfma_f32_16x16x32_bf16 v[86:89], v[170:173], v[206:209], v[86:89]
	v_mfma_f32_16x16x32_bf16 v[82:85], v[182:185], v[206:209], v[82:85]
	v_mfma_f32_16x16x32_bf16 v[70:73], v[170:173], v[214:217], v[70:73]
	v_mfma_f32_16x16x32_bf16 v[66:69], v[182:185], v[214:217], v[66:69]
	v_mfma_f32_16x16x32_bf16 v[118:121], v[178:181], v[194:197], v[118:121]
	v_mfma_f32_16x16x32_bf16 v[114:117], v[186:189], v[194:197], v[114:117]
	v_mfma_f32_16x16x32_bf16 v[102:105], v[178:181], v[202:205], v[102:105]
	v_mfma_f32_16x16x32_bf16 v[98:101], v[186:189], v[202:205], v[98:101]
	v_mfma_f32_16x16x32_bf16 v[86:89], v[178:181], v[210:213], v[86:89]
	v_mfma_f32_16x16x32_bf16 v[82:85], v[186:189], v[210:213], v[82:85]
	v_mfma_f32_16x16x32_bf16 v[70:73], v[178:181], v[218:221], v[70:73]
	v_mfma_f32_16x16x32_bf16 v[66:69], v[186:189], v[218:221], v[66:69]
	s_setprio 0
	s_barrier
	s_add_i32 s34, s51, s17
	v_lshl_add_u64 v[222:223], s[38:39], 0, v[132:133]
	s_mov_b32 m0, s34
	ds_read_b128 v[190:193], v155 offset:16384
	ds_read_b128 v[194:197], v155 offset:17408
	ds_read_b128 v[198:201], v155 offset:18432
	ds_read_b128 v[202:205], v155 offset:19456
	ds_read_b128 v[206:209], v155 offset:20480
	ds_read_b128 v[210:213], v155 offset:21504
	ds_read_b128 v[214:217], v155 offset:22528
	ds_read_b128 v[218:221], v155 offset:23552
	global_load_lds_dwordx4 v[222:223], off
	s_add_i32 m0, s34, 0x2000
	s_add_u32 s34, s38, 0x40000
	v_lshl_add_u64 v[224:225], s[38:39], 0, v[136:137]
	s_addc_u32 s35, s39, 0
	s_add_i32 s58, s52, s17
	global_load_lds_dwordx4 v[224:225], off
	v_lshl_add_u64 v[226:227], s[34:35], 0, v[132:133]
	s_mov_b32 m0, s58
	v_lshl_add_u64 v[228:229], s[40:41], 0, v[134:135]
	global_load_lds_dwordx4 v[226:227], off
	s_add_i32 m0, s58, 0x2000
	v_lshl_add_u64 v[226:227], s[34:35], 0, v[136:137]
	global_load_lds_dwordx4 v[226:227], off
	s_mov_b32 m0, s42
	v_lshl_add_u64 v[226:227], s[40:41], 0, v[130:131]
	global_load_lds_dwordx4 v[226:227], off
	s_mov_b32 m0, s43
	s_nop 0
	global_load_lds_dwordx4 v[228:229], off
	s_waitcnt vmcnt(8)
	s_waitcnt lgkmcnt(0)
	s_barrier
	s_setprio 1
	s_waitcnt lgkmcnt(0)
	v_mfma_f32_16x16x32_bf16 v[62:65], v[146:149], v[190:193], v[62:65]
	v_mfma_f32_16x16x32_bf16 v[58:61], v[162:165], v[190:193], v[58:61]
	v_mfma_f32_16x16x32_bf16 v[46:49], v[146:149], v[198:201], v[46:49]
	v_mfma_f32_16x16x32_bf16 v[42:45], v[162:165], v[198:201], v[42:45]
	v_mfma_f32_16x16x32_bf16 v[30:33], v[146:149], v[206:209], v[30:33]
	v_mfma_f32_16x16x32_bf16 v[26:29], v[162:165], v[206:209], v[26:29]
	v_mfma_f32_16x16x32_bf16 v[14:17], v[146:149], v[214:217], v[14:17]
	v_mfma_f32_16x16x32_bf16 v[10:13], v[162:165], v[214:217], v[10:13]
	v_mfma_f32_16x16x32_bf16 v[62:65], v[158:161], v[194:197], v[62:65]
	v_mfma_f32_16x16x32_bf16 v[58:61], v[166:169], v[194:197], v[58:61]
	v_mfma_f32_16x16x32_bf16 v[46:49], v[158:161], v[202:205], v[46:49]
	v_mfma_f32_16x16x32_bf16 v[42:45], v[166:169], v[202:205], v[42:45]
	v_mfma_f32_16x16x32_bf16 v[30:33], v[158:161], v[210:213], v[30:33]
	v_mfma_f32_16x16x32_bf16 v[26:29], v[166:169], v[210:213], v[26:29]
	v_mfma_f32_16x16x32_bf16 v[14:17], v[158:161], v[218:221], v[14:17]
	v_mfma_f32_16x16x32_bf16 v[10:13], v[166:169], v[218:221], v[10:13]
	s_setprio 0
	s_setprio 1
	v_mfma_f32_16x16x32_bf16 v[54:57], v[170:173], v[190:193], v[54:57]
	v_mfma_f32_16x16x32_bf16 v[50:53], v[182:185], v[190:193], v[50:53]
	v_mfma_f32_16x16x32_bf16 v[38:41], v[170:173], v[198:201], v[38:41]
	v_mfma_f32_16x16x32_bf16 v[34:37], v[182:185], v[198:201], v[34:37]
	v_mfma_f32_16x16x32_bf16 v[22:25], v[170:173], v[206:209], v[22:25]
	v_mfma_f32_16x16x32_bf16 v[18:21], v[182:185], v[206:209], v[18:21]
	v_mfma_f32_16x16x32_bf16 v[6:9], v[170:173], v[214:217], v[6:9]
	v_mfma_f32_16x16x32_bf16 v[2:5], v[182:185], v[214:217], v[2:5]
	v_mfma_f32_16x16x32_bf16 v[54:57], v[178:181], v[194:197], v[54:57]
	v_mfma_f32_16x16x32_bf16 v[50:53], v[186:189], v[194:197], v[50:53]
	v_mfma_f32_16x16x32_bf16 v[38:41], v[178:181], v[202:205], v[38:41]
	v_mfma_f32_16x16x32_bf16 v[34:37], v[186:189], v[202:205], v[34:37]
	v_mfma_f32_16x16x32_bf16 v[22:25], v[178:181], v[210:213], v[22:25]
	v_mfma_f32_16x16x32_bf16 v[18:21], v[186:189], v[210:213], v[18:21]
	v_mfma_f32_16x16x32_bf16 v[6:9], v[178:181], v[218:221], v[6:9]
	v_mfma_f32_16x16x32_bf16 v[2:5], v[186:189], v[218:221], v[2:5]
	s_setprio 0
	s_barrier
	s_add_i32 s58, 0, 0x18000
	v_add_u32_e32 v157, s58, v151
	s_add_i32 s59, 0, 0x1c000
	ds_read_b128 v[146:149], v157
	ds_read_b128 v[158:161], v157 offset:1024
	ds_read_b128 v[162:165], v157 offset:2048
	ds_read_b128 v[166:169], v157 offset:3072
	v_add_u32_e32 v157, s59, v151
	ds_read_b128 v[170:173], v157
	ds_read_b128 v[178:181], v157 offset:1024
	ds_read_b128 v[182:185], v157 offset:2048
	ds_read_b128 v[186:189], v157 offset:3072
	s_add_u32 s34, s40, 0x40000
	s_addc_u32 s35, s41, 0
	s_mov_b32 m0, s44
	v_lshl_add_u64 v[230:231], s[34:35], 0, v[130:131]
	ds_read_b128 v[190:193], v155 offset:32768
	ds_read_b128 v[194:197], v155 offset:33792
	ds_read_b128 v[198:201], v155 offset:34816
	ds_read_b128 v[202:205], v155 offset:35840
	ds_read_b128 v[206:209], v155 offset:36864
	ds_read_b128 v[210:213], v155 offset:37888
	ds_read_b128 v[214:217], v155 offset:38912
	ds_read_b128 v[218:221], v155 offset:39936
	global_load_lds_dwordx4 v[230:231], off
	s_mov_b32 m0, s45
	v_lshl_add_u64 v[230:231], s[34:35], 0, v[134:135]
	global_load_lds_dwordx4 v[230:231], off
	s_waitcnt vmcnt(8)
	s_waitcnt lgkmcnt(0)
	s_barrier
	s_setprio 1
	s_waitcnt lgkmcnt(0)
	v_mfma_f32_16x16x32_bf16 v[126:129], v[146:149], v[190:193], v[126:129]
	v_mfma_f32_16x16x32_bf16 v[122:125], v[162:165], v[190:193], v[122:125]
	v_mfma_f32_16x16x32_bf16 v[110:113], v[146:149], v[198:201], v[110:113]
	v_mfma_f32_16x16x32_bf16 v[106:109], v[162:165], v[198:201], v[106:109]
	v_mfma_f32_16x16x32_bf16 v[94:97], v[146:149], v[206:209], v[94:97]
	v_mfma_f32_16x16x32_bf16 v[90:93], v[162:165], v[206:209], v[90:93]
	v_mfma_f32_16x16x32_bf16 v[78:81], v[146:149], v[214:217], v[78:81]
	v_mfma_f32_16x16x32_bf16 v[74:77], v[162:165], v[214:217], v[74:77]
	v_mfma_f32_16x16x32_bf16 v[126:129], v[158:161], v[194:197], v[126:129]
	v_mfma_f32_16x16x32_bf16 v[122:125], v[166:169], v[194:197], v[122:125]
	v_mfma_f32_16x16x32_bf16 v[110:113], v[158:161], v[202:205], v[110:113]
	v_mfma_f32_16x16x32_bf16 v[106:109], v[166:169], v[202:205], v[106:109]
	v_mfma_f32_16x16x32_bf16 v[94:97], v[158:161], v[210:213], v[94:97]
	v_mfma_f32_16x16x32_bf16 v[90:93], v[166:169], v[210:213], v[90:93]
	v_mfma_f32_16x16x32_bf16 v[78:81], v[158:161], v[218:221], v[78:81]
	v_mfma_f32_16x16x32_bf16 v[74:77], v[166:169], v[218:221], v[74:77]
	s_setprio 0
	s_setprio 1
	v_mfma_f32_16x16x32_bf16 v[118:121], v[170:173], v[190:193], v[118:121]
	v_mfma_f32_16x16x32_bf16 v[114:117], v[182:185], v[190:193], v[114:117]
	v_mfma_f32_16x16x32_bf16 v[102:105], v[170:173], v[198:201], v[102:105]
	v_mfma_f32_16x16x32_bf16 v[98:101], v[182:185], v[198:201], v[98:101]
	v_mfma_f32_16x16x32_bf16 v[86:89], v[170:173], v[206:209], v[86:89]
	v_mfma_f32_16x16x32_bf16 v[82:85], v[182:185], v[206:209], v[82:85]
	v_mfma_f32_16x16x32_bf16 v[70:73], v[170:173], v[214:217], v[70:73]
	v_mfma_f32_16x16x32_bf16 v[66:69], v[182:185], v[214:217], v[66:69]
	v_mfma_f32_16x16x32_bf16 v[118:121], v[178:181], v[194:197], v[118:121]
	v_mfma_f32_16x16x32_bf16 v[114:117], v[186:189], v[194:197], v[114:117]
	v_mfma_f32_16x16x32_bf16 v[102:105], v[178:181], v[202:205], v[102:105]
	v_mfma_f32_16x16x32_bf16 v[98:101], v[186:189], v[202:205], v[98:101]
	v_mfma_f32_16x16x32_bf16 v[86:89], v[178:181], v[210:213], v[86:89]
	v_mfma_f32_16x16x32_bf16 v[82:85], v[186:189], v[210:213], v[82:85]
	v_mfma_f32_16x16x32_bf16 v[70:73], v[178:181], v[218:221], v[70:73]
	v_mfma_f32_16x16x32_bf16 v[66:69], v[186:189], v[218:221], v[66:69]
	s_setprio 0
	s_barrier
	s_add_i32 s34, s58, s17
	v_lshl_add_u64 v[222:223], v[222:223], 0, s[18:19]
	s_mov_b32 m0, s34
	ds_read_b128 v[190:193], v155 offset:49152
	ds_read_b128 v[194:197], v155 offset:50176
	ds_read_b128 v[198:201], v155 offset:51200
	ds_read_b128 v[202:205], v155 offset:52224
	ds_read_b128 v[206:209], v155 offset:53248
	ds_read_b128 v[210:213], v155 offset:54272
	ds_read_b128 v[214:217], v155 offset:55296
	ds_read_b128 v[218:221], v155 offset:56320
	global_load_lds_dwordx4 v[222:223], off
	s_add_i32 m0, s34, 0x2000
	s_add_u32 s34, s38, 0x40080
	v_lshl_add_u64 v[222:223], v[224:225], 0, s[18:19]
	s_addc_u32 s35, s39, 0
	s_add_i32 s38, s59, s17
	global_load_lds_dwordx4 v[222:223], off
	s_mov_b32 m0, s38
	v_lshl_add_u64 v[222:223], s[34:35], 0, v[132:133]
	global_load_lds_dwordx4 v[222:223], off
	s_add_i32 m0, s38, 0x2000
	v_lshl_add_u64 v[222:223], s[34:35], 0, v[136:137]
	global_load_lds_dwordx4 v[222:223], off
	s_mov_b32 m0, s47
	v_lshl_add_u64 v[222:223], v[226:227], 0, s[18:19]
	global_load_lds_dwordx4 v[222:223], off
	s_mov_b32 m0, s48
	v_lshl_add_u64 v[222:223], v[228:229], 0, s[18:19]
	global_load_lds_dwordx4 v[222:223], off
	s_waitcnt vmcnt(8)
	s_waitcnt lgkmcnt(0)
	s_barrier
	s_setprio 1
	s_waitcnt lgkmcnt(0)
	v_mfma_f32_16x16x32_bf16 v[62:65], v[146:149], v[190:193], v[62:65]
	v_mfma_f32_16x16x32_bf16 v[58:61], v[162:165], v[190:193], v[58:61]
	v_mfma_f32_16x16x32_bf16 v[46:49], v[146:149], v[198:201], v[46:49]
	v_mfma_f32_16x16x32_bf16 v[42:45], v[162:165], v[198:201], v[42:45]
	v_mfma_f32_16x16x32_bf16 v[30:33], v[146:149], v[206:209], v[30:33]
	v_mfma_f32_16x16x32_bf16 v[26:29], v[162:165], v[206:209], v[26:29]
	v_mfma_f32_16x16x32_bf16 v[14:17], v[146:149], v[214:217], v[14:17]
	v_mfma_f32_16x16x32_bf16 v[10:13], v[162:165], v[214:217], v[10:13]
	v_mfma_f32_16x16x32_bf16 v[62:65], v[158:161], v[194:197], v[62:65]
	v_mfma_f32_16x16x32_bf16 v[58:61], v[166:169], v[194:197], v[58:61]
	v_mfma_f32_16x16x32_bf16 v[46:49], v[158:161], v[202:205], v[46:49]
	v_mfma_f32_16x16x32_bf16 v[42:45], v[166:169], v[202:205], v[42:45]
	v_mfma_f32_16x16x32_bf16 v[30:33], v[158:161], v[210:213], v[30:33]
	v_mfma_f32_16x16x32_bf16 v[26:29], v[166:169], v[210:213], v[26:29]
	v_mfma_f32_16x16x32_bf16 v[14:17], v[158:161], v[218:221], v[14:17]
	v_mfma_f32_16x16x32_bf16 v[10:13], v[166:169], v[218:221], v[10:13]
	s_setprio 0
	s_setprio 1
	v_mfma_f32_16x16x32_bf16 v[54:57], v[170:173], v[190:193], v[54:57]
	v_mfma_f32_16x16x32_bf16 v[50:53], v[182:185], v[190:193], v[50:53]
	v_mfma_f32_16x16x32_bf16 v[38:41], v[170:173], v[198:201], v[38:41]
	v_mfma_f32_16x16x32_bf16 v[34:37], v[182:185], v[198:201], v[34:37]
	v_mfma_f32_16x16x32_bf16 v[22:25], v[170:173], v[206:209], v[22:25]
	v_mfma_f32_16x16x32_bf16 v[18:21], v[182:185], v[206:209], v[18:21]
	v_mfma_f32_16x16x32_bf16 v[6:9], v[170:173], v[214:217], v[6:9]
	v_mfma_f32_16x16x32_bf16 v[2:5], v[182:185], v[214:217], v[2:5]
	v_mfma_f32_16x16x32_bf16 v[54:57], v[178:181], v[194:197], v[54:57]
	v_mfma_f32_16x16x32_bf16 v[50:53], v[186:189], v[194:197], v[50:53]
	v_mfma_f32_16x16x32_bf16 v[38:41], v[178:181], v[202:205], v[38:41]
	v_mfma_f32_16x16x32_bf16 v[34:37], v[186:189], v[202:205], v[34:37]
	v_mfma_f32_16x16x32_bf16 v[22:25], v[178:181], v[210:213], v[22:25]
	v_mfma_f32_16x16x32_bf16 v[18:21], v[186:189], v[210:213], v[18:21]
	v_mfma_f32_16x16x32_bf16 v[6:9], v[178:181], v[218:221], v[6:9]
	v_mfma_f32_16x16x32_bf16 v[2:5], v[186:189], v[218:221], v[2:5]
	s_setprio 0
	s_barrier
	s_add_i32 s57, s57, 2
	s_add_u32 s55, s55, 0x100
	s_addc_u32 s56, s56, 0
	s_cmp_gt_u32 s57, 13
	s_mov_b64 s[34:35], s[36:37]
	s_cbranch_scc0 .LBB0_1496

.LBB0_1589:
	s_ashr_i32 s21, s20, 31
	s_lshl_b64 s[22:23], s[20:21], 19
	s_add_u32 s22, s14, s22
	s_addc_u32 s23, s15, s23
	s_and_b64 s[24:25], s[0:1], exec
	s_cselect_b32 s21, s23, s27
	s_cselect_b32 s49, s22, s26
	s_ashr_i32 s19, s18, 31
	s_lshl_b64 s[24:25], s[18:19], 19
	s_add_u32 s24, s16, s24
	s_addc_u32 s25, s17, s25
	s_and_b64 s[30:31], s[0:1], exec
	s_cselect_b32 s19, s25, s29
	s_cselect_b32 s50, s24, s28
	s_add_u32 s51, s28, 0x100
	s_addc_u32 s52, s29, 0
	s_mov_b32 s53, -2
	s_waitcnt vmcnt(0)
	ds_read_b128 v[146:149], v155
	ds_read_b128 v[160:163], v155 offset:1024
	ds_read_b128 v[164:167], v155 offset:2048
	ds_read_b128 v[168:171], v155 offset:3072
	ds_read_b128 v[178:181], v156
	ds_read_b128 v[182:185], v156 offset:1024
	ds_read_b128 v[186:189], v156 offset:2048
	ds_read_b128 v[190:193], v156 offset:3072
	s_add_u32 s28, s26, 0x100
	s_addc_u32 s29, s27, 0
	s_cmp_eq_u32 s53, 12
	s_cselect_b32 s35, s21, s29
	s_cselect_b32 s34, s49, s28
	s_cselect_b32 s31, s19, s52
	s_cselect_b32 s30, s50, s51
	v_lshl_add_u64 v[150:151], s[26:27], 0, v[138:139]
	s_add_i32 m0, s37, 0xc000
	ds_read_b128 v[194:197], v157
	ds_read_b128 v[198:201], v157 offset:1024
	ds_read_b128 v[202:205], v157 offset:2048
	ds_read_b128 v[206:209], v157 offset:3072
	ds_read_b128 v[210:213], v157 offset:4096
	ds_read_b128 v[214:217], v157 offset:5120
	ds_read_b128 v[218:221], v157 offset:6144
	ds_read_b128 v[222:225], v157 offset:7168
	global_load_lds_dwordx4 v[150:151], off
	s_add_i32 m0, s37, 0xe000
	v_lshl_add_u64 v[150:151], s[26:27], 0, v[140:141]
	global_load_lds_dwordx4 v[150:151], off
	s_waitcnt vmcnt(8)
	s_waitcnt lgkmcnt(0)
	s_barrier
	s_setprio 1
	s_waitcnt lgkmcnt(0)
	v_mfma_f32_16x16x32_bf16 v[126:129], v[146:149], v[194:197], 0
	v_mfma_f32_16x16x32_bf16 v[122:125], v[164:167], v[194:197], 0
	v_mfma_f32_16x16x32_bf16 v[110:113], v[146:149], v[202:205], 0
	v_mfma_f32_16x16x32_bf16 v[106:109], v[164:167], v[202:205], 0
	v_mfma_f32_16x16x32_bf16 v[94:97], v[146:149], v[210:213], 0
	v_mfma_f32_16x16x32_bf16 v[90:93], v[164:167], v[210:213], 0
	v_mfma_f32_16x16x32_bf16 v[78:81], v[146:149], v[218:221], 0
	v_mfma_f32_16x16x32_bf16 v[74:77], v[164:167], v[218:221], 0
	v_mfma_f32_16x16x32_bf16 v[126:129], v[160:163], v[198:201], v[126:129]
	v_mfma_f32_16x16x32_bf16 v[122:125], v[168:171], v[198:201], v[122:125]
	v_mfma_f32_16x16x32_bf16 v[110:113], v[160:163], v[206:209], v[110:113]
	v_mfma_f32_16x16x32_bf16 v[106:109], v[168:171], v[206:209], v[106:109]
	v_mfma_f32_16x16x32_bf16 v[94:97], v[160:163], v[214:217], v[94:97]
	v_mfma_f32_16x16x32_bf16 v[90:93], v[168:171], v[214:217], v[90:93]
	v_mfma_f32_16x16x32_bf16 v[78:81], v[160:163], v[222:225], v[78:81]
	v_mfma_f32_16x16x32_bf16 v[74:77], v[168:171], v[222:225], v[74:77]
	s_setprio 0
	s_setprio 1
	v_mfma_f32_16x16x32_bf16 v[118:121], v[178:181], v[194:197], 0
	v_mfma_f32_16x16x32_bf16 v[114:117], v[186:189], v[194:197], 0
	v_mfma_f32_16x16x32_bf16 v[102:105], v[178:181], v[202:205], 0
	v_mfma_f32_16x16x32_bf16 v[98:101], v[186:189], v[202:205], 0
	v_mfma_f32_16x16x32_bf16 v[86:89], v[178:181], v[210:213], 0
	v_mfma_f32_16x16x32_bf16 v[82:85], v[186:189], v[210:213], 0
	v_mfma_f32_16x16x32_bf16 v[70:73], v[178:181], v[218:221], 0
	v_mfma_f32_16x16x32_bf16 v[66:69], v[186:189], v[218:221], 0
	v_mfma_f32_16x16x32_bf16 v[118:121], v[182:185], v[198:201], v[118:121]
	v_mfma_f32_16x16x32_bf16 v[114:117], v[190:193], v[198:201], v[114:117]
	v_mfma_f32_16x16x32_bf16 v[102:105], v[182:185], v[206:209], v[102:105]
	v_mfma_f32_16x16x32_bf16 v[98:101], v[190:193], v[206:209], v[98:101]
	v_mfma_f32_16x16x32_bf16 v[86:89], v[182:185], v[214:217], v[86:89]
	v_mfma_f32_16x16x32_bf16 v[82:85], v[190:193], v[214:217], v[82:85]
	v_mfma_f32_16x16x32_bf16 v[70:73], v[182:185], v[222:225], v[70:73]
	v_mfma_f32_16x16x32_bf16 v[66:69], v[190:193], v[222:225], v[66:69]
	s_setprio 0
	s_barrier
	s_add_i32 s26, s45, s36
	v_lshl_add_u64 v[150:151], s[30:31], 0, v[132:133]
	s_mov_b32 m0, s26
	ds_read_b128 v[194:197], v157 offset:16384
	ds_read_b128 v[198:201], v157 offset:17408
	ds_read_b128 v[202:205], v157 offset:18432
	ds_read_b128 v[206:209], v157 offset:19456
	ds_read_b128 v[210:213], v157 offset:20480
	ds_read_b128 v[214:217], v157 offset:21504
	ds_read_b128 v[218:221], v157 offset:22528
	ds_read_b128 v[222:225], v157 offset:23552
	global_load_lds_dwordx4 v[150:151], off
	s_add_i32 m0, s26, 0x2000
	s_add_u32 s26, s30, 0x40000
	v_lshl_add_u64 v[172:173], s[30:31], 0, v[136:137]
	s_addc_u32 s27, s31, 0
	s_add_i32 s54, s46, s36
	global_load_lds_dwordx4 v[172:173], off
	v_lshl_add_u64 v[226:227], s[26:27], 0, v[132:133]
	s_mov_b32 m0, s54
	v_lshl_add_u64 v[228:229], s[34:35], 0, v[134:135]
	global_load_lds_dwordx4 v[226:227], off
	s_add_i32 m0, s54, 0x2000
	v_lshl_add_u64 v[226:227], s[26:27], 0, v[136:137]
	global_load_lds_dwordx4 v[226:227], off
	s_mov_b32 m0, s37
	v_lshl_add_u64 v[226:227], s[34:35], 0, v[130:131]
	global_load_lds_dwordx4 v[226:227], off
	s_mov_b32 m0, s38
	s_nop 0
	global_load_lds_dwordx4 v[228:229], off
	s_waitcnt vmcnt(8)
	s_waitcnt lgkmcnt(0)
	s_barrier
	s_setprio 1
	s_waitcnt lgkmcnt(0)
	v_mfma_f32_16x16x32_bf16 v[62:65], v[146:149], v[194:197], 0
	v_mfma_f32_16x16x32_bf16 v[58:61], v[164:167], v[194:197], 0
	v_mfma_f32_16x16x32_bf16 v[46:49], v[146:149], v[202:205], 0
	v_mfma_f32_16x16x32_bf16 v[42:45], v[164:167], v[202:205], 0
	v_mfma_f32_16x16x32_bf16 v[30:33], v[146:149], v[210:213], 0
	v_mfma_f32_16x16x32_bf16 v[26:29], v[164:167], v[210:213], 0
	v_mfma_f32_16x16x32_bf16 v[14:17], v[146:149], v[218:221], 0
	v_mfma_f32_16x16x32_bf16 v[10:13], v[164:167], v[218:221], 0
	v_mfma_f32_16x16x32_bf16 v[62:65], v[160:163], v[198:201], v[62:65]
	v_mfma_f32_16x16x32_bf16 v[58:61], v[168:171], v[198:201], v[58:61]
	v_mfma_f32_16x16x32_bf16 v[46:49], v[160:163], v[206:209], v[46:49]
	v_mfma_f32_16x16x32_bf16 v[42:45], v[168:171], v[206:209], v[42:45]
	v_mfma_f32_16x16x32_bf16 v[30:33], v[160:163], v[214:217], v[30:33]
	v_mfma_f32_16x16x32_bf16 v[26:29], v[168:171], v[214:217], v[26:29]
	v_mfma_f32_16x16x32_bf16 v[14:17], v[160:163], v[222:225], v[14:17]
	v_mfma_f32_16x16x32_bf16 v[10:13], v[168:171], v[222:225], v[10:13]
	s_setprio 0
	s_setprio 1
	v_mfma_f32_16x16x32_bf16 v[54:57], v[178:181], v[194:197], 0
	v_mfma_f32_16x16x32_bf16 v[50:53], v[186:189], v[194:197], 0
	v_mfma_f32_16x16x32_bf16 v[38:41], v[178:181], v[202:205], 0
	v_mfma_f32_16x16x32_bf16 v[34:37], v[186:189], v[202:205], 0
	v_mfma_f32_16x16x32_bf16 v[22:25], v[178:181], v[210:213], 0
	v_mfma_f32_16x16x32_bf16 v[18:21], v[186:189], v[210:213], 0
	v_mfma_f32_16x16x32_bf16 v[6:9], v[178:181], v[218:221], 0
	v_mfma_f32_16x16x32_bf16 v[2:5], v[186:189], v[218:221], 0
	v_mfma_f32_16x16x32_bf16 v[54:57], v[182:185], v[198:201], v[54:57]
	v_mfma_f32_16x16x32_bf16 v[50:53], v[190:193], v[198:201], v[50:53]
	v_mfma_f32_16x16x32_bf16 v[38:41], v[182:185], v[206:209], v[38:41]
	v_mfma_f32_16x16x32_bf16 v[34:37], v[190:193], v[206:209], v[34:37]
	v_mfma_f32_16x16x32_bf16 v[22:25], v[182:185], v[214:217], v[22:25]
	v_mfma_f32_16x16x32_bf16 v[18:21], v[190:193], v[214:217], v[18:21]
	v_mfma_f32_16x16x32_bf16 v[6:9], v[182:185], v[222:225], v[6:9]
	v_mfma_f32_16x16x32_bf16 v[2:5], v[190:193], v[222:225], v[2:5]
	s_setprio 0
	s_barrier
	s_add_i32 s54, 0, 0x18000
	s_add_i32 s55, 0, 0x1c000
	v_add_u32_e32 v168, s54, v153
	v_add_u32_e32 v177, s55, v153
	ds_read_b128 v[146:149], v168
	ds_read_b128 v[160:163], v168 offset:1024
	ds_read_b128 v[164:167], v168 offset:2048
	ds_read_b128 v[168:171], v168 offset:3072
	ds_read_b128 v[178:181], v177
	ds_read_b128 v[182:185], v177 offset:1024
	ds_read_b128 v[186:189], v177 offset:2048
	ds_read_b128 v[190:193], v177 offset:3072
	s_add_u32 s26, s34, 0x40000
	s_addc_u32 s27, s35, 0
	s_mov_b32 m0, s39
	v_lshl_add_u64 v[230:231], s[26:27], 0, v[130:131]
	ds_read_b128 v[194:197], v157 offset:32768
	ds_read_b128 v[198:201], v157 offset:33792
	ds_read_b128 v[202:205], v157 offset:34816
	ds_read_b128 v[206:209], v157 offset:35840
	ds_read_b128 v[210:213], v157 offset:36864
	ds_read_b128 v[214:217], v157 offset:37888
	ds_read_b128 v[218:221], v157 offset:38912
	ds_read_b128 v[222:225], v157 offset:39936
	global_load_lds_dwordx4 v[230:231], off
	s_mov_b32 m0, s40
	v_lshl_add_u64 v[230:231], s[26:27], 0, v[134:135]
	global_load_lds_dwordx4 v[230:231], off
	s_waitcnt vmcnt(8)
	s_waitcnt lgkmcnt(0)
	s_barrier
	s_setprio 1
	s_waitcnt lgkmcnt(0)
	v_mfma_f32_16x16x32_bf16 v[126:129], v[146:149], v[194:197], v[126:129]
	v_mfma_f32_16x16x32_bf16 v[122:125], v[164:167], v[194:197], v[122:125]
	v_mfma_f32_16x16x32_bf16 v[110:113], v[146:149], v[202:205], v[110:113]
	v_mfma_f32_16x16x32_bf16 v[106:109], v[164:167], v[202:205], v[106:109]
	v_mfma_f32_16x16x32_bf16 v[94:97], v[146:149], v[210:213], v[94:97]
	v_mfma_f32_16x16x32_bf16 v[90:93], v[164:167], v[210:213], v[90:93]
	v_mfma_f32_16x16x32_bf16 v[78:81], v[146:149], v[218:221], v[78:81]
	v_mfma_f32_16x16x32_bf16 v[74:77], v[164:167], v[218:221], v[74:77]
	v_mfma_f32_16x16x32_bf16 v[126:129], v[160:163], v[198:201], v[126:129]
	v_mfma_f32_16x16x32_bf16 v[122:125], v[168:171], v[198:201], v[122:125]
	v_mfma_f32_16x16x32_bf16 v[110:113], v[160:163], v[206:209], v[110:113]
	v_mfma_f32_16x16x32_bf16 v[106:109], v[168:171], v[206:209], v[106:109]
	v_mfma_f32_16x16x32_bf16 v[94:97], v[160:163], v[214:217], v[94:97]
	v_mfma_f32_16x16x32_bf16 v[90:93], v[168:171], v[214:217], v[90:93]
	v_mfma_f32_16x16x32_bf16 v[78:81], v[160:163], v[222:225], v[78:81]
	v_mfma_f32_16x16x32_bf16 v[74:77], v[168:171], v[222:225], v[74:77]
	s_setprio 0
	s_setprio 1
	v_mfma_f32_16x16x32_bf16 v[118:121], v[178:181], v[194:197], v[118:121]
	v_mfma_f32_16x16x32_bf16 v[114:117], v[186:189], v[194:197], v[114:117]
	v_mfma_f32_16x16x32_bf16 v[102:105], v[178:181], v[202:205], v[102:105]
	v_mfma_f32_16x16x32_bf16 v[98:101], v[186:189], v[202:205], v[98:101]
	v_mfma_f32_16x16x32_bf16 v[86:89], v[178:181], v[210:213], v[86:89]
	v_mfma_f32_16x16x32_bf16 v[82:85], v[186:189], v[210:213], v[82:85]
	v_mfma_f32_16x16x32_bf16 v[70:73], v[178:181], v[218:221], v[70:73]
	v_mfma_f32_16x16x32_bf16 v[66:69], v[186:189], v[218:221], v[66:69]
	v_mfma_f32_16x16x32_bf16 v[118:121], v[182:185], v[198:201], v[118:121]
	v_mfma_f32_16x16x32_bf16 v[114:117], v[190:193], v[198:201], v[114:117]
	v_mfma_f32_16x16x32_bf16 v[102:105], v[182:185], v[206:209], v[102:105]
	v_mfma_f32_16x16x32_bf16 v[98:101], v[190:193], v[206:209], v[98:101]
	v_mfma_f32_16x16x32_bf16 v[86:89], v[182:185], v[214:217], v[86:89]
	v_mfma_f32_16x16x32_bf16 v[82:85], v[190:193], v[214:217], v[82:85]
	v_mfma_f32_16x16x32_bf16 v[70:73], v[182:185], v[222:225], v[70:73]
	v_mfma_f32_16x16x32_bf16 v[66:69], v[190:193], v[222:225], v[66:69]
	s_setprio 0
	s_barrier
	s_add_i32 s26, s54, s36
	v_lshl_add_u64 v[150:151], v[150:151], 0, s[10:11]
	s_mov_b32 m0, s26
	ds_read_b128 v[194:197], v157 offset:49152
	ds_read_b128 v[198:201], v157 offset:50176
	ds_read_b128 v[202:205], v157 offset:51200
	ds_read_b128 v[206:209], v157 offset:52224
	ds_read_b128 v[210:213], v157 offset:53248
	ds_read_b128 v[214:217], v157 offset:54272
	ds_read_b128 v[218:221], v157 offset:55296
	ds_read_b128 v[222:225], v157 offset:56320
	global_load_lds_dwordx4 v[150:151], off
	s_add_i32 m0, s26, 0x2000
	s_add_u32 s26, s30, 0x40080
	v_lshl_add_u64 v[150:151], v[172:173], 0, s[10:11]
	s_addc_u32 s27, s31, 0
	s_add_i32 s30, s55, s36
	global_load_lds_dwordx4 v[150:151], off
	s_mov_b32 m0, s30
	v_lshl_add_u64 v[150:151], s[26:27], 0, v[132:133]
	global_load_lds_dwordx4 v[150:151], off
	s_add_i32 m0, s30, 0x2000
	v_lshl_add_u64 v[150:151], s[26:27], 0, v[136:137]
	global_load_lds_dwordx4 v[150:151], off
	s_mov_b32 m0, s42
	v_lshl_add_u64 v[150:151], v[226:227], 0, s[10:11]
	global_load_lds_dwordx4 v[150:151], off
	s_mov_b32 m0, s43
	v_lshl_add_u64 v[150:151], v[228:229], 0, s[10:11]
	global_load_lds_dwordx4 v[150:151], off
	s_waitcnt vmcnt(8)
	s_waitcnt lgkmcnt(0)
	s_barrier
	s_setprio 1
	s_waitcnt lgkmcnt(0)
	v_mfma_f32_16x16x32_bf16 v[62:65], v[146:149], v[194:197], v[62:65]
	v_mfma_f32_16x16x32_bf16 v[58:61], v[164:167], v[194:197], v[58:61]
	v_mfma_f32_16x16x32_bf16 v[46:49], v[146:149], v[202:205], v[46:49]
	v_mfma_f32_16x16x32_bf16 v[42:45], v[164:167], v[202:205], v[42:45]
	v_mfma_f32_16x16x32_bf16 v[30:33], v[146:149], v[210:213], v[30:33]
	v_mfma_f32_16x16x32_bf16 v[26:29], v[164:167], v[210:213], v[26:29]
	v_mfma_f32_16x16x32_bf16 v[14:17], v[146:149], v[218:221], v[14:17]
	v_mfma_f32_16x16x32_bf16 v[10:13], v[164:167], v[218:221], v[10:13]
	v_mfma_f32_16x16x32_bf16 v[62:65], v[160:163], v[198:201], v[62:65]
	v_mfma_f32_16x16x32_bf16 v[58:61], v[168:171], v[198:201], v[58:61]
	v_mfma_f32_16x16x32_bf16 v[46:49], v[160:163], v[206:209], v[46:49]
	v_mfma_f32_16x16x32_bf16 v[42:45], v[168:171], v[206:209], v[42:45]
	v_mfma_f32_16x16x32_bf16 v[30:33], v[160:163], v[214:217], v[30:33]
	v_mfma_f32_16x16x32_bf16 v[26:29], v[168:171], v[214:217], v[26:29]
	v_mfma_f32_16x16x32_bf16 v[14:17], v[160:163], v[222:225], v[14:17]
	v_mfma_f32_16x16x32_bf16 v[10:13], v[168:171], v[222:225], v[10:13]
	s_setprio 0
	s_setprio 1
	v_mfma_f32_16x16x32_bf16 v[54:57], v[178:181], v[194:197], v[54:57]
	v_mfma_f32_16x16x32_bf16 v[50:53], v[186:189], v[194:197], v[50:53]
	v_mfma_f32_16x16x32_bf16 v[38:41], v[178:181], v[202:205], v[38:41]
	v_mfma_f32_16x16x32_bf16 v[34:37], v[186:189], v[202:205], v[34:37]
	v_mfma_f32_16x16x32_bf16 v[22:25], v[178:181], v[210:213], v[22:25]
	v_mfma_f32_16x16x32_bf16 v[18:21], v[186:189], v[210:213], v[18:21]
	v_mfma_f32_16x16x32_bf16 v[6:9], v[178:181], v[218:221], v[6:9]
	v_mfma_f32_16x16x32_bf16 v[2:5], v[186:189], v[218:221], v[2:5]
	v_mfma_f32_16x16x32_bf16 v[54:57], v[182:185], v[198:201], v[54:57]
	v_mfma_f32_16x16x32_bf16 v[50:53], v[190:193], v[198:201], v[50:53]
	v_mfma_f32_16x16x32_bf16 v[38:41], v[182:185], v[206:209], v[38:41]
	v_mfma_f32_16x16x32_bf16 v[34:37], v[190:193], v[206:209], v[34:37]
	v_mfma_f32_16x16x32_bf16 v[22:25], v[182:185], v[214:217], v[22:25]
	v_mfma_f32_16x16x32_bf16 v[18:21], v[190:193], v[214:217], v[18:21]
	v_mfma_f32_16x16x32_bf16 v[6:9], v[182:185], v[222:225], v[6:9]
	v_mfma_f32_16x16x32_bf16 v[2:5], v[190:193], v[222:225], v[2:5]
	s_setprio 0
	s_barrier
	s_add_i32 s53, s53, 2
	s_add_u32 s51, s51, 0x100
	s_addc_u32 s52, s52, 0
	s_cmp_gt_u32 s53, 13
	s_mov_b64 s[26:27], s[28:29]
	s_cbranch_scc0 .LBB0_1590
	s_branch .Lpeel_exit_1590
.LBB0_1590:
	ds_read_b128 v[146:149], v155
	ds_read_b128 v[160:163], v155 offset:1024
	ds_read_b128 v[164:167], v155 offset:2048
	ds_read_b128 v[168:171], v155 offset:3072
	ds_read_b128 v[178:181], v156
	ds_read_b128 v[182:185], v156 offset:1024
	ds_read_b128 v[186:189], v156 offset:2048
	ds_read_b128 v[190:193], v156 offset:3072
	s_add_u32 s28, s26, 0x100
	s_addc_u32 s29, s27, 0
	s_cmp_eq_u32 s53, 12
	s_cselect_b32 s35, s21, s29
	s_cselect_b32 s34, s49, s28
	s_cselect_b32 s31, s19, s52
	s_cselect_b32 s30, s50, s51
	v_lshl_add_u64 v[150:151], s[26:27], 0, v[138:139]
	s_add_i32 m0, s37, 0xc000
	ds_read_b128 v[194:197], v157
	ds_read_b128 v[198:201], v157 offset:1024
	ds_read_b128 v[202:205], v157 offset:2048
	ds_read_b128 v[206:209], v157 offset:3072
	ds_read_b128 v[210:213], v157 offset:4096
	ds_read_b128 v[214:217], v157 offset:5120
	ds_read_b128 v[218:221], v157 offset:6144
	ds_read_b128 v[222:225], v157 offset:7168
	global_load_lds_dwordx4 v[150:151], off
	s_add_i32 m0, s37, 0xe000
	v_lshl_add_u64 v[150:151], s[26:27], 0, v[140:141]
	global_load_lds_dwordx4 v[150:151], off
	s_waitcnt vmcnt(8)
	s_waitcnt lgkmcnt(0)
	s_barrier
	s_setprio 1
	s_waitcnt lgkmcnt(0)
	v_mfma_f32_16x16x32_bf16 v[126:129], v[146:149], v[194:197], v[126:129]
	v_mfma_f32_16x16x32_bf16 v[122:125], v[164:167], v[194:197], v[122:125]
	v_mfma_f32_16x16x32_bf16 v[110:113], v[146:149], v[202:205], v[110:113]
	v_mfma_f32_16x16x32_bf16 v[106:109], v[164:167], v[202:205], v[106:109]
	v_mfma_f32_16x16x32_bf16 v[94:97], v[146:149], v[210:213], v[94:97]
	v_mfma_f32_16x16x32_bf16 v[90:93], v[164:167], v[210:213], v[90:93]
	v_mfma_f32_16x16x32_bf16 v[78:81], v[146:149], v[218:221], v[78:81]
	v_mfma_f32_16x16x32_bf16 v[74:77], v[164:167], v[218:221], v[74:77]
	v_mfma_f32_16x16x32_bf16 v[126:129], v[160:163], v[198:201], v[126:129]
	v_mfma_f32_16x16x32_bf16 v[122:125], v[168:171], v[198:201], v[122:125]
	v_mfma_f32_16x16x32_bf16 v[110:113], v[160:163], v[206:209], v[110:113]
	v_mfma_f32_16x16x32_bf16 v[106:109], v[168:171], v[206:209], v[106:109]
	v_mfma_f32_16x16x32_bf16 v[94:97], v[160:163], v[214:217], v[94:97]
	v_mfma_f32_16x16x32_bf16 v[90:93], v[168:171], v[214:217], v[90:93]
	v_mfma_f32_16x16x32_bf16 v[78:81], v[160:163], v[222:225], v[78:81]
	v_mfma_f32_16x16x32_bf16 v[74:77], v[168:171], v[222:225], v[74:77]
	s_setprio 0
	s_setprio 1
	v_mfma_f32_16x16x32_bf16 v[118:121], v[178:181], v[194:197], v[118:121]
	v_mfma_f32_16x16x32_bf16 v[114:117], v[186:189], v[194:197], v[114:117]
	v_mfma_f32_16x16x32_bf16 v[102:105], v[178:181], v[202:205], v[102:105]
	v_mfma_f32_16x16x32_bf16 v[98:101], v[186:189], v[202:205], v[98:101]
	v_mfma_f32_16x16x32_bf16 v[86:89], v[178:181], v[210:213], v[86:89]
	v_mfma_f32_16x16x32_bf16 v[82:85], v[186:189], v[210:213], v[82:85]
	v_mfma_f32_16x16x32_bf16 v[70:73], v[178:181], v[218:221], v[70:73]
	v_mfma_f32_16x16x32_bf16 v[66:69], v[186:189], v[218:221], v[66:69]
	v_mfma_f32_16x16x32_bf16 v[118:121], v[182:185], v[198:201], v[118:121]
	v_mfma_f32_16x16x32_bf16 v[114:117], v[190:193], v[198:201], v[114:117]
	v_mfma_f32_16x16x32_bf16 v[102:105], v[182:185], v[206:209], v[102:105]
	v_mfma_f32_16x16x32_bf16 v[98:101], v[190:193], v[206:209], v[98:101]
	v_mfma_f32_16x16x32_bf16 v[86:89], v[182:185], v[214:217], v[86:89]
	v_mfma_f32_16x16x32_bf16 v[82:85], v[190:193], v[214:217], v[82:85]
	v_mfma_f32_16x16x32_bf16 v[70:73], v[182:185], v[222:225], v[70:73]
	v_mfma_f32_16x16x32_bf16 v[66:69], v[190:193], v[222:225], v[66:69]
	s_setprio 0
	s_barrier
	s_add_i32 s26, s45, s36
	v_lshl_add_u64 v[150:151], s[30:31], 0, v[132:133]
	s_mov_b32 m0, s26
	ds_read_b128 v[194:197], v157 offset:16384
	ds_read_b128 v[198:201], v157 offset:17408
	ds_read_b128 v[202:205], v157 offset:18432
	ds_read_b128 v[206:209], v157 offset:19456
	ds_read_b128 v[210:213], v157 offset:20480
	ds_read_b128 v[214:217], v157 offset:21504
	ds_read_b128 v[218:221], v157 offset:22528
	ds_read_b128 v[222:225], v157 offset:23552
	global_load_lds_dwordx4 v[150:151], off
	s_add_i32 m0, s26, 0x2000
	s_add_u32 s26, s30, 0x40000
	v_lshl_add_u64 v[172:173], s[30:31], 0, v[136:137]
	s_addc_u32 s27, s31, 0
	s_add_i32 s54, s46, s36
	global_load_lds_dwordx4 v[172:173], off
	v_lshl_add_u64 v[226:227], s[26:27], 0, v[132:133]
	s_mov_b32 m0, s54
	v_lshl_add_u64 v[228:229], s[34:35], 0, v[134:135]
	global_load_lds_dwordx4 v[226:227], off
	s_add_i32 m0, s54, 0x2000
	v_lshl_add_u64 v[226:227], s[26:27], 0, v[136:137]
	global_load_lds_dwordx4 v[226:227], off
	s_mov_b32 m0, s37
	v_lshl_add_u64 v[226:227], s[34:35], 0, v[130:131]
	global_load_lds_dwordx4 v[226:227], off
	s_mov_b32 m0, s38
	s_nop 0
	global_load_lds_dwordx4 v[228:229], off
	s_waitcnt vmcnt(8)
	s_waitcnt lgkmcnt(0)
	s_barrier
	s_setprio 1
	s_waitcnt lgkmcnt(0)
	v_mfma_f32_16x16x32_bf16 v[62:65], v[146:149], v[194:197], v[62:65]
	v_mfma_f32_16x16x32_bf16 v[58:61], v[164:167], v[194:197], v[58:61]
	v_mfma_f32_16x16x32_bf16 v[46:49], v[146:149], v[202:205], v[46:49]
	v_mfma_f32_16x16x32_bf16 v[42:45], v[164:167], v[202:205], v[42:45]
	v_mfma_f32_16x16x32_bf16 v[30:33], v[146:149], v[210:213], v[30:33]
	v_mfma_f32_16x16x32_bf16 v[26:29], v[164:167], v[210:213], v[26:29]
	v_mfma_f32_16x16x32_bf16 v[14:17], v[146:149], v[218:221], v[14:17]
	v_mfma_f32_16x16x32_bf16 v[10:13], v[164:167], v[218:221], v[10:13]
	v_mfma_f32_16x16x32_bf16 v[62:65], v[160:163], v[198:201], v[62:65]
	v_mfma_f32_16x16x32_bf16 v[58:61], v[168:171], v[198:201], v[58:61]
	v_mfma_f32_16x16x32_bf16 v[46:49], v[160:163], v[206:209], v[46:49]
	v_mfma_f32_16x16x32_bf16 v[42:45], v[168:171], v[206:209], v[42:45]
	v_mfma_f32_16x16x32_bf16 v[30:33], v[160:163], v[214:217], v[30:33]
	v_mfma_f32_16x16x32_bf16 v[26:29], v[168:171], v[214:217], v[26:29]
	v_mfma_f32_16x16x32_bf16 v[14:17], v[160:163], v[222:225], v[14:17]
	v_mfma_f32_16x16x32_bf16 v[10:13], v[168:171], v[222:225], v[10:13]
	s_setprio 0
	s_setprio 1
	v_mfma_f32_16x16x32_bf16 v[54:57], v[178:181], v[194:197], v[54:57]
	v_mfma_f32_16x16x32_bf16 v[50:53], v[186:189], v[194:197], v[50:53]
	v_mfma_f32_16x16x32_bf16 v[38:41], v[178:181], v[202:205], v[38:41]
	v_mfma_f32_16x16x32_bf16 v[34:37], v[186:189], v[202:205], v[34:37]
	v_mfma_f32_16x16x32_bf16 v[22:25], v[178:181], v[210:213], v[22:25]
	v_mfma_f32_16x16x32_bf16 v[18:21], v[186:189], v[210:213], v[18:21]
	v_mfma_f32_16x16x32_bf16 v[6:9], v[178:181], v[218:221], v[6:9]
	v_mfma_f32_16x16x32_bf16 v[2:5], v[186:189], v[218:221], v[2:5]
	v_mfma_f32_16x16x32_bf16 v[54:57], v[182:185], v[198:201], v[54:57]
	v_mfma_f32_16x16x32_bf16 v[50:53], v[190:193], v[198:201], v[50:53]
	v_mfma_f32_16x16x32_bf16 v[38:41], v[182:185], v[206:209], v[38:41]
	v_mfma_f32_16x16x32_bf16 v[34:37], v[190:193], v[206:209], v[34:37]
	v_mfma_f32_16x16x32_bf16 v[22:25], v[182:185], v[214:217], v[22:25]
	v_mfma_f32_16x16x32_bf16 v[18:21], v[190:193], v[214:217], v[18:21]
	v_mfma_f32_16x16x32_bf16 v[6:9], v[182:185], v[222:225], v[6:9]
	v_mfma_f32_16x16x32_bf16 v[2:5], v[190:193], v[222:225], v[2:5]
	s_setprio 0
	s_barrier
	s_add_i32 s54, 0, 0x18000
	s_add_i32 s55, 0, 0x1c000
	v_add_u32_e32 v168, s54, v153
	v_add_u32_e32 v177, s55, v153
	ds_read_b128 v[146:149], v168
	ds_read_b128 v[160:163], v168 offset:1024
	ds_read_b128 v[164:167], v168 offset:2048
	ds_read_b128 v[168:171], v168 offset:3072
	ds_read_b128 v[178:181], v177
	ds_read_b128 v[182:185], v177 offset:1024
	ds_read_b128 v[186:189], v177 offset:2048
	ds_read_b128 v[190:193], v177 offset:3072
	s_add_u32 s26, s34, 0x40000
	s_addc_u32 s27, s35, 0
	s_mov_b32 m0, s39
	v_lshl_add_u64 v[230:231], s[26:27], 0, v[130:131]
	ds_read_b128 v[194:197], v157 offset:32768
	ds_read_b128 v[198:201], v157 offset:33792
	ds_read_b128 v[202:205], v157 offset:34816
	ds_read_b128 v[206:209], v157 offset:35840
	ds_read_b128 v[210:213], v157 offset:36864
	ds_read_b128 v[214:217], v157 offset:37888
	ds_read_b128 v[218:221], v157 offset:38912
	ds_read_b128 v[222:225], v157 offset:39936
	global_load_lds_dwordx4 v[230:231], off
	s_mov_b32 m0, s40
	v_lshl_add_u64 v[230:231], s[26:27], 0, v[134:135]
	global_load_lds_dwordx4 v[230:231], off
	s_waitcnt vmcnt(8)
	s_waitcnt lgkmcnt(0)
	s_barrier
	s_setprio 1
	s_waitcnt lgkmcnt(0)
	v_mfma_f32_16x16x32_bf16 v[126:129], v[146:149], v[194:197], v[126:129]
	v_mfma_f32_16x16x32_bf16 v[122:125], v[164:167], v[194:197], v[122:125]
	v_mfma_f32_16x16x32_bf16 v[110:113], v[146:149], v[202:205], v[110:113]
	v_mfma_f32_16x16x32_bf16 v[106:109], v[164:167], v[202:205], v[106:109]
	v_mfma_f32_16x16x32_bf16 v[94:97], v[146:149], v[210:213], v[94:97]
	v_mfma_f32_16x16x32_bf16 v[90:93], v[164:167], v[210:213], v[90:93]
	v_mfma_f32_16x16x32_bf16 v[78:81], v[146:149], v[218:221], v[78:81]
	v_mfma_f32_16x16x32_bf16 v[74:77], v[164:167], v[218:221], v[74:77]
	v_mfma_f32_16x16x32_bf16 v[126:129], v[160:163], v[198:201], v[126:129]
	v_mfma_f32_16x16x32_bf16 v[122:125], v[168:171], v[198:201], v[122:125]
	v_mfma_f32_16x16x32_bf16 v[110:113], v[160:163], v[206:209], v[110:113]
	v_mfma_f32_16x16x32_bf16 v[106:109], v[168:171], v[206:209], v[106:109]
	v_mfma_f32_16x16x32_bf16 v[94:97], v[160:163], v[214:217], v[94:97]
	v_mfma_f32_16x16x32_bf16 v[90:93], v[168:171], v[214:217], v[90:93]
	v_mfma_f32_16x16x32_bf16 v[78:81], v[160:163], v[222:225], v[78:81]
	v_mfma_f32_16x16x32_bf16 v[74:77], v[168:171], v[222:225], v[74:77]
	s_setprio 0
	s_setprio 1
	v_mfma_f32_16x16x32_bf16 v[118:121], v[178:181], v[194:197], v[118:121]
	v_mfma_f32_16x16x32_bf16 v[114:117], v[186:189], v[194:197], v[114:117]
	v_mfma_f32_16x16x32_bf16 v[102:105], v[178:181], v[202:205], v[102:105]
	v_mfma_f32_16x16x32_bf16 v[98:101], v[186:189], v[202:205], v[98:101]
	v_mfma_f32_16x16x32_bf16 v[86:89], v[178:181], v[210:213], v[86:89]
	v_mfma_f32_16x16x32_bf16 v[82:85], v[186:189], v[210:213], v[82:85]
	v_mfma_f32_16x16x32_bf16 v[70:73], v[178:181], v[218:221], v[70:73]
	v_mfma_f32_16x16x32_bf16 v[66:69], v[186:189], v[218:221], v[66:69]
	v_mfma_f32_16x16x32_bf16 v[118:121], v[182:185], v[198:201], v[118:121]
	v_mfma_f32_16x16x32_bf16 v[114:117], v[190:193], v[198:201], v[114:117]
	v_mfma_f32_16x16x32_bf16 v[102:105], v[182:185], v[206:209], v[102:105]
	v_mfma_f32_16x16x32_bf16 v[98:101], v[190:193], v[206:209], v[98:101]
	v_mfma_f32_16x16x32_bf16 v[86:89], v[182:185], v[214:217], v[86:89]
	v_mfma_f32_16x16x32_bf16 v[82:85], v[190:193], v[214:217], v[82:85]
	v_mfma_f32_16x16x32_bf16 v[70:73], v[182:185], v[222:225], v[70:73]
	v_mfma_f32_16x16x32_bf16 v[66:69], v[190:193], v[222:225], v[66:69]
	s_setprio 0
	s_barrier
	s_add_i32 s26, s54, s36
	v_lshl_add_u64 v[150:151], v[150:151], 0, s[10:11]
	s_mov_b32 m0, s26
	ds_read_b128 v[194:197], v157 offset:49152
	ds_read_b128 v[198:201], v157 offset:50176
	ds_read_b128 v[202:205], v157 offset:51200
	ds_read_b128 v[206:209], v157 offset:52224
	ds_read_b128 v[210:213], v157 offset:53248
	ds_read_b128 v[214:217], v157 offset:54272
	ds_read_b128 v[218:221], v157 offset:55296
	ds_read_b128 v[222:225], v157 offset:56320
	global_load_lds_dwordx4 v[150:151], off
	s_add_i32 m0, s26, 0x2000
	s_add_u32 s26, s30, 0x40080
	v_lshl_add_u64 v[150:151], v[172:173], 0, s[10:11]
	s_addc_u32 s27, s31, 0
	s_add_i32 s30, s55, s36
	global_load_lds_dwordx4 v[150:151], off
	s_mov_b32 m0, s30
	v_lshl_add_u64 v[150:151], s[26:27], 0, v[132:133]
	global_load_lds_dwordx4 v[150:151], off
	s_add_i32 m0, s30, 0x2000
	v_lshl_add_u64 v[150:151], s[26:27], 0, v[136:137]
	global_load_lds_dwordx4 v[150:151], off
	s_mov_b32 m0, s42
	v_lshl_add_u64 v[150:151], v[226:227], 0, s[10:11]
	global_load_lds_dwordx4 v[150:151], off
	s_mov_b32 m0, s43
	v_lshl_add_u64 v[150:151], v[228:229], 0, s[10:11]
	global_load_lds_dwordx4 v[150:151], off
	s_waitcnt vmcnt(8)
	s_waitcnt lgkmcnt(0)
	s_barrier
	s_setprio 1
	s_waitcnt lgkmcnt(0)
	v_mfma_f32_16x16x32_bf16 v[62:65], v[146:149], v[194:197], v[62:65]
	v_mfma_f32_16x16x32_bf16 v[58:61], v[164:167], v[194:197], v[58:61]
	v_mfma_f32_16x16x32_bf16 v[46:49], v[146:149], v[202:205], v[46:49]
	v_mfma_f32_16x16x32_bf16 v[42:45], v[164:167], v[202:205], v[42:45]
	v_mfma_f32_16x16x32_bf16 v[30:33], v[146:149], v[210:213], v[30:33]
	v_mfma_f32_16x16x32_bf16 v[26:29], v[164:167], v[210:213], v[26:29]
	v_mfma_f32_16x16x32_bf16 v[14:17], v[146:149], v[218:221], v[14:17]
	v_mfma_f32_16x16x32_bf16 v[10:13], v[164:167], v[218:221], v[10:13]
	v_mfma_f32_16x16x32_bf16 v[62:65], v[160:163], v[198:201], v[62:65]
	v_mfma_f32_16x16x32_bf16 v[58:61], v[168:171], v[198:201], v[58:61]
	v_mfma_f32_16x16x32_bf16 v[46:49], v[160:163], v[206:209], v[46:49]
	v_mfma_f32_16x16x32_bf16 v[42:45], v[168:171], v[206:209], v[42:45]
	v_mfma_f32_16x16x32_bf16 v[30:33], v[160:163], v[214:217], v[30:33]
	v_mfma_f32_16x16x32_bf16 v[26:29], v[168:171], v[214:217], v[26:29]
	v_mfma_f32_16x16x32_bf16 v[14:17], v[160:163], v[222:225], v[14:17]
	v_mfma_f32_16x16x32_bf16 v[10:13], v[168:171], v[222:225], v[10:13]
	s_setprio 0
	s_setprio 1
	v_mfma_f32_16x16x32_bf16 v[54:57], v[178:181], v[194:197], v[54:57]
	v_mfma_f32_16x16x32_bf16 v[50:53], v[186:189], v[194:197], v[50:53]
	v_mfma_f32_16x16x32_bf16 v[38:41], v[178:181], v[202:205], v[38:41]
	v_mfma_f32_16x16x32_bf16 v[34:37], v[186:189], v[202:205], v[34:37]
	v_mfma_f32_16x16x32_bf16 v[22:25], v[178:181], v[210:213], v[22:25]
	v_mfma_f32_16x16x32_bf16 v[18:21], v[186:189], v[210:213], v[18:21]
	v_mfma_f32_16x16x32_bf16 v[6:9], v[178:181], v[218:221], v[6:9]
	v_mfma_f32_16x16x32_bf16 v[2:5], v[186:189], v[218:221], v[2:5]
	v_mfma_f32_16x16x32_bf16 v[54:57], v[182:185], v[198:201], v[54:57]
	v_mfma_f32_16x16x32_bf16 v[50:53], v[190:193], v[198:201], v[50:53]
	v_mfma_f32_16x16x32_bf16 v[38:41], v[182:185], v[206:209], v[38:41]
	v_mfma_f32_16x16x32_bf16 v[34:37], v[190:193], v[206:209], v[34:37]
	v_mfma_f32_16x16x32_bf16 v[22:25], v[182:185], v[214:217], v[22:25]
	v_mfma_f32_16x16x32_bf16 v[18:21], v[190:193], v[214:217], v[18:21]
	v_mfma_f32_16x16x32_bf16 v[6:9], v[182:185], v[222:225], v[6:9]
	v_mfma_f32_16x16x32_bf16 v[2:5], v[190:193], v[222:225], v[2:5]
	s_setprio 0
	s_barrier
	s_add_i32 s53, s53, 2
	s_add_u32 s51, s51, 0x100
	s_addc_u32 s52, s52, 0
	s_cmp_gt_u32 s53, 13
	s_mov_b64 s[26:27], s[28:29]
	s_cbranch_scc0 .LBB0_1590

.LBB0_1683:
	s_add_u32 s49, s28, 0x100
	s_addc_u32 s50, s29, 0
	s_mov_b32 s51, -2
	s_waitcnt lgkmcnt(0)
	ds_read_b128 v[144:147], v151
	ds_read_b128 v[156:159], v151 offset:1024
	ds_read_b128 v[160:163], v151 offset:2048
	ds_read_b128 v[164:167], v151 offset:3072
	ds_read_b128 v[168:171], v152
	ds_read_b128 v[176:179], v152 offset:1024
	ds_read_b128 v[180:183], v152 offset:2048
	ds_read_b128 v[184:187], v152 offset:3072
	s_add_u32 s28, s26, 0x100
	s_addc_u32 s29, s27, 0
	s_cmp_eq_u32 s51, 40
	s_cselect_b32 s35, s7, s29
	s_cselect_b32 s34, s6, s28
	s_cselect_b32 s31, s25, s50
	s_cselect_b32 s30, s24, s49
	v_lshl_add_u64 v[172:173], s[26:27], 0, v[136:137]
	s_add_i32 m0, s16, 0xc000
	ds_read_b128 v[188:191], v153
	ds_read_b128 v[192:195], v153 offset:1024
	ds_read_b128 v[196:199], v153 offset:2048
	ds_read_b128 v[200:203], v153 offset:3072
	ds_read_b128 v[204:207], v153 offset:4096
	ds_read_b128 v[208:211], v153 offset:5120
	ds_read_b128 v[212:215], v153 offset:6144
	ds_read_b128 v[216:219], v153 offset:7168
	global_load_lds_dwordx4 v[172:173], off
	s_add_i32 m0, s16, 0xe000
	v_lshl_add_u64 v[172:173], s[26:27], 0, v[138:139]
	global_load_lds_dwordx4 v[172:173], off
	s_waitcnt vmcnt(8)
	s_waitcnt lgkmcnt(0)
	s_barrier
	s_setprio 1
	s_waitcnt lgkmcnt(0)
	v_mfma_f32_16x16x32_bf16 v[124:127], v[144:147], v[188:191], 0
	v_mfma_f32_16x16x32_bf16 v[120:123], v[160:163], v[188:191], 0
	v_mfma_f32_16x16x32_bf16 v[108:111], v[144:147], v[196:199], 0
	v_mfma_f32_16x16x32_bf16 v[104:107], v[160:163], v[196:199], 0
	v_mfma_f32_16x16x32_bf16 v[92:95], v[144:147], v[204:207], 0
	v_mfma_f32_16x16x32_bf16 v[88:91], v[160:163], v[204:207], 0
	v_mfma_f32_16x16x32_bf16 v[76:79], v[144:147], v[212:215], 0
	v_mfma_f32_16x16x32_bf16 v[72:75], v[160:163], v[212:215], 0
	v_mfma_f32_16x16x32_bf16 v[124:127], v[156:159], v[192:195], v[124:127]
	v_mfma_f32_16x16x32_bf16 v[120:123], v[164:167], v[192:195], v[120:123]
	v_mfma_f32_16x16x32_bf16 v[108:111], v[156:159], v[200:203], v[108:111]
	v_mfma_f32_16x16x32_bf16 v[104:107], v[164:167], v[200:203], v[104:107]
	v_mfma_f32_16x16x32_bf16 v[92:95], v[156:159], v[208:211], v[92:95]
	v_mfma_f32_16x16x32_bf16 v[88:91], v[164:167], v[208:211], v[88:91]
	v_mfma_f32_16x16x32_bf16 v[76:79], v[156:159], v[216:219], v[76:79]
	v_mfma_f32_16x16x32_bf16 v[72:75], v[164:167], v[216:219], v[72:75]
	s_setprio 0
	s_setprio 1
	v_mfma_f32_16x16x32_bf16 v[116:119], v[168:171], v[188:191], 0
	v_mfma_f32_16x16x32_bf16 v[112:115], v[180:183], v[188:191], 0
	v_mfma_f32_16x16x32_bf16 v[100:103], v[168:171], v[196:199], 0
	v_mfma_f32_16x16x32_bf16 v[96:99], v[180:183], v[196:199], 0
	v_mfma_f32_16x16x32_bf16 v[84:87], v[168:171], v[204:207], 0
	v_mfma_f32_16x16x32_bf16 v[80:83], v[180:183], v[204:207], 0
	v_mfma_f32_16x16x32_bf16 v[68:71], v[168:171], v[212:215], 0
	v_mfma_f32_16x16x32_bf16 v[64:67], v[180:183], v[212:215], 0
	v_mfma_f32_16x16x32_bf16 v[116:119], v[176:179], v[192:195], v[116:119]
	v_mfma_f32_16x16x32_bf16 v[112:115], v[184:187], v[192:195], v[112:115]
	v_mfma_f32_16x16x32_bf16 v[100:103], v[176:179], v[200:203], v[100:103]
	v_mfma_f32_16x16x32_bf16 v[96:99], v[184:187], v[200:203], v[96:99]
	v_mfma_f32_16x16x32_bf16 v[84:87], v[176:179], v[208:211], v[84:87]
	v_mfma_f32_16x16x32_bf16 v[80:83], v[184:187], v[208:211], v[80:83]
	v_mfma_f32_16x16x32_bf16 v[68:71], v[176:179], v[216:219], v[68:71]
	v_mfma_f32_16x16x32_bf16 v[64:67], v[184:187], v[216:219], v[64:67]
	s_setprio 0
	s_barrier
	s_add_i32 s26, s43, s15
	v_lshl_add_u64 v[172:173], s[30:31], 0, v[130:131]
	s_mov_b32 m0, s26
	ds_read_b128 v[188:191], v153 offset:16384
	ds_read_b128 v[192:195], v153 offset:17408
	ds_read_b128 v[196:199], v153 offset:18432
	ds_read_b128 v[200:203], v153 offset:19456
	ds_read_b128 v[204:207], v153 offset:20480
	ds_read_b128 v[208:211], v153 offset:21504
	ds_read_b128 v[212:215], v153 offset:22528
	ds_read_b128 v[216:219], v153 offset:23552
	global_load_lds_dwordx4 v[172:173], off
	s_add_i32 m0, s26, 0x2000
	s_add_u32 s26, s30, 0xb0000
	v_lshl_add_u64 v[220:221], s[30:31], 0, v[134:135]
	s_addc_u32 s27, s31, 0
	s_add_i32 s52, s44, s15
	global_load_lds_dwordx4 v[220:221], off
	v_lshl_add_u64 v[222:223], s[26:27], 0, v[130:131]
	s_mov_b32 m0, s52
	v_lshl_add_u64 v[224:225], s[34:35], 0, v[132:133]
	global_load_lds_dwordx4 v[222:223], off
	s_add_i32 m0, s52, 0x2000
	v_lshl_add_u64 v[222:223], s[26:27], 0, v[134:135]
	global_load_lds_dwordx4 v[222:223], off
	s_mov_b32 m0, s16
	v_lshl_add_u64 v[222:223], s[34:35], 0, v[128:129]
	global_load_lds_dwordx4 v[222:223], off
	s_mov_b32 m0, s17
	s_nop 0
	global_load_lds_dwordx4 v[224:225], off
	s_waitcnt vmcnt(8)
	s_waitcnt lgkmcnt(0)
	s_barrier
	s_setprio 1
	s_waitcnt lgkmcnt(0)
	v_mfma_f32_16x16x32_bf16 v[60:63], v[144:147], v[188:191], 0
	v_mfma_f32_16x16x32_bf16 v[56:59], v[160:163], v[188:191], 0
	v_mfma_f32_16x16x32_bf16 v[44:47], v[144:147], v[196:199], 0
	v_mfma_f32_16x16x32_bf16 v[40:43], v[160:163], v[196:199], 0
	v_mfma_f32_16x16x32_bf16 v[28:31], v[144:147], v[204:207], 0
	v_mfma_f32_16x16x32_bf16 v[24:27], v[160:163], v[204:207], 0
	v_mfma_f32_16x16x32_bf16 v[12:15], v[144:147], v[212:215], 0
	v_mfma_f32_16x16x32_bf16 v[8:11], v[160:163], v[212:215], 0
	v_mfma_f32_16x16x32_bf16 v[60:63], v[156:159], v[192:195], v[60:63]
	v_mfma_f32_16x16x32_bf16 v[56:59], v[164:167], v[192:195], v[56:59]
	v_mfma_f32_16x16x32_bf16 v[44:47], v[156:159], v[200:203], v[44:47]
	v_mfma_f32_16x16x32_bf16 v[40:43], v[164:167], v[200:203], v[40:43]
	v_mfma_f32_16x16x32_bf16 v[28:31], v[156:159], v[208:211], v[28:31]
	v_mfma_f32_16x16x32_bf16 v[24:27], v[164:167], v[208:211], v[24:27]
	v_mfma_f32_16x16x32_bf16 v[12:15], v[156:159], v[216:219], v[12:15]
	v_mfma_f32_16x16x32_bf16 v[8:11], v[164:167], v[216:219], v[8:11]
	s_setprio 0
	s_setprio 1
	v_mfma_f32_16x16x32_bf16 v[52:55], v[168:171], v[188:191], 0
	v_mfma_f32_16x16x32_bf16 v[48:51], v[180:183], v[188:191], 0
	v_mfma_f32_16x16x32_bf16 v[36:39], v[168:171], v[196:199], 0
	v_mfma_f32_16x16x32_bf16 v[32:35], v[180:183], v[196:199], 0
	v_mfma_f32_16x16x32_bf16 v[20:23], v[168:171], v[204:207], 0
	v_mfma_f32_16x16x32_bf16 v[16:19], v[180:183], v[204:207], 0
	v_mfma_f32_16x16x32_bf16 v[4:7], v[168:171], v[212:215], 0
	v_mfma_f32_16x16x32_bf16 v[0:3], v[180:183], v[212:215], 0
	v_mfma_f32_16x16x32_bf16 v[52:55], v[176:179], v[192:195], v[52:55]
	v_mfma_f32_16x16x32_bf16 v[48:51], v[184:187], v[192:195], v[48:51]
	v_mfma_f32_16x16x32_bf16 v[36:39], v[176:179], v[200:203], v[36:39]
	v_mfma_f32_16x16x32_bf16 v[32:35], v[184:187], v[200:203], v[32:35]
	v_mfma_f32_16x16x32_bf16 v[20:23], v[176:179], v[208:211], v[20:23]
	v_mfma_f32_16x16x32_bf16 v[16:19], v[184:187], v[208:211], v[16:19]
	v_mfma_f32_16x16x32_bf16 v[4:7], v[176:179], v[216:219], v[4:7]
	v_mfma_f32_16x16x32_bf16 v[0:3], v[184:187], v[216:219], v[0:3]
	s_setprio 0
	s_barrier
	s_add_i32 s52, 0, 0x18000
	v_add_u32_e32 v155, s52, v149
	s_add_i32 s53, 0, 0x1c000
	ds_read_b128 v[144:147], v155
	ds_read_b128 v[156:159], v155 offset:1024
	ds_read_b128 v[160:163], v155 offset:2048
	ds_read_b128 v[164:167], v155 offset:3072
	v_add_u32_e32 v155, s53, v149
	ds_read_b128 v[168:171], v155
	ds_read_b128 v[176:179], v155 offset:1024
	ds_read_b128 v[180:183], v155 offset:2048
	ds_read_b128 v[184:187], v155 offset:3072
	s_add_u32 s26, s34, 0xb0000
	s_addc_u32 s27, s35, 0
	s_mov_b32 m0, s36
	v_lshl_add_u64 v[226:227], s[26:27], 0, v[128:129]
	ds_read_b128 v[188:191], v153 offset:32768
	ds_read_b128 v[192:195], v153 offset:33792
	ds_read_b128 v[196:199], v153 offset:34816
	ds_read_b128 v[200:203], v153 offset:35840
	ds_read_b128 v[204:207], v153 offset:36864
	ds_read_b128 v[208:211], v153 offset:37888
	ds_read_b128 v[212:215], v153 offset:38912
	ds_read_b128 v[216:219], v153 offset:39936
	global_load_lds_dwordx4 v[226:227], off
	s_mov_b32 m0, s37
	v_lshl_add_u64 v[226:227], s[26:27], 0, v[132:133]
	global_load_lds_dwordx4 v[226:227], off
	s_waitcnt vmcnt(8)
	s_waitcnt lgkmcnt(0)
	s_barrier
	s_setprio 1
	s_waitcnt lgkmcnt(0)
	v_mfma_f32_16x16x32_bf16 v[124:127], v[144:147], v[188:191], v[124:127]
	v_mfma_f32_16x16x32_bf16 v[120:123], v[160:163], v[188:191], v[120:123]
	v_mfma_f32_16x16x32_bf16 v[108:111], v[144:147], v[196:199], v[108:111]
	v_mfma_f32_16x16x32_bf16 v[104:107], v[160:163], v[196:199], v[104:107]
	v_mfma_f32_16x16x32_bf16 v[92:95], v[144:147], v[204:207], v[92:95]
	v_mfma_f32_16x16x32_bf16 v[88:91], v[160:163], v[204:207], v[88:91]
	v_mfma_f32_16x16x32_bf16 v[76:79], v[144:147], v[212:215], v[76:79]
	v_mfma_f32_16x16x32_bf16 v[72:75], v[160:163], v[212:215], v[72:75]
	v_mfma_f32_16x16x32_bf16 v[124:127], v[156:159], v[192:195], v[124:127]
	v_mfma_f32_16x16x32_bf16 v[120:123], v[164:167], v[192:195], v[120:123]
	v_mfma_f32_16x16x32_bf16 v[108:111], v[156:159], v[200:203], v[108:111]
	v_mfma_f32_16x16x32_bf16 v[104:107], v[164:167], v[200:203], v[104:107]
	v_mfma_f32_16x16x32_bf16 v[92:95], v[156:159], v[208:211], v[92:95]
	v_mfma_f32_16x16x32_bf16 v[88:91], v[164:167], v[208:211], v[88:91]
	v_mfma_f32_16x16x32_bf16 v[76:79], v[156:159], v[216:219], v[76:79]
	v_mfma_f32_16x16x32_bf16 v[72:75], v[164:167], v[216:219], v[72:75]
	s_setprio 0
	s_setprio 1
	v_mfma_f32_16x16x32_bf16 v[116:119], v[168:171], v[188:191], v[116:119]
	v_mfma_f32_16x16x32_bf16 v[112:115], v[180:183], v[188:191], v[112:115]
	v_mfma_f32_16x16x32_bf16 v[100:103], v[168:171], v[196:199], v[100:103]
	v_mfma_f32_16x16x32_bf16 v[96:99], v[180:183], v[196:199], v[96:99]
	v_mfma_f32_16x16x32_bf16 v[84:87], v[168:171], v[204:207], v[84:87]
	v_mfma_f32_16x16x32_bf16 v[80:83], v[180:183], v[204:207], v[80:83]
	v_mfma_f32_16x16x32_bf16 v[68:71], v[168:171], v[212:215], v[68:71]
	v_mfma_f32_16x16x32_bf16 v[64:67], v[180:183], v[212:215], v[64:67]
	v_mfma_f32_16x16x32_bf16 v[116:119], v[176:179], v[192:195], v[116:119]
	v_mfma_f32_16x16x32_bf16 v[112:115], v[184:187], v[192:195], v[112:115]
	v_mfma_f32_16x16x32_bf16 v[100:103], v[176:179], v[200:203], v[100:103]
	v_mfma_f32_16x16x32_bf16 v[96:99], v[184:187], v[200:203], v[96:99]
	v_mfma_f32_16x16x32_bf16 v[84:87], v[176:179], v[208:211], v[84:87]
	v_mfma_f32_16x16x32_bf16 v[80:83], v[184:187], v[208:211], v[80:83]
	v_mfma_f32_16x16x32_bf16 v[68:71], v[176:179], v[216:219], v[68:71]
	v_mfma_f32_16x16x32_bf16 v[64:67], v[184:187], v[216:219], v[64:67]
	s_setprio 0
	s_barrier
	s_add_i32 s26, s52, s15
	v_lshl_add_u64 v[172:173], v[172:173], 0, s[20:21]
	s_mov_b32 m0, s26
	ds_read_b128 v[188:191], v153 offset:49152
	ds_read_b128 v[192:195], v153 offset:50176
	ds_read_b128 v[196:199], v153 offset:51200
	ds_read_b128 v[200:203], v153 offset:52224
	ds_read_b128 v[204:207], v153 offset:53248
	ds_read_b128 v[208:211], v153 offset:54272
	ds_read_b128 v[212:215], v153 offset:55296
	ds_read_b128 v[216:219], v153 offset:56320
	global_load_lds_dwordx4 v[172:173], off
	s_add_i32 m0, s26, 0x2000
	s_add_u32 s26, s30, 0xb0080
	v_lshl_add_u64 v[172:173], v[220:221], 0, s[20:21]
	s_addc_u32 s27, s31, 0
	s_add_i32 s30, s53, s15
	global_load_lds_dwordx4 v[172:173], off
	s_mov_b32 m0, s30
	v_lshl_add_u64 v[172:173], s[26:27], 0, v[130:131]
	global_load_lds_dwordx4 v[172:173], off
	s_add_i32 m0, s30, 0x2000
	v_lshl_add_u64 v[172:173], s[26:27], 0, v[134:135]
	global_load_lds_dwordx4 v[172:173], off
	s_mov_b32 m0, s39
	v_lshl_add_u64 v[172:173], v[222:223], 0, s[20:21]
	global_load_lds_dwordx4 v[172:173], off
	s_mov_b32 m0, s40
	v_lshl_add_u64 v[172:173], v[224:225], 0, s[20:21]
	global_load_lds_dwordx4 v[172:173], off
	s_waitcnt vmcnt(8)
	s_waitcnt lgkmcnt(0)
	s_barrier
	s_setprio 1
	s_waitcnt lgkmcnt(0)
	v_mfma_f32_16x16x32_bf16 v[60:63], v[144:147], v[188:191], v[60:63]
	v_mfma_f32_16x16x32_bf16 v[56:59], v[160:163], v[188:191], v[56:59]
	v_mfma_f32_16x16x32_bf16 v[44:47], v[144:147], v[196:199], v[44:47]
	v_mfma_f32_16x16x32_bf16 v[40:43], v[160:163], v[196:199], v[40:43]
	v_mfma_f32_16x16x32_bf16 v[28:31], v[144:147], v[204:207], v[28:31]
	v_mfma_f32_16x16x32_bf16 v[24:27], v[160:163], v[204:207], v[24:27]
	v_mfma_f32_16x16x32_bf16 v[12:15], v[144:147], v[212:215], v[12:15]
	v_mfma_f32_16x16x32_bf16 v[8:11], v[160:163], v[212:215], v[8:11]
	v_mfma_f32_16x16x32_bf16 v[60:63], v[156:159], v[192:195], v[60:63]
	v_mfma_f32_16x16x32_bf16 v[56:59], v[164:167], v[192:195], v[56:59]
	v_mfma_f32_16x16x32_bf16 v[44:47], v[156:159], v[200:203], v[44:47]
	v_mfma_f32_16x16x32_bf16 v[40:43], v[164:167], v[200:203], v[40:43]
	v_mfma_f32_16x16x32_bf16 v[28:31], v[156:159], v[208:211], v[28:31]
	v_mfma_f32_16x16x32_bf16 v[24:27], v[164:167], v[208:211], v[24:27]
	v_mfma_f32_16x16x32_bf16 v[12:15], v[156:159], v[216:219], v[12:15]
	v_mfma_f32_16x16x32_bf16 v[8:11], v[164:167], v[216:219], v[8:11]
	s_setprio 0
	s_setprio 1
	v_mfma_f32_16x16x32_bf16 v[52:55], v[168:171], v[188:191], v[52:55]
	v_mfma_f32_16x16x32_bf16 v[48:51], v[180:183], v[188:191], v[48:51]
	v_mfma_f32_16x16x32_bf16 v[36:39], v[168:171], v[196:199], v[36:39]
	v_mfma_f32_16x16x32_bf16 v[32:35], v[180:183], v[196:199], v[32:35]
	v_mfma_f32_16x16x32_bf16 v[20:23], v[168:171], v[204:207], v[20:23]
	v_mfma_f32_16x16x32_bf16 v[16:19], v[180:183], v[204:207], v[16:19]
	v_mfma_f32_16x16x32_bf16 v[4:7], v[168:171], v[212:215], v[4:7]
	v_mfma_f32_16x16x32_bf16 v[0:3], v[180:183], v[212:215], v[0:3]
	v_mfma_f32_16x16x32_bf16 v[52:55], v[176:179], v[192:195], v[52:55]
	v_mfma_f32_16x16x32_bf16 v[48:51], v[184:187], v[192:195], v[48:51]
	v_mfma_f32_16x16x32_bf16 v[36:39], v[176:179], v[200:203], v[36:39]
	v_mfma_f32_16x16x32_bf16 v[32:35], v[184:187], v[200:203], v[32:35]
	v_mfma_f32_16x16x32_bf16 v[20:23], v[176:179], v[208:211], v[20:23]
	v_mfma_f32_16x16x32_bf16 v[16:19], v[184:187], v[208:211], v[16:19]
	v_mfma_f32_16x16x32_bf16 v[4:7], v[176:179], v[216:219], v[4:7]
	v_mfma_f32_16x16x32_bf16 v[0:3], v[184:187], v[216:219], v[0:3]
	s_setprio 0
	s_barrier
	s_add_i32 s51, s51, 2
	s_add_u32 s49, s49, 0x100
	s_addc_u32 s50, s50, 0
	s_cmp_gt_u32 s51, 41
	s_mov_b64 s[26:27], s[28:29]
	s_cbranch_scc0 .LBB0_1684
	s_branch .Lpeel_exit_1684
.LBB0_1684:
	ds_read_b128 v[144:147], v151
	ds_read_b128 v[156:159], v151 offset:1024
	ds_read_b128 v[160:163], v151 offset:2048
	ds_read_b128 v[164:167], v151 offset:3072
	ds_read_b128 v[168:171], v152
	ds_read_b128 v[176:179], v152 offset:1024
	ds_read_b128 v[180:183], v152 offset:2048
	ds_read_b128 v[184:187], v152 offset:3072
	s_add_u32 s28, s26, 0x100
	s_addc_u32 s29, s27, 0
	s_cmp_eq_u32 s51, 40
	s_cselect_b32 s35, s7, s29
	s_cselect_b32 s34, s6, s28
	s_cselect_b32 s31, s25, s50
	s_cselect_b32 s30, s24, s49
	v_lshl_add_u64 v[172:173], s[26:27], 0, v[136:137]
	s_add_i32 m0, s16, 0xc000
	ds_read_b128 v[188:191], v153
	ds_read_b128 v[192:195], v153 offset:1024
	ds_read_b128 v[196:199], v153 offset:2048
	ds_read_b128 v[200:203], v153 offset:3072
	ds_read_b128 v[204:207], v153 offset:4096
	ds_read_b128 v[208:211], v153 offset:5120
	ds_read_b128 v[212:215], v153 offset:6144
	ds_read_b128 v[216:219], v153 offset:7168
	global_load_lds_dwordx4 v[172:173], off
	s_add_i32 m0, s16, 0xe000
	v_lshl_add_u64 v[172:173], s[26:27], 0, v[138:139]
	global_load_lds_dwordx4 v[172:173], off
	s_waitcnt vmcnt(8)
	s_waitcnt lgkmcnt(0)
	s_barrier
	s_setprio 1
	s_waitcnt lgkmcnt(0)
	v_mfma_f32_16x16x32_bf16 v[124:127], v[144:147], v[188:191], v[124:127]
	v_mfma_f32_16x16x32_bf16 v[120:123], v[160:163], v[188:191], v[120:123]
	v_mfma_f32_16x16x32_bf16 v[108:111], v[144:147], v[196:199], v[108:111]
	v_mfma_f32_16x16x32_bf16 v[104:107], v[160:163], v[196:199], v[104:107]
	v_mfma_f32_16x16x32_bf16 v[92:95], v[144:147], v[204:207], v[92:95]
	v_mfma_f32_16x16x32_bf16 v[88:91], v[160:163], v[204:207], v[88:91]
	v_mfma_f32_16x16x32_bf16 v[76:79], v[144:147], v[212:215], v[76:79]
	v_mfma_f32_16x16x32_bf16 v[72:75], v[160:163], v[212:215], v[72:75]
	v_mfma_f32_16x16x32_bf16 v[124:127], v[156:159], v[192:195], v[124:127]
	v_mfma_f32_16x16x32_bf16 v[120:123], v[164:167], v[192:195], v[120:123]
	v_mfma_f32_16x16x32_bf16 v[108:111], v[156:159], v[200:203], v[108:111]
	v_mfma_f32_16x16x32_bf16 v[104:107], v[164:167], v[200:203], v[104:107]
	v_mfma_f32_16x16x32_bf16 v[92:95], v[156:159], v[208:211], v[92:95]
	v_mfma_f32_16x16x32_bf16 v[88:91], v[164:167], v[208:211], v[88:91]
	v_mfma_f32_16x16x32_bf16 v[76:79], v[156:159], v[216:219], v[76:79]
	v_mfma_f32_16x16x32_bf16 v[72:75], v[164:167], v[216:219], v[72:75]
	s_setprio 0
	s_setprio 1
	v_mfma_f32_16x16x32_bf16 v[116:119], v[168:171], v[188:191], v[116:119]
	v_mfma_f32_16x16x32_bf16 v[112:115], v[180:183], v[188:191], v[112:115]
	v_mfma_f32_16x16x32_bf16 v[100:103], v[168:171], v[196:199], v[100:103]
	v_mfma_f32_16x16x32_bf16 v[96:99], v[180:183], v[196:199], v[96:99]
	v_mfma_f32_16x16x32_bf16 v[84:87], v[168:171], v[204:207], v[84:87]
	v_mfma_f32_16x16x32_bf16 v[80:83], v[180:183], v[204:207], v[80:83]
	v_mfma_f32_16x16x32_bf16 v[68:71], v[168:171], v[212:215], v[68:71]
	v_mfma_f32_16x16x32_bf16 v[64:67], v[180:183], v[212:215], v[64:67]
	v_mfma_f32_16x16x32_bf16 v[116:119], v[176:179], v[192:195], v[116:119]
	v_mfma_f32_16x16x32_bf16 v[112:115], v[184:187], v[192:195], v[112:115]
	v_mfma_f32_16x16x32_bf16 v[100:103], v[176:179], v[200:203], v[100:103]
	v_mfma_f32_16x16x32_bf16 v[96:99], v[184:187], v[200:203], v[96:99]
	v_mfma_f32_16x16x32_bf16 v[84:87], v[176:179], v[208:211], v[84:87]
	v_mfma_f32_16x16x32_bf16 v[80:83], v[184:187], v[208:211], v[80:83]
	v_mfma_f32_16x16x32_bf16 v[68:71], v[176:179], v[216:219], v[68:71]
	v_mfma_f32_16x16x32_bf16 v[64:67], v[184:187], v[216:219], v[64:67]
	s_setprio 0
	s_barrier
	s_add_i32 s26, s43, s15
	v_lshl_add_u64 v[172:173], s[30:31], 0, v[130:131]
	s_mov_b32 m0, s26
	ds_read_b128 v[188:191], v153 offset:16384
	ds_read_b128 v[192:195], v153 offset:17408
	ds_read_b128 v[196:199], v153 offset:18432
	ds_read_b128 v[200:203], v153 offset:19456
	ds_read_b128 v[204:207], v153 offset:20480
	ds_read_b128 v[208:211], v153 offset:21504
	ds_read_b128 v[212:215], v153 offset:22528
	ds_read_b128 v[216:219], v153 offset:23552
	global_load_lds_dwordx4 v[172:173], off
	s_add_i32 m0, s26, 0x2000
	s_add_u32 s26, s30, 0xb0000
	v_lshl_add_u64 v[220:221], s[30:31], 0, v[134:135]
	s_addc_u32 s27, s31, 0
	s_add_i32 s52, s44, s15
	global_load_lds_dwordx4 v[220:221], off
	v_lshl_add_u64 v[222:223], s[26:27], 0, v[130:131]
	s_mov_b32 m0, s52
	v_lshl_add_u64 v[224:225], s[34:35], 0, v[132:133]
	global_load_lds_dwordx4 v[222:223], off
	s_add_i32 m0, s52, 0x2000
	v_lshl_add_u64 v[222:223], s[26:27], 0, v[134:135]
	global_load_lds_dwordx4 v[222:223], off
	s_mov_b32 m0, s16
	v_lshl_add_u64 v[222:223], s[34:35], 0, v[128:129]
	global_load_lds_dwordx4 v[222:223], off
	s_mov_b32 m0, s17
	s_nop 0
	global_load_lds_dwordx4 v[224:225], off
	s_waitcnt vmcnt(8)
	s_waitcnt lgkmcnt(0)
	s_barrier
	s_setprio 1
	s_waitcnt lgkmcnt(0)
	v_mfma_f32_16x16x32_bf16 v[60:63], v[144:147], v[188:191], v[60:63]
	v_mfma_f32_16x16x32_bf16 v[56:59], v[160:163], v[188:191], v[56:59]
	v_mfma_f32_16x16x32_bf16 v[44:47], v[144:147], v[196:199], v[44:47]
	v_mfma_f32_16x16x32_bf16 v[40:43], v[160:163], v[196:199], v[40:43]
	v_mfma_f32_16x16x32_bf16 v[28:31], v[144:147], v[204:207], v[28:31]
	v_mfma_f32_16x16x32_bf16 v[24:27], v[160:163], v[204:207], v[24:27]
	v_mfma_f32_16x16x32_bf16 v[12:15], v[144:147], v[212:215], v[12:15]
	v_mfma_f32_16x16x32_bf16 v[8:11], v[160:163], v[212:215], v[8:11]
	v_mfma_f32_16x16x32_bf16 v[60:63], v[156:159], v[192:195], v[60:63]
	v_mfma_f32_16x16x32_bf16 v[56:59], v[164:167], v[192:195], v[56:59]
	v_mfma_f32_16x16x32_bf16 v[44:47], v[156:159], v[200:203], v[44:47]
	v_mfma_f32_16x16x32_bf16 v[40:43], v[164:167], v[200:203], v[40:43]
	v_mfma_f32_16x16x32_bf16 v[28:31], v[156:159], v[208:211], v[28:31]
	v_mfma_f32_16x16x32_bf16 v[24:27], v[164:167], v[208:211], v[24:27]
	v_mfma_f32_16x16x32_bf16 v[12:15], v[156:159], v[216:219], v[12:15]
	v_mfma_f32_16x16x32_bf16 v[8:11], v[164:167], v[216:219], v[8:11]
	s_setprio 0
	s_setprio 1
	v_mfma_f32_16x16x32_bf16 v[52:55], v[168:171], v[188:191], v[52:55]
	v_mfma_f32_16x16x32_bf16 v[48:51], v[180:183], v[188:191], v[48:51]
	v_mfma_f32_16x16x32_bf16 v[36:39], v[168:171], v[196:199], v[36:39]
	v_mfma_f32_16x16x32_bf16 v[32:35], v[180:183], v[196:199], v[32:35]
	v_mfma_f32_16x16x32_bf16 v[20:23], v[168:171], v[204:207], v[20:23]
	v_mfma_f32_16x16x32_bf16 v[16:19], v[180:183], v[204:207], v[16:19]
	v_mfma_f32_16x16x32_bf16 v[4:7], v[168:171], v[212:215], v[4:7]
	v_mfma_f32_16x16x32_bf16 v[0:3], v[180:183], v[212:215], v[0:3]
	v_mfma_f32_16x16x32_bf16 v[52:55], v[176:179], v[192:195], v[52:55]
	v_mfma_f32_16x16x32_bf16 v[48:51], v[184:187], v[192:195], v[48:51]
	v_mfma_f32_16x16x32_bf16 v[36:39], v[176:179], v[200:203], v[36:39]
	v_mfma_f32_16x16x32_bf16 v[32:35], v[184:187], v[200:203], v[32:35]
	v_mfma_f32_16x16x32_bf16 v[20:23], v[176:179], v[208:211], v[20:23]
	v_mfma_f32_16x16x32_bf16 v[16:19], v[184:187], v[208:211], v[16:19]
	v_mfma_f32_16x16x32_bf16 v[4:7], v[176:179], v[216:219], v[4:7]
	v_mfma_f32_16x16x32_bf16 v[0:3], v[184:187], v[216:219], v[0:3]
	s_setprio 0
	s_barrier
	s_add_i32 s52, 0, 0x18000
	v_add_u32_e32 v155, s52, v149
	s_add_i32 s53, 0, 0x1c000
	ds_read_b128 v[144:147], v155
	ds_read_b128 v[156:159], v155 offset:1024
	ds_read_b128 v[160:163], v155 offset:2048
	ds_read_b128 v[164:167], v155 offset:3072
	v_add_u32_e32 v155, s53, v149
	ds_read_b128 v[168:171], v155
	ds_read_b128 v[176:179], v155 offset:1024
	ds_read_b128 v[180:183], v155 offset:2048
	ds_read_b128 v[184:187], v155 offset:3072
	s_add_u32 s26, s34, 0xb0000
	s_addc_u32 s27, s35, 0
	s_mov_b32 m0, s36
	v_lshl_add_u64 v[226:227], s[26:27], 0, v[128:129]
	ds_read_b128 v[188:191], v153 offset:32768
	ds_read_b128 v[192:195], v153 offset:33792
	ds_read_b128 v[196:199], v153 offset:34816
	ds_read_b128 v[200:203], v153 offset:35840
	ds_read_b128 v[204:207], v153 offset:36864
	ds_read_b128 v[208:211], v153 offset:37888
	ds_read_b128 v[212:215], v153 offset:38912
	ds_read_b128 v[216:219], v153 offset:39936
	global_load_lds_dwordx4 v[226:227], off
	s_mov_b32 m0, s37
	v_lshl_add_u64 v[226:227], s[26:27], 0, v[132:133]
	global_load_lds_dwordx4 v[226:227], off
	s_waitcnt vmcnt(8)
	s_waitcnt lgkmcnt(0)
	s_barrier
	s_setprio 1
	s_waitcnt lgkmcnt(0)
	v_mfma_f32_16x16x32_bf16 v[124:127], v[144:147], v[188:191], v[124:127]
	v_mfma_f32_16x16x32_bf16 v[120:123], v[160:163], v[188:191], v[120:123]
	v_mfma_f32_16x16x32_bf16 v[108:111], v[144:147], v[196:199], v[108:111]
	v_mfma_f32_16x16x32_bf16 v[104:107], v[160:163], v[196:199], v[104:107]
	v_mfma_f32_16x16x32_bf16 v[92:95], v[144:147], v[204:207], v[92:95]
	v_mfma_f32_16x16x32_bf16 v[88:91], v[160:163], v[204:207], v[88:91]
	v_mfma_f32_16x16x32_bf16 v[76:79], v[144:147], v[212:215], v[76:79]
	v_mfma_f32_16x16x32_bf16 v[72:75], v[160:163], v[212:215], v[72:75]
	v_mfma_f32_16x16x32_bf16 v[124:127], v[156:159], v[192:195], v[124:127]
	v_mfma_f32_16x16x32_bf16 v[120:123], v[164:167], v[192:195], v[120:123]
	v_mfma_f32_16x16x32_bf16 v[108:111], v[156:159], v[200:203], v[108:111]
	v_mfma_f32_16x16x32_bf16 v[104:107], v[164:167], v[200:203], v[104:107]
	v_mfma_f32_16x16x32_bf16 v[92:95], v[156:159], v[208:211], v[92:95]
	v_mfma_f32_16x16x32_bf16 v[88:91], v[164:167], v[208:211], v[88:91]
	v_mfma_f32_16x16x32_bf16 v[76:79], v[156:159], v[216:219], v[76:79]
	v_mfma_f32_16x16x32_bf16 v[72:75], v[164:167], v[216:219], v[72:75]
	s_setprio 0
	s_setprio 1
	v_mfma_f32_16x16x32_bf16 v[116:119], v[168:171], v[188:191], v[116:119]
	v_mfma_f32_16x16x32_bf16 v[112:115], v[180:183], v[188:191], v[112:115]
	v_mfma_f32_16x16x32_bf16 v[100:103], v[168:171], v[196:199], v[100:103]
	v_mfma_f32_16x16x32_bf16 v[96:99], v[180:183], v[196:199], v[96:99]
	v_mfma_f32_16x16x32_bf16 v[84:87], v[168:171], v[204:207], v[84:87]
	v_mfma_f32_16x16x32_bf16 v[80:83], v[180:183], v[204:207], v[80:83]
	v_mfma_f32_16x16x32_bf16 v[68:71], v[168:171], v[212:215], v[68:71]
	v_mfma_f32_16x16x32_bf16 v[64:67], v[180:183], v[212:215], v[64:67]
	v_mfma_f32_16x16x32_bf16 v[116:119], v[176:179], v[192:195], v[116:119]
	v_mfma_f32_16x16x32_bf16 v[112:115], v[184:187], v[192:195], v[112:115]
	v_mfma_f32_16x16x32_bf16 v[100:103], v[176:179], v[200:203], v[100:103]
	v_mfma_f32_16x16x32_bf16 v[96:99], v[184:187], v[200:203], v[96:99]
	v_mfma_f32_16x16x32_bf16 v[84:87], v[176:179], v[208:211], v[84:87]
	v_mfma_f32_16x16x32_bf16 v[80:83], v[184:187], v[208:211], v[80:83]
	v_mfma_f32_16x16x32_bf16 v[68:71], v[176:179], v[216:219], v[68:71]
	v_mfma_f32_16x16x32_bf16 v[64:67], v[184:187], v[216:219], v[64:67]
	s_setprio 0
	s_barrier
	s_add_i32 s26, s52, s15
	v_lshl_add_u64 v[172:173], v[172:173], 0, s[20:21]
	s_mov_b32 m0, s26
	ds_read_b128 v[188:191], v153 offset:49152
	ds_read_b128 v[192:195], v153 offset:50176
	ds_read_b128 v[196:199], v153 offset:51200
	ds_read_b128 v[200:203], v153 offset:52224
	ds_read_b128 v[204:207], v153 offset:53248
	ds_read_b128 v[208:211], v153 offset:54272
	ds_read_b128 v[212:215], v153 offset:55296
	ds_read_b128 v[216:219], v153 offset:56320
	global_load_lds_dwordx4 v[172:173], off
	s_add_i32 m0, s26, 0x2000
	s_add_u32 s26, s30, 0xb0080
	v_lshl_add_u64 v[172:173], v[220:221], 0, s[20:21]
	s_addc_u32 s27, s31, 0
	s_add_i32 s30, s53, s15
	global_load_lds_dwordx4 v[172:173], off
	s_mov_b32 m0, s30
	v_lshl_add_u64 v[172:173], s[26:27], 0, v[130:131]
	global_load_lds_dwordx4 v[172:173], off
	s_add_i32 m0, s30, 0x2000
	v_lshl_add_u64 v[172:173], s[26:27], 0, v[134:135]
	global_load_lds_dwordx4 v[172:173], off
	s_mov_b32 m0, s39
	v_lshl_add_u64 v[172:173], v[222:223], 0, s[20:21]
	global_load_lds_dwordx4 v[172:173], off
	s_mov_b32 m0, s40
	v_lshl_add_u64 v[172:173], v[224:225], 0, s[20:21]
	global_load_lds_dwordx4 v[172:173], off
	s_waitcnt vmcnt(8)
	s_waitcnt lgkmcnt(0)
	s_barrier
	s_setprio 1
	s_waitcnt lgkmcnt(0)
	v_mfma_f32_16x16x32_bf16 v[60:63], v[144:147], v[188:191], v[60:63]
	v_mfma_f32_16x16x32_bf16 v[56:59], v[160:163], v[188:191], v[56:59]
	v_mfma_f32_16x16x32_bf16 v[44:47], v[144:147], v[196:199], v[44:47]
	v_mfma_f32_16x16x32_bf16 v[40:43], v[160:163], v[196:199], v[40:43]
	v_mfma_f32_16x16x32_bf16 v[28:31], v[144:147], v[204:207], v[28:31]
	v_mfma_f32_16x16x32_bf16 v[24:27], v[160:163], v[204:207], v[24:27]
	v_mfma_f32_16x16x32_bf16 v[12:15], v[144:147], v[212:215], v[12:15]
	v_mfma_f32_16x16x32_bf16 v[8:11], v[160:163], v[212:215], v[8:11]
	v_mfma_f32_16x16x32_bf16 v[60:63], v[156:159], v[192:195], v[60:63]
	v_mfma_f32_16x16x32_bf16 v[56:59], v[164:167], v[192:195], v[56:59]
	v_mfma_f32_16x16x32_bf16 v[44:47], v[156:159], v[200:203], v[44:47]
	v_mfma_f32_16x16x32_bf16 v[40:43], v[164:167], v[200:203], v[40:43]
	v_mfma_f32_16x16x32_bf16 v[28:31], v[156:159], v[208:211], v[28:31]
	v_mfma_f32_16x16x32_bf16 v[24:27], v[164:167], v[208:211], v[24:27]
	v_mfma_f32_16x16x32_bf16 v[12:15], v[156:159], v[216:219], v[12:15]
	v_mfma_f32_16x16x32_bf16 v[8:11], v[164:167], v[216:219], v[8:11]
	s_setprio 0
	s_setprio 1
	v_mfma_f32_16x16x32_bf16 v[52:55], v[168:171], v[188:191], v[52:55]
	v_mfma_f32_16x16x32_bf16 v[48:51], v[180:183], v[188:191], v[48:51]
	v_mfma_f32_16x16x32_bf16 v[36:39], v[168:171], v[196:199], v[36:39]
	v_mfma_f32_16x16x32_bf16 v[32:35], v[180:183], v[196:199], v[32:35]
	v_mfma_f32_16x16x32_bf16 v[20:23], v[168:171], v[204:207], v[20:23]
	v_mfma_f32_16x16x32_bf16 v[16:19], v[180:183], v[204:207], v[16:19]
	v_mfma_f32_16x16x32_bf16 v[4:7], v[168:171], v[212:215], v[4:7]
	v_mfma_f32_16x16x32_bf16 v[0:3], v[180:183], v[212:215], v[0:3]
	v_mfma_f32_16x16x32_bf16 v[52:55], v[176:179], v[192:195], v[52:55]
	v_mfma_f32_16x16x32_bf16 v[48:51], v[184:187], v[192:195], v[48:51]
	v_mfma_f32_16x16x32_bf16 v[36:39], v[176:179], v[200:203], v[36:39]
	v_mfma_f32_16x16x32_bf16 v[32:35], v[184:187], v[200:203], v[32:35]
	v_mfma_f32_16x16x32_bf16 v[20:23], v[176:179], v[208:211], v[20:23]
	v_mfma_f32_16x16x32_bf16 v[16:19], v[184:187], v[208:211], v[16:19]
	v_mfma_f32_16x16x32_bf16 v[4:7], v[176:179], v[216:219], v[4:7]
	v_mfma_f32_16x16x32_bf16 v[0:3], v[184:187], v[216:219], v[0:3]
	s_setprio 0
	s_barrier
	s_add_i32 s51, s51, 2
	s_add_u32 s49, s49, 0x100
	s_addc_u32 s50, s50, 0
	s_cmp_gt_u32 s51, 41
	s_mov_b64 s[26:27], s[28:29]
	s_cbranch_scc0 .LBB0_1684
